# merge: gates held in registers borrowed from hoisted constants (restored per tile); next group's K-steps 0 and 1 prefetched in steps 5 and 6
# speedup vs baseline: 1.0008x; 1.0008x over previous
.LBB0_1010:
	ds_read_b128 v[90:93], v119 offset:0
	ds_read_b128 v[208:211], v205 offset:0
	ds_read_b128 v[212:215], v119 offset:2560
	ds_read_b128 v[216:219], v119 offset:5120
	ds_read_b128 v[220:223], v119 offset:7680
	s_waitcnt lgkmcnt(3)
	v_mfma_f32_16x16x32_bf16 v[6:9], v[90:93], v[208:211], v[6:9]
	s_waitcnt lgkmcnt(2)
	v_mfma_f32_16x16x32_bf16 v[30:33], v[212:215], v[208:211], v[30:33]
	s_waitcnt vmcnt(11)
	ds_write_b128 v207, v[228:231] offset:0
	s_waitcnt lgkmcnt(2)
	v_mfma_f32_16x16x32_bf16 v[38:41], v[216:219], v[208:211], v[38:41]
	s_waitcnt lgkmcnt(1)
	v_mfma_f32_16x16x32_bf16 v[42:45], v[220:223], v[208:211], v[42:45]
	ds_read_b128 v[208:211], v205 offset:2560
	s_waitcnt lgkmcnt(0)
	v_mfma_f32_16x16x32_bf16 v[46:49], v[90:93], v[208:211], v[46:49]
	v_mfma_f32_16x16x32_bf16 v[26:29], v[212:215], v[208:211], v[26:29]
	s_waitcnt vmcnt(10)
	ds_write_b128 v207, v[232:235] offset:10240
	v_mfma_f32_16x16x32_bf16 v[14:17], v[216:219], v[208:211], v[14:17]
	v_mfma_f32_16x16x32_bf16 v[10:13], v[220:223], v[208:211], v[10:13]
	ds_read_b128 v[208:211], v205 offset:5120
	s_waitcnt lgkmcnt(0)
	v_mfma_f32_16x16x32_bf16 v[34:37], v[90:93], v[208:211], v[34:37]
	v_mfma_f32_16x16x32_bf16 v[22:25], v[212:215], v[208:211], v[22:25]
	s_waitcnt vmcnt(9)
	ds_write_b128 v207, v[236:239] offset:20480
	v_mfma_f32_16x16x32_bf16 v[18:21], v[216:219], v[208:211], v[18:21]
	v_mfma_f32_16x16x32_bf16 v[62:65], v[220:223], v[208:211], v[62:65]
	ds_read_b128 v[208:211], v205 offset:7680
	s_waitcnt lgkmcnt(0)
	v_mfma_f32_16x16x32_bf16 v[58:61], v[90:93], v[208:211], v[58:61]
	ds_read_b128 v[90:93], v119 offset:64
	v_mfma_f32_16x16x32_bf16 v[54:57], v[212:215], v[208:211], v[54:57]
	s_waitcnt vmcnt(8)
	ds_write_b128 v207, v[240:243] offset:30720
	ds_read_b128 v[212:215], v119 offset:2624
	v_mfma_f32_16x16x32_bf16 v[50:53], v[216:219], v[208:211], v[50:53]
	ds_read_b128 v[216:219], v119 offset:5184
	v_mfma_f32_16x16x32_bf16 v[2:5], v[220:223], v[208:211], v[2:5]
	ds_read_b128 v[220:223], v119 offset:7744
	ds_read_b128 v[208:211], v205 offset:64
	ds_read_b128 v[224:227], v205 offset:7744
	s_waitcnt lgkmcnt(1)
	v_mfma_f32_16x16x32_bf16 v[6:9], v[90:93], v[208:211], v[6:9]
	v_mfma_f32_16x16x32_bf16 v[30:33], v[212:215], v[208:211], v[30:33]
	s_waitcnt vmcnt(7)
	ds_write_b128 v0, v[244:247] offset:20480
	v_mfma_f32_16x16x32_bf16 v[38:41], v[216:219], v[208:211], v[38:41]
	v_mfma_f32_16x16x32_bf16 v[42:45], v[220:223], v[208:211], v[42:45]
	ds_read_b128 v[208:211], v205 offset:2624
	s_waitcnt lgkmcnt(0)
	v_mfma_f32_16x16x32_bf16 v[46:49], v[90:93], v[208:211], v[46:49]
	v_mfma_f32_16x16x32_bf16 v[26:29], v[212:215], v[208:211], v[26:29]
	s_waitcnt vmcnt(6)
	ds_write_b128 v0, v[248:251] offset:30720
	v_mfma_f32_16x16x32_bf16 v[14:17], v[216:219], v[208:211], v[14:17]
	v_mfma_f32_16x16x32_bf16 v[10:13], v[220:223], v[208:211], v[10:13]
	ds_read_b128 v[208:211], v205 offset:5184
	s_waitcnt lgkmcnt(0)
	v_mfma_f32_16x16x32_bf16 v[34:37], v[90:93], v[208:211], v[34:37]
	v_mfma_f32_16x16x32_bf16 v[22:25], v[212:215], v[208:211], v[22:25]
	v_mfma_f32_16x16x32_bf16 v[18:21], v[216:219], v[208:211], v[18:21]
	v_mfma_f32_16x16x32_bf16 v[62:65], v[220:223], v[208:211], v[62:65]
	v_mfma_f32_16x16x32_bf16 v[58:61], v[90:93], v[224:227], v[58:61]
	s_waitcnt lgkmcnt(0)
	v_mfma_f32_16x16x32_bf16 v[54:57], v[212:215], v[224:227], v[54:57]
	s_barrier
	v_mfma_f32_16x16x32_bf16 v[50:53], v[216:219], v[224:227], v[50:53]
	v_mfma_f32_16x16x32_bf16 v[2:5], v[220:223], v[224:227], v[2:5]
	global_load_dwordx4 v[228:231], v190, s[80:81] offset:384
	global_load_dwordx4 v[232:235], v191, s[80:81] offset:384
	global_load_dwordx4 v[236:239], v190, s[86:87] offset:384
	global_load_dwordx4 v[240:243], v191, s[86:87] offset:384
	global_load_dwordx4 v[244:247], v188, s[96:97] offset:384
	global_load_dwordx4 v[248:251], v188, s[98:99] offset:384
	ds_read_b128 v[90:93], v119 offset:20480
	ds_read_b128 v[208:211], v205 offset:40960
	ds_read_b128 v[212:215], v119 offset:23040
	ds_read_b128 v[216:219], v119 offset:25600
	ds_read_b128 v[220:223], v119 offset:28160
	s_waitcnt lgkmcnt(3)
	v_mfma_f32_16x16x32_bf16 v[6:9], v[90:93], v[208:211], v[6:9]
	s_waitcnt lgkmcnt(2)
	v_mfma_f32_16x16x32_bf16 v[30:33], v[212:215], v[208:211], v[30:33]
	s_waitcnt vmcnt(11)
	ds_write_b128 v206, v[66:69] offset:0
	s_waitcnt lgkmcnt(2)
	v_mfma_f32_16x16x32_bf16 v[38:41], v[216:219], v[208:211], v[38:41]
	s_waitcnt lgkmcnt(1)
	v_mfma_f32_16x16x32_bf16 v[42:45], v[220:223], v[208:211], v[42:45]
	ds_read_b128 v[208:211], v205 offset:43520
	s_waitcnt lgkmcnt(0)
	v_mfma_f32_16x16x32_bf16 v[46:49], v[90:93], v[208:211], v[46:49]
	v_mfma_f32_16x16x32_bf16 v[26:29], v[212:215], v[208:211], v[26:29]
	s_waitcnt vmcnt(10)
	ds_write_b128 v206, v[70:73] offset:10240
	v_mfma_f32_16x16x32_bf16 v[14:17], v[216:219], v[208:211], v[14:17]
	v_mfma_f32_16x16x32_bf16 v[10:13], v[220:223], v[208:211], v[10:13]
	ds_read_b128 v[208:211], v205 offset:46080
	s_waitcnt lgkmcnt(0)
	v_mfma_f32_16x16x32_bf16 v[34:37], v[90:93], v[208:211], v[34:37]
	v_mfma_f32_16x16x32_bf16 v[22:25], v[212:215], v[208:211], v[22:25]
	s_waitcnt vmcnt(9)
	ds_write_b128 v206, v[74:77] offset:20480
	v_mfma_f32_16x16x32_bf16 v[18:21], v[216:219], v[208:211], v[18:21]
	v_mfma_f32_16x16x32_bf16 v[62:65], v[220:223], v[208:211], v[62:65]
	ds_read_b128 v[208:211], v205 offset:48640
	s_waitcnt lgkmcnt(0)
	v_mfma_f32_16x16x32_bf16 v[58:61], v[90:93], v[208:211], v[58:61]
	ds_read_b128 v[90:93], v119 offset:20544
	v_mfma_f32_16x16x32_bf16 v[54:57], v[212:215], v[208:211], v[54:57]
	s_waitcnt vmcnt(8)
	ds_write_b128 v206, v[78:81] offset:30720
	ds_read_b128 v[212:215], v119 offset:23104
	v_mfma_f32_16x16x32_bf16 v[50:53], v[216:219], v[208:211], v[50:53]
	ds_read_b128 v[216:219], v119 offset:25664
	v_mfma_f32_16x16x32_bf16 v[2:5], v[220:223], v[208:211], v[2:5]
	ds_read_b128 v[220:223], v119 offset:28224
	ds_read_b128 v[208:211], v205 offset:41024
	ds_read_b128 v[224:227], v205 offset:48704
	s_waitcnt lgkmcnt(1)
	v_mfma_f32_16x16x32_bf16 v[6:9], v[90:93], v[208:211], v[6:9]
	v_mfma_f32_16x16x32_bf16 v[30:33], v[212:215], v[208:211], v[30:33]
	s_waitcnt vmcnt(7)
	ds_write_b128 v0, v[82:85] offset:0
	v_mfma_f32_16x16x32_bf16 v[38:41], v[216:219], v[208:211], v[38:41]
	v_mfma_f32_16x16x32_bf16 v[42:45], v[220:223], v[208:211], v[42:45]
	ds_read_b128 v[208:211], v205 offset:43584
	s_waitcnt lgkmcnt(0)
	v_mfma_f32_16x16x32_bf16 v[46:49], v[90:93], v[208:211], v[46:49]
	v_mfma_f32_16x16x32_bf16 v[26:29], v[212:215], v[208:211], v[26:29]
	s_waitcnt vmcnt(6)
	ds_write_b128 v0, v[86:89] offset:10240
	v_mfma_f32_16x16x32_bf16 v[14:17], v[216:219], v[208:211], v[14:17]
	v_mfma_f32_16x16x32_bf16 v[10:13], v[220:223], v[208:211], v[10:13]
	ds_read_b128 v[208:211], v205 offset:46144
	s_waitcnt lgkmcnt(0)
	v_mfma_f32_16x16x32_bf16 v[34:37], v[90:93], v[208:211], v[34:37]
	v_mfma_f32_16x16x32_bf16 v[22:25], v[212:215], v[208:211], v[22:25]
	v_mfma_f32_16x16x32_bf16 v[18:21], v[216:219], v[208:211], v[18:21]
	v_mfma_f32_16x16x32_bf16 v[62:65], v[220:223], v[208:211], v[62:65]
	v_mfma_f32_16x16x32_bf16 v[58:61], v[90:93], v[224:227], v[58:61]
	s_waitcnt lgkmcnt(0)
	v_mfma_f32_16x16x32_bf16 v[54:57], v[212:215], v[224:227], v[54:57]
	s_barrier
	v_mfma_f32_16x16x32_bf16 v[50:53], v[216:219], v[224:227], v[50:53]
	v_mfma_f32_16x16x32_bf16 v[2:5], v[220:223], v[224:227], v[2:5]
	global_load_dwordx4 v[66:69], v190, s[80:81] offset:512
	global_load_dwordx4 v[70:73], v191, s[80:81] offset:512
	global_load_dwordx4 v[74:77], v190, s[86:87] offset:512
	global_load_dwordx4 v[78:81], v191, s[86:87] offset:512
	global_load_dwordx4 v[82:85], v188, s[96:97] offset:512
	global_load_dwordx4 v[86:89], v188, s[98:99] offset:512
	ds_read_b128 v[90:93], v119 offset:0
	ds_read_b128 v[208:211], v205 offset:0
	ds_read_b128 v[212:215], v119 offset:2560
	ds_read_b128 v[216:219], v119 offset:5120
	ds_read_b128 v[220:223], v119 offset:7680
	s_waitcnt lgkmcnt(3)
	v_mfma_f32_16x16x32_bf16 v[6:9], v[90:93], v[208:211], v[6:9]
	s_waitcnt lgkmcnt(2)
	v_mfma_f32_16x16x32_bf16 v[30:33], v[212:215], v[208:211], v[30:33]
	s_waitcnt vmcnt(11)
	ds_write_b128 v207, v[228:231] offset:0
	s_waitcnt lgkmcnt(2)
	v_mfma_f32_16x16x32_bf16 v[38:41], v[216:219], v[208:211], v[38:41]
	s_waitcnt lgkmcnt(1)
	v_mfma_f32_16x16x32_bf16 v[42:45], v[220:223], v[208:211], v[42:45]
	ds_read_b128 v[208:211], v205 offset:2560
	s_waitcnt lgkmcnt(0)
	v_mfma_f32_16x16x32_bf16 v[46:49], v[90:93], v[208:211], v[46:49]
	v_mfma_f32_16x16x32_bf16 v[26:29], v[212:215], v[208:211], v[26:29]
	s_waitcnt vmcnt(10)
	ds_write_b128 v207, v[232:235] offset:10240
	v_mfma_f32_16x16x32_bf16 v[14:17], v[216:219], v[208:211], v[14:17]
	v_mfma_f32_16x16x32_bf16 v[10:13], v[220:223], v[208:211], v[10:13]
	ds_read_b128 v[208:211], v205 offset:5120
	s_waitcnt lgkmcnt(0)
	v_mfma_f32_16x16x32_bf16 v[34:37], v[90:93], v[208:211], v[34:37]
	v_mfma_f32_16x16x32_bf16 v[22:25], v[212:215], v[208:211], v[22:25]
	s_waitcnt vmcnt(9)
	ds_write_b128 v207, v[236:239] offset:20480
	v_mfma_f32_16x16x32_bf16 v[18:21], v[216:219], v[208:211], v[18:21]
	v_mfma_f32_16x16x32_bf16 v[62:65], v[220:223], v[208:211], v[62:65]
	ds_read_b128 v[208:211], v205 offset:7680
	s_waitcnt lgkmcnt(0)
	v_mfma_f32_16x16x32_bf16 v[58:61], v[90:93], v[208:211], v[58:61]
	ds_read_b128 v[90:93], v119 offset:64
	v_mfma_f32_16x16x32_bf16 v[54:57], v[212:215], v[208:211], v[54:57]
	s_waitcnt vmcnt(8)
	ds_write_b128 v207, v[240:243] offset:30720
	ds_read_b128 v[212:215], v119 offset:2624
	v_mfma_f32_16x16x32_bf16 v[50:53], v[216:219], v[208:211], v[50:53]
	ds_read_b128 v[216:219], v119 offset:5184
	v_mfma_f32_16x16x32_bf16 v[2:5], v[220:223], v[208:211], v[2:5]
	ds_read_b128 v[220:223], v119 offset:7744
	ds_read_b128 v[208:211], v205 offset:64
	ds_read_b128 v[224:227], v205 offset:7744
	s_waitcnt lgkmcnt(1)
	v_mfma_f32_16x16x32_bf16 v[6:9], v[90:93], v[208:211], v[6:9]
	v_mfma_f32_16x16x32_bf16 v[30:33], v[212:215], v[208:211], v[30:33]
	s_waitcnt vmcnt(7)
	ds_write_b128 v0, v[244:247] offset:20480
	v_mfma_f32_16x16x32_bf16 v[38:41], v[216:219], v[208:211], v[38:41]
	v_mfma_f32_16x16x32_bf16 v[42:45], v[220:223], v[208:211], v[42:45]
	ds_read_b128 v[208:211], v205 offset:2624
	s_waitcnt lgkmcnt(0)
	v_mfma_f32_16x16x32_bf16 v[46:49], v[90:93], v[208:211], v[46:49]
	v_mfma_f32_16x16x32_bf16 v[26:29], v[212:215], v[208:211], v[26:29]
	s_waitcnt vmcnt(6)
	ds_write_b128 v0, v[248:251] offset:30720
	v_mfma_f32_16x16x32_bf16 v[14:17], v[216:219], v[208:211], v[14:17]
	v_mfma_f32_16x16x32_bf16 v[10:13], v[220:223], v[208:211], v[10:13]
	ds_read_b128 v[208:211], v205 offset:5184
	s_waitcnt lgkmcnt(0)
	v_mfma_f32_16x16x32_bf16 v[34:37], v[90:93], v[208:211], v[34:37]
	v_mfma_f32_16x16x32_bf16 v[22:25], v[212:215], v[208:211], v[22:25]
	v_mfma_f32_16x16x32_bf16 v[18:21], v[216:219], v[208:211], v[18:21]
	v_mfma_f32_16x16x32_bf16 v[62:65], v[220:223], v[208:211], v[62:65]
	v_mfma_f32_16x16x32_bf16 v[58:61], v[90:93], v[224:227], v[58:61]
	s_waitcnt lgkmcnt(0)
	v_mfma_f32_16x16x32_bf16 v[54:57], v[212:215], v[224:227], v[54:57]
	s_barrier
	v_mfma_f32_16x16x32_bf16 v[50:53], v[216:219], v[224:227], v[50:53]
	v_mfma_f32_16x16x32_bf16 v[2:5], v[220:223], v[224:227], v[2:5]
	global_load_dwordx4 v[228:231], v190, s[80:81] offset:640
	global_load_dwordx4 v[232:235], v191, s[80:81] offset:640
	global_load_dwordx4 v[236:239], v190, s[86:87] offset:640
	global_load_dwordx4 v[240:243], v191, s[86:87] offset:640
	global_load_dwordx4 v[244:247], v188, s[96:97] offset:640
	global_load_dwordx4 v[248:251], v188, s[98:99] offset:640
	ds_read_b128 v[90:93], v119 offset:20480
	ds_read_b128 v[208:211], v205 offset:40960
	ds_read_b128 v[212:215], v119 offset:23040
	ds_read_b128 v[216:219], v119 offset:25600
	ds_read_b128 v[220:223], v119 offset:28160
	s_waitcnt lgkmcnt(3)
	v_mfma_f32_16x16x32_bf16 v[6:9], v[90:93], v[208:211], v[6:9]
	s_waitcnt lgkmcnt(2)
	v_mfma_f32_16x16x32_bf16 v[30:33], v[212:215], v[208:211], v[30:33]
	s_waitcnt vmcnt(11)
	ds_write_b128 v206, v[66:69] offset:0
	s_waitcnt lgkmcnt(2)
	v_mfma_f32_16x16x32_bf16 v[38:41], v[216:219], v[208:211], v[38:41]
	s_waitcnt lgkmcnt(1)
	v_mfma_f32_16x16x32_bf16 v[42:45], v[220:223], v[208:211], v[42:45]
	ds_read_b128 v[208:211], v205 offset:43520
	s_waitcnt lgkmcnt(0)
	v_mfma_f32_16x16x32_bf16 v[46:49], v[90:93], v[208:211], v[46:49]
	v_mfma_f32_16x16x32_bf16 v[26:29], v[212:215], v[208:211], v[26:29]
	s_waitcnt vmcnt(10)
	ds_write_b128 v206, v[70:73] offset:10240
	v_mfma_f32_16x16x32_bf16 v[14:17], v[216:219], v[208:211], v[14:17]
	v_mfma_f32_16x16x32_bf16 v[10:13], v[220:223], v[208:211], v[10:13]
	ds_read_b128 v[208:211], v205 offset:46080
	s_waitcnt lgkmcnt(0)
	v_mfma_f32_16x16x32_bf16 v[34:37], v[90:93], v[208:211], v[34:37]
	v_mfma_f32_16x16x32_bf16 v[22:25], v[212:215], v[208:211], v[22:25]
	s_waitcnt vmcnt(9)
	ds_write_b128 v206, v[74:77] offset:20480
	v_mfma_f32_16x16x32_bf16 v[18:21], v[216:219], v[208:211], v[18:21]
	v_mfma_f32_16x16x32_bf16 v[62:65], v[220:223], v[208:211], v[62:65]
	ds_read_b128 v[208:211], v205 offset:48640
	s_waitcnt lgkmcnt(0)
	v_mfma_f32_16x16x32_bf16 v[58:61], v[90:93], v[208:211], v[58:61]
	ds_read_b128 v[90:93], v119 offset:20544
	v_mfma_f32_16x16x32_bf16 v[54:57], v[212:215], v[208:211], v[54:57]
	s_waitcnt vmcnt(8)
	ds_write_b128 v206, v[78:81] offset:30720
	ds_read_b128 v[212:215], v119 offset:23104
	v_mfma_f32_16x16x32_bf16 v[50:53], v[216:219], v[208:211], v[50:53]
	ds_read_b128 v[216:219], v119 offset:25664
	v_mfma_f32_16x16x32_bf16 v[2:5], v[220:223], v[208:211], v[2:5]
	ds_read_b128 v[220:223], v119 offset:28224
	ds_read_b128 v[208:211], v205 offset:41024
	ds_read_b128 v[224:227], v205 offset:48704
	s_waitcnt lgkmcnt(1)
	v_mfma_f32_16x16x32_bf16 v[6:9], v[90:93], v[208:211], v[6:9]
	v_mfma_f32_16x16x32_bf16 v[30:33], v[212:215], v[208:211], v[30:33]
	s_waitcnt vmcnt(7)
	ds_write_b128 v0, v[82:85] offset:0
	v_mfma_f32_16x16x32_bf16 v[38:41], v[216:219], v[208:211], v[38:41]
	v_mfma_f32_16x16x32_bf16 v[42:45], v[220:223], v[208:211], v[42:45]
	ds_read_b128 v[208:211], v205 offset:43584
	s_waitcnt lgkmcnt(0)
	v_mfma_f32_16x16x32_bf16 v[46:49], v[90:93], v[208:211], v[46:49]
	v_mfma_f32_16x16x32_bf16 v[26:29], v[212:215], v[208:211], v[26:29]
	s_waitcnt vmcnt(6)
	ds_write_b128 v0, v[86:89] offset:10240
	v_mfma_f32_16x16x32_bf16 v[14:17], v[216:219], v[208:211], v[14:17]
	v_mfma_f32_16x16x32_bf16 v[10:13], v[220:223], v[208:211], v[10:13]
	ds_read_b128 v[208:211], v205 offset:46144
	s_waitcnt lgkmcnt(0)
	v_mfma_f32_16x16x32_bf16 v[34:37], v[90:93], v[208:211], v[34:37]
	v_mfma_f32_16x16x32_bf16 v[22:25], v[212:215], v[208:211], v[22:25]
	v_mfma_f32_16x16x32_bf16 v[18:21], v[216:219], v[208:211], v[18:21]
	v_mfma_f32_16x16x32_bf16 v[62:65], v[220:223], v[208:211], v[62:65]
	v_mfma_f32_16x16x32_bf16 v[58:61], v[90:93], v[224:227], v[58:61]
	s_waitcnt lgkmcnt(0)
	v_mfma_f32_16x16x32_bf16 v[54:57], v[212:215], v[224:227], v[54:57]
	s_barrier
	v_mfma_f32_16x16x32_bf16 v[50:53], v[216:219], v[224:227], v[50:53]
	v_mfma_f32_16x16x32_bf16 v[2:5], v[220:223], v[224:227], v[2:5]
	global_load_dwordx4 v[66:69], v190, s[80:81] offset:768
	global_load_dwordx4 v[70:73], v191, s[80:81] offset:768
	global_load_dwordx4 v[74:77], v190, s[86:87] offset:768
	global_load_dwordx4 v[78:81], v191, s[86:87] offset:768
	global_load_dwordx4 v[82:85], v188, s[96:97] offset:768
	global_load_dwordx4 v[86:89], v188, s[98:99] offset:768
	ds_read_b128 v[90:93], v119 offset:0
	ds_read_b128 v[208:211], v205 offset:0
	ds_read_b128 v[212:215], v119 offset:2560
	ds_read_b128 v[216:219], v119 offset:5120
	ds_read_b128 v[220:223], v119 offset:7680
	s_waitcnt lgkmcnt(3)
	v_mfma_f32_16x16x32_bf16 v[6:9], v[90:93], v[208:211], v[6:9]
	s_waitcnt lgkmcnt(2)
	v_mfma_f32_16x16x32_bf16 v[30:33], v[212:215], v[208:211], v[30:33]
	s_waitcnt vmcnt(11)
	ds_write_b128 v207, v[228:231] offset:0
	s_waitcnt lgkmcnt(2)
	v_mfma_f32_16x16x32_bf16 v[38:41], v[216:219], v[208:211], v[38:41]
	s_waitcnt lgkmcnt(1)
	v_mfma_f32_16x16x32_bf16 v[42:45], v[220:223], v[208:211], v[42:45]
	ds_read_b128 v[208:211], v205 offset:2560
	s_waitcnt lgkmcnt(0)
	v_mfma_f32_16x16x32_bf16 v[46:49], v[90:93], v[208:211], v[46:49]
	v_mfma_f32_16x16x32_bf16 v[26:29], v[212:215], v[208:211], v[26:29]
	s_waitcnt vmcnt(10)
	ds_write_b128 v207, v[232:235] offset:10240
	v_mfma_f32_16x16x32_bf16 v[14:17], v[216:219], v[208:211], v[14:17]
	v_mfma_f32_16x16x32_bf16 v[10:13], v[220:223], v[208:211], v[10:13]
	ds_read_b128 v[208:211], v205 offset:5120
	s_waitcnt lgkmcnt(0)
	v_mfma_f32_16x16x32_bf16 v[34:37], v[90:93], v[208:211], v[34:37]
	v_mfma_f32_16x16x32_bf16 v[22:25], v[212:215], v[208:211], v[22:25]
	s_waitcnt vmcnt(9)
	ds_write_b128 v207, v[236:239] offset:20480
	v_mfma_f32_16x16x32_bf16 v[18:21], v[216:219], v[208:211], v[18:21]
	v_mfma_f32_16x16x32_bf16 v[62:65], v[220:223], v[208:211], v[62:65]
	ds_read_b128 v[208:211], v205 offset:7680
	s_waitcnt lgkmcnt(0)
	v_mfma_f32_16x16x32_bf16 v[58:61], v[90:93], v[208:211], v[58:61]
	ds_read_b128 v[90:93], v119 offset:64
	v_mfma_f32_16x16x32_bf16 v[54:57], v[212:215], v[208:211], v[54:57]
	s_waitcnt vmcnt(8)
	ds_write_b128 v207, v[240:243] offset:30720
	ds_read_b128 v[212:215], v119 offset:2624
	v_mfma_f32_16x16x32_bf16 v[50:53], v[216:219], v[208:211], v[50:53]
	ds_read_b128 v[216:219], v119 offset:5184
	v_mfma_f32_16x16x32_bf16 v[2:5], v[220:223], v[208:211], v[2:5]
	ds_read_b128 v[220:223], v119 offset:7744
	ds_read_b128 v[208:211], v205 offset:64
	ds_read_b128 v[224:227], v205 offset:7744
	s_waitcnt lgkmcnt(1)
	v_mfma_f32_16x16x32_bf16 v[6:9], v[90:93], v[208:211], v[6:9]
	v_mfma_f32_16x16x32_bf16 v[30:33], v[212:215], v[208:211], v[30:33]
	s_waitcnt vmcnt(7)
	ds_write_b128 v0, v[244:247] offset:20480
	v_mfma_f32_16x16x32_bf16 v[38:41], v[216:219], v[208:211], v[38:41]
	v_mfma_f32_16x16x32_bf16 v[42:45], v[220:223], v[208:211], v[42:45]
	ds_read_b128 v[208:211], v205 offset:2624
	s_waitcnt lgkmcnt(0)
	v_mfma_f32_16x16x32_bf16 v[46:49], v[90:93], v[208:211], v[46:49]
	v_mfma_f32_16x16x32_bf16 v[26:29], v[212:215], v[208:211], v[26:29]
	s_waitcnt vmcnt(6)
	ds_write_b128 v0, v[248:251] offset:30720
	s_movk_i32 s10, 0x0
	s_mov_b32 s11, 0
	v_lshl_add_u64 v[200:201], v[128:129], 0, s[10:11]
	global_load_dwordx2 v[138:139], v[200:201], off
	global_load_dwordx2 v[140:141], v[200:201], off offset:32
	v_lshl_add_u64 v[200:201], v[132:133], 0, s[10:11]
	global_load_dwordx2 v[142:143], v[200:201], off
	global_load_dwordx2 v[144:145], v[200:201], off offset:32
	v_lshl_add_u64 v[200:201], v[152:153], 0, s[10:11]
	global_load_dwordx2 v[146:147], v[200:201], off
	global_load_dwordx2 v[148:149], v[200:201], off offset:32
	v_lshl_add_u64 v[200:201], v[154:155], 0, s[10:11]
	global_load_dwordx2 v[194:195], v[200:201], off
	global_load_dwordx2 v[196:197], v[200:201], off offset:32
	v_mfma_f32_16x16x32_bf16 v[14:17], v[216:219], v[208:211], v[14:17]
	v_mfma_f32_16x16x32_bf16 v[10:13], v[220:223], v[208:211], v[10:13]
	ds_read_b128 v[208:211], v205 offset:5184
	s_waitcnt lgkmcnt(0)
	v_mfma_f32_16x16x32_bf16 v[34:37], v[90:93], v[208:211], v[34:37]
	v_mfma_f32_16x16x32_bf16 v[22:25], v[212:215], v[208:211], v[22:25]
	v_mfma_f32_16x16x32_bf16 v[18:21], v[216:219], v[208:211], v[18:21]
	v_mfma_f32_16x16x32_bf16 v[62:65], v[220:223], v[208:211], v[62:65]
	v_mfma_f32_16x16x32_bf16 v[58:61], v[90:93], v[224:227], v[58:61]
	s_waitcnt lgkmcnt(0)
	v_mfma_f32_16x16x32_bf16 v[54:57], v[212:215], v[224:227], v[54:57]
	s_barrier
	v_mfma_f32_16x16x32_bf16 v[50:53], v[216:219], v[224:227], v[50:53]
	v_mfma_f32_16x16x32_bf16 v[2:5], v[220:223], v[224:227], v[2:5]
	global_load_dwordx4 v[228:231], v190, s[80:81] offset:896
	global_load_dwordx4 v[232:235], v191, s[80:81] offset:896
	global_load_dwordx4 v[236:239], v190, s[86:87] offset:896
	global_load_dwordx4 v[240:243], v191, s[86:87] offset:896
	global_load_dwordx4 v[244:247], v188, s[96:97] offset:896
	global_load_dwordx4 v[248:251], v188, s[98:99] offset:896
	ds_read_b128 v[90:93], v119 offset:20480
	ds_read_b128 v[208:211], v205 offset:40960
	ds_read_b128 v[212:215], v119 offset:23040
	ds_read_b128 v[216:219], v119 offset:25600
	ds_read_b128 v[220:223], v119 offset:28160
	s_waitcnt lgkmcnt(3)
	v_mfma_f32_16x16x32_bf16 v[6:9], v[90:93], v[208:211], v[6:9]
	s_waitcnt lgkmcnt(2)
	v_mfma_f32_16x16x32_bf16 v[30:33], v[212:215], v[208:211], v[30:33]
	s_waitcnt vmcnt(19)
	ds_write_b128 v206, v[66:69] offset:0
	s_waitcnt lgkmcnt(2)
	v_mfma_f32_16x16x32_bf16 v[38:41], v[216:219], v[208:211], v[38:41]
	s_waitcnt lgkmcnt(1)
	v_mfma_f32_16x16x32_bf16 v[42:45], v[220:223], v[208:211], v[42:45]
	ds_read_b128 v[208:211], v205 offset:43520
	s_waitcnt lgkmcnt(0)
	v_mfma_f32_16x16x32_bf16 v[46:49], v[90:93], v[208:211], v[46:49]
	v_mfma_f32_16x16x32_bf16 v[26:29], v[212:215], v[208:211], v[26:29]
	s_waitcnt vmcnt(18)
	ds_write_b128 v206, v[70:73] offset:10240
	v_mfma_f32_16x16x32_bf16 v[14:17], v[216:219], v[208:211], v[14:17]
	v_mfma_f32_16x16x32_bf16 v[10:13], v[220:223], v[208:211], v[10:13]
	ds_read_b128 v[208:211], v205 offset:46080
	s_waitcnt lgkmcnt(0)
	v_mfma_f32_16x16x32_bf16 v[34:37], v[90:93], v[208:211], v[34:37]
	v_mfma_f32_16x16x32_bf16 v[22:25], v[212:215], v[208:211], v[22:25]
	s_waitcnt vmcnt(17)
	ds_write_b128 v206, v[74:77] offset:20480
	v_mfma_f32_16x16x32_bf16 v[18:21], v[216:219], v[208:211], v[18:21]
	v_mfma_f32_16x16x32_bf16 v[62:65], v[220:223], v[208:211], v[62:65]
	ds_read_b128 v[208:211], v205 offset:48640
	s_waitcnt lgkmcnt(0)
	v_mfma_f32_16x16x32_bf16 v[58:61], v[90:93], v[208:211], v[58:61]
	ds_read_b128 v[90:93], v119 offset:20544
	v_mfma_f32_16x16x32_bf16 v[54:57], v[212:215], v[208:211], v[54:57]
	s_waitcnt vmcnt(16)
	ds_write_b128 v206, v[78:81] offset:30720
	ds_read_b128 v[212:215], v119 offset:23104
	v_mfma_f32_16x16x32_bf16 v[50:53], v[216:219], v[208:211], v[50:53]
	ds_read_b128 v[216:219], v119 offset:25664
	v_mfma_f32_16x16x32_bf16 v[2:5], v[220:223], v[208:211], v[2:5]
	ds_read_b128 v[220:223], v119 offset:28224
	ds_read_b128 v[208:211], v205 offset:41024
	ds_read_b128 v[224:227], v205 offset:48704
	s_waitcnt lgkmcnt(1)
	v_mfma_f32_16x16x32_bf16 v[6:9], v[90:93], v[208:211], v[6:9]
	v_mfma_f32_16x16x32_bf16 v[30:33], v[212:215], v[208:211], v[30:33]
	s_waitcnt vmcnt(15)
	ds_write_b128 v0, v[82:85] offset:0
	v_mfma_f32_16x16x32_bf16 v[38:41], v[216:219], v[208:211], v[38:41]
	v_mfma_f32_16x16x32_bf16 v[42:45], v[220:223], v[208:211], v[42:45]
	ds_read_b128 v[208:211], v205 offset:43584
	s_waitcnt lgkmcnt(0)
	v_mfma_f32_16x16x32_bf16 v[46:49], v[90:93], v[208:211], v[46:49]
	v_mfma_f32_16x16x32_bf16 v[26:29], v[212:215], v[208:211], v[26:29]
	s_waitcnt vmcnt(14)
	ds_write_b128 v0, v[86:89] offset:10240
	s_add_u32 s80, s80, 0x400
	s_addc_u32 s81, s81, 0
	s_add_u32 s86, s80, 0x1f0000
	s_addc_u32 s87, s81, 0
	s_add_u32 s96, s96, 0x100000
	s_addc_u32 s97, s97, 0
	s_add_u32 s98, s96, 0x10000
	s_addc_u32 s99, s97, 0
	global_load_dwordx4 v[66:69], v190, s[80:81] offset:0
	global_load_dwordx4 v[70:73], v191, s[80:81] offset:0
	global_load_dwordx4 v[74:77], v190, s[86:87] offset:0
	global_load_dwordx4 v[78:81], v191, s[86:87] offset:0
	global_load_dwordx4 v[82:85], v188, s[96:97] offset:0
	global_load_dwordx4 v[86:89], v188, s[98:99] offset:0
	v_mfma_f32_16x16x32_bf16 v[14:17], v[216:219], v[208:211], v[14:17]
	v_mfma_f32_16x16x32_bf16 v[10:13], v[220:223], v[208:211], v[10:13]
	ds_read_b128 v[208:211], v205 offset:46144
	s_waitcnt lgkmcnt(0)
	v_mfma_f32_16x16x32_bf16 v[34:37], v[90:93], v[208:211], v[34:37]
	v_mfma_f32_16x16x32_bf16 v[22:25], v[212:215], v[208:211], v[22:25]
	v_mfma_f32_16x16x32_bf16 v[18:21], v[216:219], v[208:211], v[18:21]
	v_mfma_f32_16x16x32_bf16 v[62:65], v[220:223], v[208:211], v[62:65]
	v_mfma_f32_16x16x32_bf16 v[58:61], v[90:93], v[224:227], v[58:61]
	s_waitcnt lgkmcnt(0)
	v_mfma_f32_16x16x32_bf16 v[54:57], v[212:215], v[224:227], v[54:57]
	s_barrier
	v_mfma_f32_16x16x32_bf16 v[50:53], v[216:219], v[224:227], v[50:53]
	v_mfma_f32_16x16x32_bf16 v[2:5], v[220:223], v[224:227], v[2:5]
	ds_read_b128 v[90:93], v119 offset:0
	ds_read_b128 v[208:211], v205 offset:0
	ds_read_b128 v[212:215], v119 offset:2560
	ds_read_b128 v[216:219], v119 offset:5120
	ds_read_b128 v[220:223], v119 offset:7680
	s_waitcnt lgkmcnt(3)
	v_mfma_f32_16x16x32_bf16 v[6:9], v[90:93], v[208:211], v[6:9]
	s_waitcnt lgkmcnt(2)
	v_mfma_f32_16x16x32_bf16 v[30:33], v[212:215], v[208:211], v[30:33]
	s_waitcnt vmcnt(11)
	ds_write_b128 v207, v[228:231] offset:0
	s_waitcnt lgkmcnt(2)
	v_mfma_f32_16x16x32_bf16 v[38:41], v[216:219], v[208:211], v[38:41]
	s_waitcnt lgkmcnt(1)
	v_mfma_f32_16x16x32_bf16 v[42:45], v[220:223], v[208:211], v[42:45]
	ds_read_b128 v[208:211], v205 offset:2560
	s_waitcnt lgkmcnt(0)
	v_mfma_f32_16x16x32_bf16 v[46:49], v[90:93], v[208:211], v[46:49]
	v_mfma_f32_16x16x32_bf16 v[26:29], v[212:215], v[208:211], v[26:29]
	s_waitcnt vmcnt(10)
	ds_write_b128 v207, v[232:235] offset:10240
	v_mfma_f32_16x16x32_bf16 v[14:17], v[216:219], v[208:211], v[14:17]
	v_mfma_f32_16x16x32_bf16 v[10:13], v[220:223], v[208:211], v[10:13]
	ds_read_b128 v[208:211], v205 offset:5120
	s_waitcnt lgkmcnt(0)
	v_mfma_f32_16x16x32_bf16 v[34:37], v[90:93], v[208:211], v[34:37]
	v_mfma_f32_16x16x32_bf16 v[22:25], v[212:215], v[208:211], v[22:25]
	s_waitcnt vmcnt(9)
	ds_write_b128 v207, v[236:239] offset:20480
	v_mfma_f32_16x16x32_bf16 v[18:21], v[216:219], v[208:211], v[18:21]
	v_mfma_f32_16x16x32_bf16 v[62:65], v[220:223], v[208:211], v[62:65]
	ds_read_b128 v[208:211], v205 offset:7680
	s_waitcnt lgkmcnt(0)
	v_mfma_f32_16x16x32_bf16 v[58:61], v[90:93], v[208:211], v[58:61]
	ds_read_b128 v[90:93], v119 offset:64
	v_mfma_f32_16x16x32_bf16 v[54:57], v[212:215], v[208:211], v[54:57]
	s_waitcnt vmcnt(8)
	ds_write_b128 v207, v[240:243] offset:30720
	ds_read_b128 v[212:215], v119 offset:2624
	v_mfma_f32_16x16x32_bf16 v[50:53], v[216:219], v[208:211], v[50:53]
	ds_read_b128 v[216:219], v119 offset:5184
	v_mfma_f32_16x16x32_bf16 v[2:5], v[220:223], v[208:211], v[2:5]
	ds_read_b128 v[220:223], v119 offset:7744
	ds_read_b128 v[208:211], v205 offset:64
	ds_read_b128 v[224:227], v205 offset:7744
	s_waitcnt lgkmcnt(1)
	v_mfma_f32_16x16x32_bf16 v[6:9], v[90:93], v[208:211], v[6:9]
	v_mfma_f32_16x16x32_bf16 v[30:33], v[212:215], v[208:211], v[30:33]
	s_waitcnt vmcnt(7)
	ds_write_b128 v0, v[244:247] offset:20480
	v_mfma_f32_16x16x32_bf16 v[38:41], v[216:219], v[208:211], v[38:41]
	v_mfma_f32_16x16x32_bf16 v[42:45], v[220:223], v[208:211], v[42:45]
	ds_read_b128 v[208:211], v205 offset:2624
	s_waitcnt lgkmcnt(0)
	v_mfma_f32_16x16x32_bf16 v[46:49], v[90:93], v[208:211], v[46:49]
	v_mfma_f32_16x16x32_bf16 v[26:29], v[212:215], v[208:211], v[26:29]
	s_waitcnt vmcnt(6)
	ds_write_b128 v0, v[248:251] offset:30720
	global_load_dwordx4 v[228:231], v190, s[80:81] offset:128
	global_load_dwordx4 v[232:235], v191, s[80:81] offset:128
	global_load_dwordx4 v[236:239], v190, s[86:87] offset:128
	global_load_dwordx4 v[240:243], v191, s[86:87] offset:128
	global_load_dwordx4 v[244:247], v188, s[96:97] offset:128
	global_load_dwordx4 v[248:251], v188, s[98:99] offset:128
	v_mfma_f32_16x16x32_bf16 v[14:17], v[216:219], v[208:211], v[14:17]
	v_mfma_f32_16x16x32_bf16 v[10:13], v[220:223], v[208:211], v[10:13]
	ds_read_b128 v[208:211], v205 offset:5184
	s_waitcnt lgkmcnt(0)
	v_mfma_f32_16x16x32_bf16 v[34:37], v[90:93], v[208:211], v[34:37]
	v_mfma_f32_16x16x32_bf16 v[22:25], v[212:215], v[208:211], v[22:25]
	v_mfma_f32_16x16x32_bf16 v[18:21], v[216:219], v[208:211], v[18:21]
	v_mfma_f32_16x16x32_bf16 v[62:65], v[220:223], v[208:211], v[62:65]
	v_mfma_f32_16x16x32_bf16 v[58:61], v[90:93], v[224:227], v[58:61]
	s_waitcnt lgkmcnt(0)
	v_mfma_f32_16x16x32_bf16 v[54:57], v[212:215], v[224:227], v[54:57]
	s_barrier
	v_mfma_f32_16x16x32_bf16 v[50:53], v[216:219], v[224:227], v[50:53]
	v_mfma_f32_16x16x32_bf16 v[2:5], v[220:223], v[224:227], v[2:5]
	ds_read_b128 v[90:93], v119 offset:20480
	ds_read_b128 v[208:211], v205 offset:40960
	ds_read_b128 v[212:215], v119 offset:23040
	ds_read_b128 v[216:219], v119 offset:25600
	ds_read_b128 v[220:223], v119 offset:28160
	s_waitcnt lgkmcnt(3)
	v_mfma_f32_16x16x32_bf16 v[6:9], v[90:93], v[208:211], v[6:9]
	s_waitcnt lgkmcnt(2)
	v_mfma_f32_16x16x32_bf16 v[30:33], v[212:215], v[208:211], v[30:33]
	s_waitcnt lgkmcnt(1)
	v_mfma_f32_16x16x32_bf16 v[38:41], v[216:219], v[208:211], v[38:41]
	s_waitcnt lgkmcnt(0)
	v_mfma_f32_16x16x32_bf16 v[42:45], v[220:223], v[208:211], v[42:45]
	ds_read_b128 v[208:211], v205 offset:43520
	s_waitcnt lgkmcnt(0)
	v_mfma_f32_16x16x32_bf16 v[46:49], v[90:93], v[208:211], v[46:49]
	v_mfma_f32_16x16x32_bf16 v[26:29], v[212:215], v[208:211], v[26:29]
	v_mfma_f32_16x16x32_bf16 v[14:17], v[216:219], v[208:211], v[14:17]
	v_mfma_f32_16x16x32_bf16 v[10:13], v[220:223], v[208:211], v[10:13]
	ds_read_b128 v[208:211], v205 offset:46080
	s_waitcnt lgkmcnt(0)
	v_mfma_f32_16x16x32_bf16 v[34:37], v[90:93], v[208:211], v[34:37]
	v_mfma_f32_16x16x32_bf16 v[22:25], v[212:215], v[208:211], v[22:25]
	v_mfma_f32_16x16x32_bf16 v[18:21], v[216:219], v[208:211], v[18:21]
	v_mfma_f32_16x16x32_bf16 v[62:65], v[220:223], v[208:211], v[62:65]
	ds_read_b128 v[208:211], v205 offset:48640
	s_waitcnt lgkmcnt(0)
	v_mfma_f32_16x16x32_bf16 v[58:61], v[90:93], v[208:211], v[58:61]
	ds_read_b128 v[90:93], v119 offset:20544
	v_mfma_f32_16x16x32_bf16 v[54:57], v[212:215], v[208:211], v[54:57]
	ds_read_b128 v[212:215], v119 offset:23104
	v_mfma_f32_16x16x32_bf16 v[50:53], v[216:219], v[208:211], v[50:53]
	ds_read_b128 v[216:219], v119 offset:25664
	v_mfma_f32_16x16x32_bf16 v[2:5], v[220:223], v[208:211], v[2:5]
	ds_read_b128 v[220:223], v119 offset:28224
	ds_read_b128 v[208:211], v205 offset:41024
	ds_read_b128 v[224:227], v205 offset:48704
	s_waitcnt lgkmcnt(1)
	v_mfma_f32_16x16x32_bf16 v[6:9], v[90:93], v[208:211], v[6:9]
	s_waitcnt vmcnt(18)
	v_mfma_f32_16x16x32_bf16 v[30:33], v[212:215], v[208:211], v[30:33]
	v_mfma_f32_16x16x32_bf16 v[38:41], v[216:219], v[208:211], v[38:41]
	v_mfma_f32_16x16x32_bf16 v[42:45], v[220:223], v[208:211], v[42:45]
	v_cvt_f32_ubyte0_e32 v200, v138
	v_cvt_f32_ubyte1_e32 v201, v138
	v_cvt_f32_ubyte2_e32 v202, v138
	v_cvt_f32_ubyte3_e32 v255, v138
	v_mul_f32_e32 v200, s34, v200
	v_mul_f32_e32 v201, s34, v201
	v_mul_f32_e32 v202, s34, v202
	v_mul_f32_e32 v255, s34, v255
	v_fma_f32 v184, v6, v200, v184
	v_fma_f32 v185, v7, v201, v185
	v_fma_f32 v186, v8, v202, v186
	v_fma_f32 v187, v9, v255, v187
	ds_read_b128 v[208:211], v205 offset:43584
	s_waitcnt lgkmcnt(0)
	v_mfma_f32_16x16x32_bf16 v[46:49], v[90:93], v[208:211], v[46:49]
	v_cvt_f32_ubyte0_e32 v200, v139
	v_cvt_f32_ubyte1_e32 v201, v139
	v_cvt_f32_ubyte2_e32 v202, v139
	v_cvt_f32_ubyte3_e32 v255, v139
	v_mul_f32_e32 v200, s34, v200
	v_mul_f32_e32 v201, s34, v201
	v_mul_f32_e32 v202, s34, v202
	v_mul_f32_e32 v255, s34, v255
	v_fma_f32 v180, v30, v200, v180
	v_fma_f32 v181, v31, v201, v181
	v_fma_f32 v182, v32, v202, v182
	v_fma_f32 v183, v33, v255, v183
	v_mfma_f32_16x16x32_bf16 v[26:29], v[212:215], v[208:211], v[26:29]
	v_cvt_f32_ubyte0_e32 v200, v140
	v_cvt_f32_ubyte1_e32 v201, v140
	v_cvt_f32_ubyte2_e32 v202, v140
	v_cvt_f32_ubyte3_e32 v255, v140
	v_mul_f32_e32 v200, s34, v200
	v_mul_f32_e32 v201, s34, v201
	v_mul_f32_e32 v202, s34, v202
	v_mul_f32_e32 v255, s34, v255
	v_fma_f32 v176, v38, v200, v176
	v_fma_f32 v177, v39, v201, v177
	v_fma_f32 v178, v40, v202, v178
	v_fma_f32 v179, v41, v255, v179
	v_mfma_f32_16x16x32_bf16 v[14:17], v[216:219], v[208:211], v[14:17]
	v_cvt_f32_ubyte0_e32 v200, v141
	v_cvt_f32_ubyte1_e32 v201, v141
	v_cvt_f32_ubyte2_e32 v202, v141
	v_cvt_f32_ubyte3_e32 v255, v141
	v_mul_f32_e32 v200, s34, v200
	v_mul_f32_e32 v201, s34, v201
	v_mul_f32_e32 v202, s34, v202
	v_mul_f32_e32 v255, s34, v255
	v_fma_f32 v172, v42, v200, v172
	v_fma_f32 v173, v43, v201, v173
	v_fma_f32 v174, v44, v202, v174
	v_fma_f32 v175, v45, v255, v175
	v_mfma_f32_16x16x32_bf16 v[10:13], v[220:223], v[208:211], v[10:13]
	v_cvt_f32_ubyte0_e32 v200, v142
	v_cvt_f32_ubyte1_e32 v201, v142
	v_cvt_f32_ubyte2_e32 v202, v142
	v_cvt_f32_ubyte3_e32 v255, v142
	v_mul_f32_e32 v200, s34, v200
	v_mul_f32_e32 v201, s34, v201
	v_mul_f32_e32 v202, s34, v202
	v_mul_f32_e32 v255, s34, v255
	v_fma_f32 v168, v46, v200, v168
	v_fma_f32 v169, v47, v201, v169
	v_fma_f32 v170, v48, v202, v170
	v_fma_f32 v171, v49, v255, v171
	ds_read_b128 v[208:211], v205 offset:46144
	s_waitcnt lgkmcnt(0)
	v_mfma_f32_16x16x32_bf16 v[34:37], v[90:93], v[208:211], v[34:37]
	v_cvt_f32_ubyte0_e32 v200, v143
	v_cvt_f32_ubyte1_e32 v201, v143
	v_cvt_f32_ubyte2_e32 v202, v143
	v_cvt_f32_ubyte3_e32 v255, v143
	v_mul_f32_e32 v200, s34, v200
	v_mul_f32_e32 v201, s34, v201
	v_mul_f32_e32 v202, s34, v202
	v_mul_f32_e32 v255, s34, v255
	v_fma_f32 v164, v26, v200, v164
	v_fma_f32 v165, v27, v201, v165
	v_fma_f32 v166, v28, v202, v166
	v_fma_f32 v167, v29, v255, v167
	v_mfma_f32_16x16x32_bf16 v[22:25], v[212:215], v[208:211], v[22:25]
	v_cvt_f32_ubyte0_e32 v200, v144
	v_cvt_f32_ubyte1_e32 v201, v144
	v_cvt_f32_ubyte2_e32 v202, v144
	v_cvt_f32_ubyte3_e32 v255, v144
	v_mul_f32_e32 v200, s34, v200
	v_mul_f32_e32 v201, s34, v201
	v_mul_f32_e32 v202, s34, v202
	v_mul_f32_e32 v255, s34, v255
	v_fma_f32 v160, v14, v200, v160
	v_fma_f32 v161, v15, v201, v161
	v_fma_f32 v162, v16, v202, v162
	v_fma_f32 v163, v17, v255, v163
	v_mfma_f32_16x16x32_bf16 v[18:21], v[216:219], v[208:211], v[18:21]
	v_cvt_f32_ubyte0_e32 v200, v145
	v_cvt_f32_ubyte1_e32 v201, v145
	v_cvt_f32_ubyte2_e32 v202, v145
	v_cvt_f32_ubyte3_e32 v255, v145
	v_mul_f32_e32 v200, s34, v200
	v_mul_f32_e32 v201, s34, v201
	v_mul_f32_e32 v202, s34, v202
	v_mul_f32_e32 v255, s34, v255
	v_fma_f32 v156, v10, v200, v156
	v_fma_f32 v157, v11, v201, v157
	v_fma_f32 v158, v12, v202, v158
	v_fma_f32 v159, v13, v255, v159
	v_mfma_f32_16x16x32_bf16 v[62:65], v[220:223], v[208:211], v[62:65]
	v_cvt_f32_ubyte0_e32 v200, v146
	v_cvt_f32_ubyte1_e32 v201, v146
	v_cvt_f32_ubyte2_e32 v202, v146
	v_cvt_f32_ubyte3_e32 v255, v146
	v_mul_f32_e32 v200, s34, v200
	v_mul_f32_e32 v201, s34, v201
	v_mul_f32_e32 v202, s34, v202
	v_mul_f32_e32 v255, s34, v255
	v_fma_f32 v136, v34, v200, v136
	v_fma_f32 v137, v35, v201, v137
	v_fma_f32 v150, v36, v202, v150
	v_fma_f32 v151, v37, v255, v151
	v_mfma_f32_16x16x32_bf16 v[58:61], v[90:93], v[224:227], v[58:61]
	v_cvt_f32_ubyte0_e32 v200, v147
	v_cvt_f32_ubyte1_e32 v201, v147
	v_cvt_f32_ubyte2_e32 v202, v147
	v_cvt_f32_ubyte3_e32 v255, v147
	v_mul_f32_e32 v200, s34, v200
	v_mul_f32_e32 v201, s34, v201
	v_mul_f32_e32 v202, s34, v202
	v_mul_f32_e32 v255, s34, v255
	v_fma_f32 v130, v22, v200, v130
	v_fma_f32 v131, v23, v201, v131
	v_fma_f32 v134, v24, v202, v134
	v_fma_f32 v135, v25, v255, v135
	v_mfma_f32_16x16x32_bf16 v[54:57], v[212:215], v[224:227], v[54:57]
	v_cvt_f32_ubyte0_e32 v200, v148
	v_cvt_f32_ubyte1_e32 v201, v148
	v_cvt_f32_ubyte2_e32 v202, v148
	v_cvt_f32_ubyte3_e32 v255, v148
	v_mul_f32_e32 v200, s34, v200
	v_mul_f32_e32 v201, s34, v201
	v_mul_f32_e32 v202, s34, v202
	v_mul_f32_e32 v255, s34, v255
	v_fma_f32 v124, v18, v200, v124
	v_fma_f32 v125, v19, v201, v125
	v_fma_f32 v126, v20, v202, v126
	v_fma_f32 v127, v21, v255, v127
	v_mfma_f32_16x16x32_bf16 v[50:53], v[216:219], v[224:227], v[50:53]
	v_cvt_f32_ubyte0_e32 v200, v149
	v_cvt_f32_ubyte1_e32 v201, v149
	v_cvt_f32_ubyte2_e32 v202, v149
	v_cvt_f32_ubyte3_e32 v255, v149
	v_mul_f32_e32 v200, s34, v200
	v_mul_f32_e32 v201, s34, v201
	v_mul_f32_e32 v202, s34, v202
	v_mul_f32_e32 v255, s34, v255
	v_fma_f32 v120, v62, v200, v120
	v_fma_f32 v121, v63, v201, v121
	v_fma_f32 v122, v64, v202, v122
	v_fma_f32 v123, v65, v255, v123
	v_mfma_f32_16x16x32_bf16 v[2:5], v[220:223], v[224:227], v[2:5]
	v_cvt_f32_ubyte0_e32 v200, v194
	v_cvt_f32_ubyte1_e32 v201, v194
	v_cvt_f32_ubyte2_e32 v202, v194
	v_cvt_f32_ubyte3_e32 v255, v194
	v_mul_f32_e32 v200, s34, v200
	v_mul_f32_e32 v201, s34, v201
	v_mul_f32_e32 v202, s34, v202
	v_mul_f32_e32 v255, s34, v255
	v_fma_f32 v114, v58, v200, v114
	v_fma_f32 v115, v59, v201, v115
	v_fma_f32 v116, v60, v202, v116
	v_fma_f32 v117, v61, v255, v117
	s_nop 7
	s_nop 3
	v_cvt_f32_ubyte0_e32 v200, v195
	v_cvt_f32_ubyte1_e32 v201, v195
	v_cvt_f32_ubyte2_e32 v202, v195
	v_cvt_f32_ubyte3_e32 v255, v195
	v_mul_f32_e32 v200, s34, v200
	v_mul_f32_e32 v201, s34, v201
	v_mul_f32_e32 v202, s34, v202
	v_mul_f32_e32 v255, s34, v255
	v_fma_f32 v106, v54, v200, v106
	v_fma_f32 v107, v55, v201, v107
	v_fma_f32 v108, v56, v202, v108
	v_fma_f32 v109, v57, v255, v109
	v_cvt_f32_ubyte0_e32 v200, v196
	v_cvt_f32_ubyte1_e32 v201, v196
	v_cvt_f32_ubyte2_e32 v202, v196
	v_cvt_f32_ubyte3_e32 v255, v196
	v_mul_f32_e32 v200, s34, v200
	v_mul_f32_e32 v201, s34, v201
	v_mul_f32_e32 v202, s34, v202
	v_mul_f32_e32 v255, s34, v255
	v_fma_f32 v100, v50, v200, v100
	v_fma_f32 v101, v51, v201, v101
	v_fma_f32 v102, v52, v202, v102
	v_fma_f32 v103, v53, v255, v103
	v_cvt_f32_ubyte0_e32 v200, v197
	v_cvt_f32_ubyte1_e32 v201, v197
	v_cvt_f32_ubyte2_e32 v202, v197
	v_cvt_f32_ubyte3_e32 v255, v197
	v_mul_f32_e32 v200, s34, v200
	v_mul_f32_e32 v201, s34, v201
	v_mul_f32_e32 v202, s34, v202
	v_mul_f32_e32 v255, s34, v255
	v_fma_f32 v96, v2, v200, v96
	v_fma_f32 v97, v3, v201, v97
	v_fma_f32 v98, v4, v202, v98
	v_fma_f32 v99, v5, v255, v99
	s_waitcnt vmcnt(11)
	ds_write_b128 v206, v[66:69] offset:0
	s_waitcnt vmcnt(10)
	ds_write_b128 v206, v[70:73] offset:10240
	s_waitcnt vmcnt(9)
	ds_write_b128 v206, v[74:77] offset:20480
	s_waitcnt vmcnt(8)
	ds_write_b128 v206, v[78:81] offset:30720
	s_waitcnt vmcnt(7)
	ds_write_b128 v0, v[82:85] offset:0
	s_waitcnt vmcnt(6)
	ds_write_b128 v0, v[86:89] offset:10240
	s_waitcnt lgkmcnt(0)
	s_barrier
	global_load_dwordx4 v[66:69], v190, s[80:81] offset:256
	global_load_dwordx4 v[70:73], v191, s[80:81] offset:256
	global_load_dwordx4 v[74:77], v190, s[86:87] offset:256
	global_load_dwordx4 v[78:81], v191, s[86:87] offset:256
	global_load_dwordx4 v[82:85], v188, s[96:97] offset:256
	global_load_dwordx4 v[86:89], v188, s[98:99] offset:256
	ds_read_b128 v[90:93], v119 offset:0
	ds_read_b128 v[208:211], v205 offset:0
	ds_read_b128 v[212:215], v119 offset:2560
	ds_read_b128 v[216:219], v119 offset:5120
	ds_read_b128 v[220:223], v119 offset:7680
	s_waitcnt lgkmcnt(3)
	v_mfma_f32_16x16x32_bf16 v[6:9], v[90:93], v[208:211], 0
	s_waitcnt lgkmcnt(2)
	v_mfma_f32_16x16x32_bf16 v[30:33], v[212:215], v[208:211], 0
	s_waitcnt vmcnt(11)
	ds_write_b128 v207, v[228:231] offset:0
	s_waitcnt lgkmcnt(2)
	v_mfma_f32_16x16x32_bf16 v[38:41], v[216:219], v[208:211], 0
	s_waitcnt lgkmcnt(1)
	v_mfma_f32_16x16x32_bf16 v[42:45], v[220:223], v[208:211], 0
	ds_read_b128 v[208:211], v205 offset:2560
	s_waitcnt lgkmcnt(0)
	v_mfma_f32_16x16x32_bf16 v[46:49], v[90:93], v[208:211], 0
	v_mfma_f32_16x16x32_bf16 v[26:29], v[212:215], v[208:211], 0
	s_waitcnt vmcnt(10)
	ds_write_b128 v207, v[232:235] offset:10240
	v_mfma_f32_16x16x32_bf16 v[14:17], v[216:219], v[208:211], 0
	v_mfma_f32_16x16x32_bf16 v[10:13], v[220:223], v[208:211], 0
	ds_read_b128 v[208:211], v205 offset:5120
	s_waitcnt lgkmcnt(0)
	v_mfma_f32_16x16x32_bf16 v[34:37], v[90:93], v[208:211], 0
	v_mfma_f32_16x16x32_bf16 v[22:25], v[212:215], v[208:211], 0
	s_waitcnt vmcnt(9)
	ds_write_b128 v207, v[236:239] offset:20480
	v_mfma_f32_16x16x32_bf16 v[18:21], v[216:219], v[208:211], 0
	v_mfma_f32_16x16x32_bf16 v[62:65], v[220:223], v[208:211], 0
	ds_read_b128 v[208:211], v205 offset:7680
	s_waitcnt lgkmcnt(0)
	v_mfma_f32_16x16x32_bf16 v[58:61], v[90:93], v[208:211], 0
	ds_read_b128 v[90:93], v119 offset:64
	v_mfma_f32_16x16x32_bf16 v[54:57], v[212:215], v[208:211], 0
	s_waitcnt vmcnt(8)
	ds_write_b128 v207, v[240:243] offset:30720
	ds_read_b128 v[212:215], v119 offset:2624
	v_mfma_f32_16x16x32_bf16 v[50:53], v[216:219], v[208:211], 0
	ds_read_b128 v[216:219], v119 offset:5184
	v_mfma_f32_16x16x32_bf16 v[2:5], v[220:223], v[208:211], 0
	ds_read_b128 v[220:223], v119 offset:7744
	ds_read_b128 v[208:211], v205 offset:64
	ds_read_b128 v[224:227], v205 offset:7744
	s_waitcnt lgkmcnt(1)
	v_mfma_f32_16x16x32_bf16 v[6:9], v[90:93], v[208:211], v[6:9]
	v_mfma_f32_16x16x32_bf16 v[30:33], v[212:215], v[208:211], v[30:33]
	s_waitcnt vmcnt(7)
	ds_write_b128 v0, v[244:247] offset:20480
	v_mfma_f32_16x16x32_bf16 v[38:41], v[216:219], v[208:211], v[38:41]
	v_mfma_f32_16x16x32_bf16 v[42:45], v[220:223], v[208:211], v[42:45]
	ds_read_b128 v[208:211], v205 offset:2624
	s_waitcnt lgkmcnt(0)
	v_mfma_f32_16x16x32_bf16 v[46:49], v[90:93], v[208:211], v[46:49]
	v_mfma_f32_16x16x32_bf16 v[26:29], v[212:215], v[208:211], v[26:29]
	s_waitcnt vmcnt(6)
	ds_write_b128 v0, v[248:251] offset:30720
	v_mfma_f32_16x16x32_bf16 v[14:17], v[216:219], v[208:211], v[14:17]
	v_mfma_f32_16x16x32_bf16 v[10:13], v[220:223], v[208:211], v[10:13]
	ds_read_b128 v[208:211], v205 offset:5184
	s_waitcnt lgkmcnt(0)
	v_mfma_f32_16x16x32_bf16 v[34:37], v[90:93], v[208:211], v[34:37]
	v_mfma_f32_16x16x32_bf16 v[22:25], v[212:215], v[208:211], v[22:25]
	v_mfma_f32_16x16x32_bf16 v[18:21], v[216:219], v[208:211], v[18:21]
	v_mfma_f32_16x16x32_bf16 v[62:65], v[220:223], v[208:211], v[62:65]
	v_mfma_f32_16x16x32_bf16 v[58:61], v[90:93], v[224:227], v[58:61]
	s_waitcnt lgkmcnt(0)
	v_mfma_f32_16x16x32_bf16 v[54:57], v[212:215], v[224:227], v[54:57]
	s_barrier
	v_mfma_f32_16x16x32_bf16 v[50:53], v[216:219], v[224:227], v[50:53]
	v_mfma_f32_16x16x32_bf16 v[2:5], v[220:223], v[224:227], v[2:5]
	global_load_dwordx4 v[228:231], v190, s[80:81] offset:384
	global_load_dwordx4 v[232:235], v191, s[80:81] offset:384
	global_load_dwordx4 v[236:239], v190, s[86:87] offset:384
	global_load_dwordx4 v[240:243], v191, s[86:87] offset:384
	global_load_dwordx4 v[244:247], v188, s[96:97] offset:384
	global_load_dwordx4 v[248:251], v188, s[98:99] offset:384
	ds_read_b128 v[90:93], v119 offset:20480
	ds_read_b128 v[208:211], v205 offset:40960
	ds_read_b128 v[212:215], v119 offset:23040
	ds_read_b128 v[216:219], v119 offset:25600
	ds_read_b128 v[220:223], v119 offset:28160
	s_waitcnt lgkmcnt(3)
	v_mfma_f32_16x16x32_bf16 v[6:9], v[90:93], v[208:211], v[6:9]
	s_waitcnt lgkmcnt(2)
	v_mfma_f32_16x16x32_bf16 v[30:33], v[212:215], v[208:211], v[30:33]
	s_waitcnt vmcnt(11)
	ds_write_b128 v206, v[66:69] offset:0
	s_waitcnt lgkmcnt(2)
	v_mfma_f32_16x16x32_bf16 v[38:41], v[216:219], v[208:211], v[38:41]
	s_waitcnt lgkmcnt(1)
	v_mfma_f32_16x16x32_bf16 v[42:45], v[220:223], v[208:211], v[42:45]
	ds_read_b128 v[208:211], v205 offset:43520
	s_waitcnt lgkmcnt(0)
	v_mfma_f32_16x16x32_bf16 v[46:49], v[90:93], v[208:211], v[46:49]
	v_mfma_f32_16x16x32_bf16 v[26:29], v[212:215], v[208:211], v[26:29]
	s_waitcnt vmcnt(10)
	ds_write_b128 v206, v[70:73] offset:10240
	v_mfma_f32_16x16x32_bf16 v[14:17], v[216:219], v[208:211], v[14:17]
	v_mfma_f32_16x16x32_bf16 v[10:13], v[220:223], v[208:211], v[10:13]
	ds_read_b128 v[208:211], v205 offset:46080
	s_waitcnt lgkmcnt(0)
	v_mfma_f32_16x16x32_bf16 v[34:37], v[90:93], v[208:211], v[34:37]
	v_mfma_f32_16x16x32_bf16 v[22:25], v[212:215], v[208:211], v[22:25]
	s_waitcnt vmcnt(9)
	ds_write_b128 v206, v[74:77] offset:20480
	v_mfma_f32_16x16x32_bf16 v[18:21], v[216:219], v[208:211], v[18:21]
	v_mfma_f32_16x16x32_bf16 v[62:65], v[220:223], v[208:211], v[62:65]
	ds_read_b128 v[208:211], v205 offset:48640
	s_waitcnt lgkmcnt(0)
	v_mfma_f32_16x16x32_bf16 v[58:61], v[90:93], v[208:211], v[58:61]
	ds_read_b128 v[90:93], v119 offset:20544
	v_mfma_f32_16x16x32_bf16 v[54:57], v[212:215], v[208:211], v[54:57]
	s_waitcnt vmcnt(8)
	ds_write_b128 v206, v[78:81] offset:30720
	ds_read_b128 v[212:215], v119 offset:23104
	v_mfma_f32_16x16x32_bf16 v[50:53], v[216:219], v[208:211], v[50:53]
	ds_read_b128 v[216:219], v119 offset:25664
	v_mfma_f32_16x16x32_bf16 v[2:5], v[220:223], v[208:211], v[2:5]
	ds_read_b128 v[220:223], v119 offset:28224
	ds_read_b128 v[208:211], v205 offset:41024
	ds_read_b128 v[224:227], v205 offset:48704
	s_waitcnt lgkmcnt(1)
	v_mfma_f32_16x16x32_bf16 v[6:9], v[90:93], v[208:211], v[6:9]
	v_mfma_f32_16x16x32_bf16 v[30:33], v[212:215], v[208:211], v[30:33]
	s_waitcnt vmcnt(7)
	ds_write_b128 v0, v[82:85] offset:0
	v_mfma_f32_16x16x32_bf16 v[38:41], v[216:219], v[208:211], v[38:41]
	v_mfma_f32_16x16x32_bf16 v[42:45], v[220:223], v[208:211], v[42:45]
	ds_read_b128 v[208:211], v205 offset:43584
	s_waitcnt lgkmcnt(0)
	v_mfma_f32_16x16x32_bf16 v[46:49], v[90:93], v[208:211], v[46:49]
	v_mfma_f32_16x16x32_bf16 v[26:29], v[212:215], v[208:211], v[26:29]
	s_waitcnt vmcnt(6)
	ds_write_b128 v0, v[86:89] offset:10240
	v_mfma_f32_16x16x32_bf16 v[14:17], v[216:219], v[208:211], v[14:17]
	v_mfma_f32_16x16x32_bf16 v[10:13], v[220:223], v[208:211], v[10:13]
	ds_read_b128 v[208:211], v205 offset:46144
	s_waitcnt lgkmcnt(0)
	v_mfma_f32_16x16x32_bf16 v[34:37], v[90:93], v[208:211], v[34:37]
	v_mfma_f32_16x16x32_bf16 v[22:25], v[212:215], v[208:211], v[22:25]
	v_mfma_f32_16x16x32_bf16 v[18:21], v[216:219], v[208:211], v[18:21]
	v_mfma_f32_16x16x32_bf16 v[62:65], v[220:223], v[208:211], v[62:65]
	v_mfma_f32_16x16x32_bf16 v[58:61], v[90:93], v[224:227], v[58:61]
	s_waitcnt lgkmcnt(0)
	v_mfma_f32_16x16x32_bf16 v[54:57], v[212:215], v[224:227], v[54:57]
	s_barrier
	v_mfma_f32_16x16x32_bf16 v[50:53], v[216:219], v[224:227], v[50:53]
	v_mfma_f32_16x16x32_bf16 v[2:5], v[220:223], v[224:227], v[2:5]
	global_load_dwordx4 v[66:69], v190, s[80:81] offset:512
	global_load_dwordx4 v[70:73], v191, s[80:81] offset:512
	global_load_dwordx4 v[74:77], v190, s[86:87] offset:512
	global_load_dwordx4 v[78:81], v191, s[86:87] offset:512
	global_load_dwordx4 v[82:85], v188, s[96:97] offset:512
	global_load_dwordx4 v[86:89], v188, s[98:99] offset:512
	ds_read_b128 v[90:93], v119 offset:0
	ds_read_b128 v[208:211], v205 offset:0
	ds_read_b128 v[212:215], v119 offset:2560
	ds_read_b128 v[216:219], v119 offset:5120
	ds_read_b128 v[220:223], v119 offset:7680
	s_waitcnt lgkmcnt(3)
	v_mfma_f32_16x16x32_bf16 v[6:9], v[90:93], v[208:211], v[6:9]
	s_waitcnt lgkmcnt(2)
	v_mfma_f32_16x16x32_bf16 v[30:33], v[212:215], v[208:211], v[30:33]
	s_waitcnt vmcnt(11)
	ds_write_b128 v207, v[228:231] offset:0
	s_waitcnt lgkmcnt(2)
	v_mfma_f32_16x16x32_bf16 v[38:41], v[216:219], v[208:211], v[38:41]
	s_waitcnt lgkmcnt(1)
	v_mfma_f32_16x16x32_bf16 v[42:45], v[220:223], v[208:211], v[42:45]
	ds_read_b128 v[208:211], v205 offset:2560
	s_waitcnt lgkmcnt(0)
	v_mfma_f32_16x16x32_bf16 v[46:49], v[90:93], v[208:211], v[46:49]
	v_mfma_f32_16x16x32_bf16 v[26:29], v[212:215], v[208:211], v[26:29]
	s_waitcnt vmcnt(10)
	ds_write_b128 v207, v[232:235] offset:10240
	v_mfma_f32_16x16x32_bf16 v[14:17], v[216:219], v[208:211], v[14:17]
	v_mfma_f32_16x16x32_bf16 v[10:13], v[220:223], v[208:211], v[10:13]
	ds_read_b128 v[208:211], v205 offset:5120
	s_waitcnt lgkmcnt(0)
	v_mfma_f32_16x16x32_bf16 v[34:37], v[90:93], v[208:211], v[34:37]
	v_mfma_f32_16x16x32_bf16 v[22:25], v[212:215], v[208:211], v[22:25]
	s_waitcnt vmcnt(9)
	ds_write_b128 v207, v[236:239] offset:20480
	v_mfma_f32_16x16x32_bf16 v[18:21], v[216:219], v[208:211], v[18:21]
	v_mfma_f32_16x16x32_bf16 v[62:65], v[220:223], v[208:211], v[62:65]
	ds_read_b128 v[208:211], v205 offset:7680
	s_waitcnt lgkmcnt(0)
	v_mfma_f32_16x16x32_bf16 v[58:61], v[90:93], v[208:211], v[58:61]
	ds_read_b128 v[90:93], v119 offset:64
	v_mfma_f32_16x16x32_bf16 v[54:57], v[212:215], v[208:211], v[54:57]
	s_waitcnt vmcnt(8)
	ds_write_b128 v207, v[240:243] offset:30720
	ds_read_b128 v[212:215], v119 offset:2624
	v_mfma_f32_16x16x32_bf16 v[50:53], v[216:219], v[208:211], v[50:53]
	ds_read_b128 v[216:219], v119 offset:5184
	v_mfma_f32_16x16x32_bf16 v[2:5], v[220:223], v[208:211], v[2:5]
	ds_read_b128 v[220:223], v119 offset:7744
	ds_read_b128 v[208:211], v205 offset:64
	ds_read_b128 v[224:227], v205 offset:7744
	s_waitcnt lgkmcnt(1)
	v_mfma_f32_16x16x32_bf16 v[6:9], v[90:93], v[208:211], v[6:9]
	v_mfma_f32_16x16x32_bf16 v[30:33], v[212:215], v[208:211], v[30:33]
	s_waitcnt vmcnt(7)
	ds_write_b128 v0, v[244:247] offset:20480
	v_mfma_f32_16x16x32_bf16 v[38:41], v[216:219], v[208:211], v[38:41]
	v_mfma_f32_16x16x32_bf16 v[42:45], v[220:223], v[208:211], v[42:45]
	ds_read_b128 v[208:211], v205 offset:2624
	s_waitcnt lgkmcnt(0)
	v_mfma_f32_16x16x32_bf16 v[46:49], v[90:93], v[208:211], v[46:49]
	v_mfma_f32_16x16x32_bf16 v[26:29], v[212:215], v[208:211], v[26:29]
	s_waitcnt vmcnt(6)
	ds_write_b128 v0, v[248:251] offset:30720
	v_mfma_f32_16x16x32_bf16 v[14:17], v[216:219], v[208:211], v[14:17]
	v_mfma_f32_16x16x32_bf16 v[10:13], v[220:223], v[208:211], v[10:13]
	ds_read_b128 v[208:211], v205 offset:5184
	s_waitcnt lgkmcnt(0)
	v_mfma_f32_16x16x32_bf16 v[34:37], v[90:93], v[208:211], v[34:37]
	v_mfma_f32_16x16x32_bf16 v[22:25], v[212:215], v[208:211], v[22:25]
	v_mfma_f32_16x16x32_bf16 v[18:21], v[216:219], v[208:211], v[18:21]
	v_mfma_f32_16x16x32_bf16 v[62:65], v[220:223], v[208:211], v[62:65]
	v_mfma_f32_16x16x32_bf16 v[58:61], v[90:93], v[224:227], v[58:61]
	s_waitcnt lgkmcnt(0)
	v_mfma_f32_16x16x32_bf16 v[54:57], v[212:215], v[224:227], v[54:57]
	s_barrier
	v_mfma_f32_16x16x32_bf16 v[50:53], v[216:219], v[224:227], v[50:53]
	v_mfma_f32_16x16x32_bf16 v[2:5], v[220:223], v[224:227], v[2:5]
	global_load_dwordx4 v[228:231], v190, s[80:81] offset:640
	global_load_dwordx4 v[232:235], v191, s[80:81] offset:640
	global_load_dwordx4 v[236:239], v190, s[86:87] offset:640
	global_load_dwordx4 v[240:243], v191, s[86:87] offset:640
	global_load_dwordx4 v[244:247], v188, s[96:97] offset:640
	global_load_dwordx4 v[248:251], v188, s[98:99] offset:640
	ds_read_b128 v[90:93], v119 offset:20480
	ds_read_b128 v[208:211], v205 offset:40960
	ds_read_b128 v[212:215], v119 offset:23040
	ds_read_b128 v[216:219], v119 offset:25600
	ds_read_b128 v[220:223], v119 offset:28160
	s_waitcnt lgkmcnt(3)
	v_mfma_f32_16x16x32_bf16 v[6:9], v[90:93], v[208:211], v[6:9]
	s_waitcnt lgkmcnt(2)
	v_mfma_f32_16x16x32_bf16 v[30:33], v[212:215], v[208:211], v[30:33]
	s_waitcnt vmcnt(11)
	ds_write_b128 v206, v[66:69] offset:0
	s_waitcnt lgkmcnt(2)
	v_mfma_f32_16x16x32_bf16 v[38:41], v[216:219], v[208:211], v[38:41]
	s_waitcnt lgkmcnt(1)
	v_mfma_f32_16x16x32_bf16 v[42:45], v[220:223], v[208:211], v[42:45]
	ds_read_b128 v[208:211], v205 offset:43520
	s_waitcnt lgkmcnt(0)
	v_mfma_f32_16x16x32_bf16 v[46:49], v[90:93], v[208:211], v[46:49]
	v_mfma_f32_16x16x32_bf16 v[26:29], v[212:215], v[208:211], v[26:29]
	s_waitcnt vmcnt(10)
	ds_write_b128 v206, v[70:73] offset:10240
	v_mfma_f32_16x16x32_bf16 v[14:17], v[216:219], v[208:211], v[14:17]
	v_mfma_f32_16x16x32_bf16 v[10:13], v[220:223], v[208:211], v[10:13]
	ds_read_b128 v[208:211], v205 offset:46080
	s_waitcnt lgkmcnt(0)
	v_mfma_f32_16x16x32_bf16 v[34:37], v[90:93], v[208:211], v[34:37]
	v_mfma_f32_16x16x32_bf16 v[22:25], v[212:215], v[208:211], v[22:25]
	s_waitcnt vmcnt(9)
	ds_write_b128 v206, v[74:77] offset:20480
	v_mfma_f32_16x16x32_bf16 v[18:21], v[216:219], v[208:211], v[18:21]
	v_mfma_f32_16x16x32_bf16 v[62:65], v[220:223], v[208:211], v[62:65]
	ds_read_b128 v[208:211], v205 offset:48640
	s_waitcnt lgkmcnt(0)
	v_mfma_f32_16x16x32_bf16 v[58:61], v[90:93], v[208:211], v[58:61]
	ds_read_b128 v[90:93], v119 offset:20544
	v_mfma_f32_16x16x32_bf16 v[54:57], v[212:215], v[208:211], v[54:57]
	s_waitcnt vmcnt(8)
	ds_write_b128 v206, v[78:81] offset:30720
	ds_read_b128 v[212:215], v119 offset:23104
	v_mfma_f32_16x16x32_bf16 v[50:53], v[216:219], v[208:211], v[50:53]
	ds_read_b128 v[216:219], v119 offset:25664
	v_mfma_f32_16x16x32_bf16 v[2:5], v[220:223], v[208:211], v[2:5]
	ds_read_b128 v[220:223], v119 offset:28224
	ds_read_b128 v[208:211], v205 offset:41024
	ds_read_b128 v[224:227], v205 offset:48704
	s_waitcnt lgkmcnt(1)
	v_mfma_f32_16x16x32_bf16 v[6:9], v[90:93], v[208:211], v[6:9]
	v_mfma_f32_16x16x32_bf16 v[30:33], v[212:215], v[208:211], v[30:33]
	s_waitcnt vmcnt(7)
	ds_write_b128 v0, v[82:85] offset:0
	v_mfma_f32_16x16x32_bf16 v[38:41], v[216:219], v[208:211], v[38:41]
	v_mfma_f32_16x16x32_bf16 v[42:45], v[220:223], v[208:211], v[42:45]
	ds_read_b128 v[208:211], v205 offset:43584
	s_waitcnt lgkmcnt(0)
	v_mfma_f32_16x16x32_bf16 v[46:49], v[90:93], v[208:211], v[46:49]
	v_mfma_f32_16x16x32_bf16 v[26:29], v[212:215], v[208:211], v[26:29]
	s_waitcnt vmcnt(6)
	ds_write_b128 v0, v[86:89] offset:10240
	v_mfma_f32_16x16x32_bf16 v[14:17], v[216:219], v[208:211], v[14:17]
	v_mfma_f32_16x16x32_bf16 v[10:13], v[220:223], v[208:211], v[10:13]
	ds_read_b128 v[208:211], v205 offset:46144
	s_waitcnt lgkmcnt(0)
	v_mfma_f32_16x16x32_bf16 v[34:37], v[90:93], v[208:211], v[34:37]
	v_mfma_f32_16x16x32_bf16 v[22:25], v[212:215], v[208:211], v[22:25]
	v_mfma_f32_16x16x32_bf16 v[18:21], v[216:219], v[208:211], v[18:21]
	v_mfma_f32_16x16x32_bf16 v[62:65], v[220:223], v[208:211], v[62:65]
	v_mfma_f32_16x16x32_bf16 v[58:61], v[90:93], v[224:227], v[58:61]
	s_waitcnt lgkmcnt(0)
	v_mfma_f32_16x16x32_bf16 v[54:57], v[212:215], v[224:227], v[54:57]
	s_barrier
	v_mfma_f32_16x16x32_bf16 v[50:53], v[216:219], v[224:227], v[50:53]
	v_mfma_f32_16x16x32_bf16 v[2:5], v[220:223], v[224:227], v[2:5]
	global_load_dwordx4 v[66:69], v190, s[80:81] offset:768
	global_load_dwordx4 v[70:73], v191, s[80:81] offset:768
	global_load_dwordx4 v[74:77], v190, s[86:87] offset:768
	global_load_dwordx4 v[78:81], v191, s[86:87] offset:768
	global_load_dwordx4 v[82:85], v188, s[96:97] offset:768
	global_load_dwordx4 v[86:89], v188, s[98:99] offset:768
	ds_read_b128 v[90:93], v119 offset:0
	ds_read_b128 v[208:211], v205 offset:0
	ds_read_b128 v[212:215], v119 offset:2560
	ds_read_b128 v[216:219], v119 offset:5120
	ds_read_b128 v[220:223], v119 offset:7680
	s_waitcnt lgkmcnt(3)
	v_mfma_f32_16x16x32_bf16 v[6:9], v[90:93], v[208:211], v[6:9]
	s_waitcnt lgkmcnt(2)
	v_mfma_f32_16x16x32_bf16 v[30:33], v[212:215], v[208:211], v[30:33]
	s_waitcnt vmcnt(11)
	ds_write_b128 v207, v[228:231] offset:0
	s_waitcnt lgkmcnt(2)
	v_mfma_f32_16x16x32_bf16 v[38:41], v[216:219], v[208:211], v[38:41]
	s_waitcnt lgkmcnt(1)
	v_mfma_f32_16x16x32_bf16 v[42:45], v[220:223], v[208:211], v[42:45]
	ds_read_b128 v[208:211], v205 offset:2560
	s_waitcnt lgkmcnt(0)
	v_mfma_f32_16x16x32_bf16 v[46:49], v[90:93], v[208:211], v[46:49]
	v_mfma_f32_16x16x32_bf16 v[26:29], v[212:215], v[208:211], v[26:29]
	s_waitcnt vmcnt(10)
	ds_write_b128 v207, v[232:235] offset:10240
	v_mfma_f32_16x16x32_bf16 v[14:17], v[216:219], v[208:211], v[14:17]
	v_mfma_f32_16x16x32_bf16 v[10:13], v[220:223], v[208:211], v[10:13]
	ds_read_b128 v[208:211], v205 offset:5120
	s_waitcnt lgkmcnt(0)
	v_mfma_f32_16x16x32_bf16 v[34:37], v[90:93], v[208:211], v[34:37]
	v_mfma_f32_16x16x32_bf16 v[22:25], v[212:215], v[208:211], v[22:25]
	s_waitcnt vmcnt(9)
	ds_write_b128 v207, v[236:239] offset:20480
	v_mfma_f32_16x16x32_bf16 v[18:21], v[216:219], v[208:211], v[18:21]
	v_mfma_f32_16x16x32_bf16 v[62:65], v[220:223], v[208:211], v[62:65]
	ds_read_b128 v[208:211], v205 offset:7680
	s_waitcnt lgkmcnt(0)
	v_mfma_f32_16x16x32_bf16 v[58:61], v[90:93], v[208:211], v[58:61]
	ds_read_b128 v[90:93], v119 offset:64
	v_mfma_f32_16x16x32_bf16 v[54:57], v[212:215], v[208:211], v[54:57]
	s_waitcnt vmcnt(8)
	ds_write_b128 v207, v[240:243] offset:30720
	ds_read_b128 v[212:215], v119 offset:2624
	v_mfma_f32_16x16x32_bf16 v[50:53], v[216:219], v[208:211], v[50:53]
	ds_read_b128 v[216:219], v119 offset:5184
	v_mfma_f32_16x16x32_bf16 v[2:5], v[220:223], v[208:211], v[2:5]
	ds_read_b128 v[220:223], v119 offset:7744
	ds_read_b128 v[208:211], v205 offset:64
	ds_read_b128 v[224:227], v205 offset:7744
	s_waitcnt lgkmcnt(1)
	v_mfma_f32_16x16x32_bf16 v[6:9], v[90:93], v[208:211], v[6:9]
	v_mfma_f32_16x16x32_bf16 v[30:33], v[212:215], v[208:211], v[30:33]
	s_waitcnt vmcnt(7)
	ds_write_b128 v0, v[244:247] offset:20480
	v_mfma_f32_16x16x32_bf16 v[38:41], v[216:219], v[208:211], v[38:41]
	v_mfma_f32_16x16x32_bf16 v[42:45], v[220:223], v[208:211], v[42:45]
	ds_read_b128 v[208:211], v205 offset:2624
	s_waitcnt lgkmcnt(0)
	v_mfma_f32_16x16x32_bf16 v[46:49], v[90:93], v[208:211], v[46:49]
	v_mfma_f32_16x16x32_bf16 v[26:29], v[212:215], v[208:211], v[26:29]
	s_waitcnt vmcnt(6)
	ds_write_b128 v0, v[248:251] offset:30720
	s_movk_i32 s10, 0x400
	s_mov_b32 s11, 0
	v_lshl_add_u64 v[200:201], v[128:129], 0, s[10:11]
	global_load_dwordx2 v[138:139], v[200:201], off
	global_load_dwordx2 v[140:141], v[200:201], off offset:32
	v_lshl_add_u64 v[200:201], v[132:133], 0, s[10:11]
	global_load_dwordx2 v[142:143], v[200:201], off
	global_load_dwordx2 v[144:145], v[200:201], off offset:32
	v_lshl_add_u64 v[200:201], v[152:153], 0, s[10:11]
	global_load_dwordx2 v[146:147], v[200:201], off
	global_load_dwordx2 v[148:149], v[200:201], off offset:32
	v_lshl_add_u64 v[200:201], v[154:155], 0, s[10:11]
	global_load_dwordx2 v[194:195], v[200:201], off
	global_load_dwordx2 v[196:197], v[200:201], off offset:32
	v_mfma_f32_16x16x32_bf16 v[14:17], v[216:219], v[208:211], v[14:17]
	v_mfma_f32_16x16x32_bf16 v[10:13], v[220:223], v[208:211], v[10:13]
	ds_read_b128 v[208:211], v205 offset:5184
	s_waitcnt lgkmcnt(0)
	v_mfma_f32_16x16x32_bf16 v[34:37], v[90:93], v[208:211], v[34:37]
	v_mfma_f32_16x16x32_bf16 v[22:25], v[212:215], v[208:211], v[22:25]
	v_mfma_f32_16x16x32_bf16 v[18:21], v[216:219], v[208:211], v[18:21]
	v_mfma_f32_16x16x32_bf16 v[62:65], v[220:223], v[208:211], v[62:65]
	v_mfma_f32_16x16x32_bf16 v[58:61], v[90:93], v[224:227], v[58:61]
	s_waitcnt lgkmcnt(0)
	v_mfma_f32_16x16x32_bf16 v[54:57], v[212:215], v[224:227], v[54:57]
	s_barrier
	v_mfma_f32_16x16x32_bf16 v[50:53], v[216:219], v[224:227], v[50:53]
	v_mfma_f32_16x16x32_bf16 v[2:5], v[220:223], v[224:227], v[2:5]
	global_load_dwordx4 v[228:231], v190, s[80:81] offset:896
	global_load_dwordx4 v[232:235], v191, s[80:81] offset:896
	global_load_dwordx4 v[236:239], v190, s[86:87] offset:896
	global_load_dwordx4 v[240:243], v191, s[86:87] offset:896
	global_load_dwordx4 v[244:247], v188, s[96:97] offset:896
	global_load_dwordx4 v[248:251], v188, s[98:99] offset:896
	ds_read_b128 v[90:93], v119 offset:20480
	ds_read_b128 v[208:211], v205 offset:40960
	ds_read_b128 v[212:215], v119 offset:23040
	ds_read_b128 v[216:219], v119 offset:25600
	ds_read_b128 v[220:223], v119 offset:28160
	s_waitcnt lgkmcnt(3)
	v_mfma_f32_16x16x32_bf16 v[6:9], v[90:93], v[208:211], v[6:9]
	s_waitcnt lgkmcnt(2)
	v_mfma_f32_16x16x32_bf16 v[30:33], v[212:215], v[208:211], v[30:33]
	s_waitcnt vmcnt(19)
	ds_write_b128 v206, v[66:69] offset:0
	s_waitcnt lgkmcnt(2)
	v_mfma_f32_16x16x32_bf16 v[38:41], v[216:219], v[208:211], v[38:41]
	s_waitcnt lgkmcnt(1)
	v_mfma_f32_16x16x32_bf16 v[42:45], v[220:223], v[208:211], v[42:45]
	ds_read_b128 v[208:211], v205 offset:43520
	s_waitcnt lgkmcnt(0)
	v_mfma_f32_16x16x32_bf16 v[46:49], v[90:93], v[208:211], v[46:49]
	v_mfma_f32_16x16x32_bf16 v[26:29], v[212:215], v[208:211], v[26:29]
	s_waitcnt vmcnt(18)
	ds_write_b128 v206, v[70:73] offset:10240
	v_mfma_f32_16x16x32_bf16 v[14:17], v[216:219], v[208:211], v[14:17]
	v_mfma_f32_16x16x32_bf16 v[10:13], v[220:223], v[208:211], v[10:13]
	ds_read_b128 v[208:211], v205 offset:46080
	s_waitcnt lgkmcnt(0)
	v_mfma_f32_16x16x32_bf16 v[34:37], v[90:93], v[208:211], v[34:37]
	v_mfma_f32_16x16x32_bf16 v[22:25], v[212:215], v[208:211], v[22:25]
	s_waitcnt vmcnt(17)
	ds_write_b128 v206, v[74:77] offset:20480
	v_mfma_f32_16x16x32_bf16 v[18:21], v[216:219], v[208:211], v[18:21]
	v_mfma_f32_16x16x32_bf16 v[62:65], v[220:223], v[208:211], v[62:65]
	ds_read_b128 v[208:211], v205 offset:48640
	s_waitcnt lgkmcnt(0)
	v_mfma_f32_16x16x32_bf16 v[58:61], v[90:93], v[208:211], v[58:61]
	ds_read_b128 v[90:93], v119 offset:20544
	v_mfma_f32_16x16x32_bf16 v[54:57], v[212:215], v[208:211], v[54:57]
	s_waitcnt vmcnt(16)
	ds_write_b128 v206, v[78:81] offset:30720
	ds_read_b128 v[212:215], v119 offset:23104
	v_mfma_f32_16x16x32_bf16 v[50:53], v[216:219], v[208:211], v[50:53]
	ds_read_b128 v[216:219], v119 offset:25664
	v_mfma_f32_16x16x32_bf16 v[2:5], v[220:223], v[208:211], v[2:5]
	ds_read_b128 v[220:223], v119 offset:28224
	ds_read_b128 v[208:211], v205 offset:41024
	ds_read_b128 v[224:227], v205 offset:48704
	s_waitcnt lgkmcnt(1)
	v_mfma_f32_16x16x32_bf16 v[6:9], v[90:93], v[208:211], v[6:9]
	v_mfma_f32_16x16x32_bf16 v[30:33], v[212:215], v[208:211], v[30:33]
	s_waitcnt vmcnt(15)
	ds_write_b128 v0, v[82:85] offset:0
	v_mfma_f32_16x16x32_bf16 v[38:41], v[216:219], v[208:211], v[38:41]
	v_mfma_f32_16x16x32_bf16 v[42:45], v[220:223], v[208:211], v[42:45]
	ds_read_b128 v[208:211], v205 offset:43584
	s_waitcnt lgkmcnt(0)
	v_mfma_f32_16x16x32_bf16 v[46:49], v[90:93], v[208:211], v[46:49]
	v_mfma_f32_16x16x32_bf16 v[26:29], v[212:215], v[208:211], v[26:29]
	s_waitcnt vmcnt(14)
	ds_write_b128 v0, v[86:89] offset:10240
	s_add_u32 s80, s80, 0x600
	s_addc_u32 s81, s81, 0
	s_add_u32 s86, s80, 0x1f0000
	s_addc_u32 s87, s81, 0
	s_add_u32 s96, s96, 0x100000
	s_addc_u32 s97, s97, 0
	s_add_u32 s98, s96, 0x10000
	s_addc_u32 s99, s97, 0
	global_load_dwordx4 v[66:69], v190, s[80:81] offset:0
	global_load_dwordx4 v[70:73], v191, s[80:81] offset:0
	global_load_dwordx4 v[74:77], v190, s[86:87] offset:0
	global_load_dwordx4 v[78:81], v191, s[86:87] offset:0
	global_load_dwordx4 v[82:85], v188, s[96:97] offset:0
	global_load_dwordx4 v[86:89], v188, s[98:99] offset:0
	v_mfma_f32_16x16x32_bf16 v[14:17], v[216:219], v[208:211], v[14:17]
	v_mfma_f32_16x16x32_bf16 v[10:13], v[220:223], v[208:211], v[10:13]
	ds_read_b128 v[208:211], v205 offset:46144
	s_waitcnt lgkmcnt(0)
	v_mfma_f32_16x16x32_bf16 v[34:37], v[90:93], v[208:211], v[34:37]
	v_mfma_f32_16x16x32_bf16 v[22:25], v[212:215], v[208:211], v[22:25]
	v_mfma_f32_16x16x32_bf16 v[18:21], v[216:219], v[208:211], v[18:21]
	v_mfma_f32_16x16x32_bf16 v[62:65], v[220:223], v[208:211], v[62:65]
	v_mfma_f32_16x16x32_bf16 v[58:61], v[90:93], v[224:227], v[58:61]
	s_waitcnt lgkmcnt(0)
	v_mfma_f32_16x16x32_bf16 v[54:57], v[212:215], v[224:227], v[54:57]
	s_barrier
	v_mfma_f32_16x16x32_bf16 v[50:53], v[216:219], v[224:227], v[50:53]
	v_mfma_f32_16x16x32_bf16 v[2:5], v[220:223], v[224:227], v[2:5]
	ds_read_b128 v[90:93], v119 offset:0
	ds_read_b128 v[208:211], v205 offset:0
	ds_read_b128 v[212:215], v119 offset:2560
	ds_read_b128 v[216:219], v119 offset:5120
	ds_read_b128 v[220:223], v119 offset:7680
	s_waitcnt lgkmcnt(3)
	v_mfma_f32_16x16x32_bf16 v[6:9], v[90:93], v[208:211], v[6:9]
	s_waitcnt lgkmcnt(2)
	v_mfma_f32_16x16x32_bf16 v[30:33], v[212:215], v[208:211], v[30:33]
	s_waitcnt vmcnt(11)
	ds_write_b128 v207, v[228:231] offset:0
	s_waitcnt lgkmcnt(2)
	v_mfma_f32_16x16x32_bf16 v[38:41], v[216:219], v[208:211], v[38:41]
	s_waitcnt lgkmcnt(1)
	v_mfma_f32_16x16x32_bf16 v[42:45], v[220:223], v[208:211], v[42:45]
	ds_read_b128 v[208:211], v205 offset:2560
	s_waitcnt lgkmcnt(0)
	v_mfma_f32_16x16x32_bf16 v[46:49], v[90:93], v[208:211], v[46:49]
	v_mfma_f32_16x16x32_bf16 v[26:29], v[212:215], v[208:211], v[26:29]
	s_waitcnt vmcnt(10)
	ds_write_b128 v207, v[232:235] offset:10240
	v_mfma_f32_16x16x32_bf16 v[14:17], v[216:219], v[208:211], v[14:17]
	v_mfma_f32_16x16x32_bf16 v[10:13], v[220:223], v[208:211], v[10:13]
	ds_read_b128 v[208:211], v205 offset:5120
	s_waitcnt lgkmcnt(0)
	v_mfma_f32_16x16x32_bf16 v[34:37], v[90:93], v[208:211], v[34:37]
	v_mfma_f32_16x16x32_bf16 v[22:25], v[212:215], v[208:211], v[22:25]
	s_waitcnt vmcnt(9)
	ds_write_b128 v207, v[236:239] offset:20480
	v_mfma_f32_16x16x32_bf16 v[18:21], v[216:219], v[208:211], v[18:21]
	v_mfma_f32_16x16x32_bf16 v[62:65], v[220:223], v[208:211], v[62:65]
	ds_read_b128 v[208:211], v205 offset:7680
	s_waitcnt lgkmcnt(0)
	v_mfma_f32_16x16x32_bf16 v[58:61], v[90:93], v[208:211], v[58:61]
	ds_read_b128 v[90:93], v119 offset:64
	v_mfma_f32_16x16x32_bf16 v[54:57], v[212:215], v[208:211], v[54:57]
	s_waitcnt vmcnt(8)
	ds_write_b128 v207, v[240:243] offset:30720
	ds_read_b128 v[212:215], v119 offset:2624
	v_mfma_f32_16x16x32_bf16 v[50:53], v[216:219], v[208:211], v[50:53]
	ds_read_b128 v[216:219], v119 offset:5184
	v_mfma_f32_16x16x32_bf16 v[2:5], v[220:223], v[208:211], v[2:5]
	ds_read_b128 v[220:223], v119 offset:7744
	ds_read_b128 v[208:211], v205 offset:64
	ds_read_b128 v[224:227], v205 offset:7744
	s_waitcnt lgkmcnt(1)
	v_mfma_f32_16x16x32_bf16 v[6:9], v[90:93], v[208:211], v[6:9]
	v_mfma_f32_16x16x32_bf16 v[30:33], v[212:215], v[208:211], v[30:33]
	s_waitcnt vmcnt(7)
	ds_write_b128 v0, v[244:247] offset:20480
	v_mfma_f32_16x16x32_bf16 v[38:41], v[216:219], v[208:211], v[38:41]
	v_mfma_f32_16x16x32_bf16 v[42:45], v[220:223], v[208:211], v[42:45]
	ds_read_b128 v[208:211], v205 offset:2624
	s_waitcnt lgkmcnt(0)
	v_mfma_f32_16x16x32_bf16 v[46:49], v[90:93], v[208:211], v[46:49]
	v_mfma_f32_16x16x32_bf16 v[26:29], v[212:215], v[208:211], v[26:29]
	s_waitcnt vmcnt(6)
	ds_write_b128 v0, v[248:251] offset:30720
	global_load_dwordx4 v[228:231], v190, s[80:81] offset:128
	global_load_dwordx4 v[232:235], v191, s[80:81] offset:128
	global_load_dwordx4 v[236:239], v190, s[86:87] offset:128
	global_load_dwordx4 v[240:243], v191, s[86:87] offset:128
	global_load_dwordx4 v[244:247], v188, s[96:97] offset:128
	global_load_dwordx4 v[248:251], v188, s[98:99] offset:128
	v_mfma_f32_16x16x32_bf16 v[14:17], v[216:219], v[208:211], v[14:17]
	v_mfma_f32_16x16x32_bf16 v[10:13], v[220:223], v[208:211], v[10:13]
	ds_read_b128 v[208:211], v205 offset:5184
	s_waitcnt lgkmcnt(0)
	v_mfma_f32_16x16x32_bf16 v[34:37], v[90:93], v[208:211], v[34:37]
	v_mfma_f32_16x16x32_bf16 v[22:25], v[212:215], v[208:211], v[22:25]
	v_mfma_f32_16x16x32_bf16 v[18:21], v[216:219], v[208:211], v[18:21]
	v_mfma_f32_16x16x32_bf16 v[62:65], v[220:223], v[208:211], v[62:65]
	v_mfma_f32_16x16x32_bf16 v[58:61], v[90:93], v[224:227], v[58:61]
	s_waitcnt lgkmcnt(0)
	v_mfma_f32_16x16x32_bf16 v[54:57], v[212:215], v[224:227], v[54:57]
	s_barrier
	v_mfma_f32_16x16x32_bf16 v[50:53], v[216:219], v[224:227], v[50:53]
	v_mfma_f32_16x16x32_bf16 v[2:5], v[220:223], v[224:227], v[2:5]
	ds_read_b128 v[90:93], v119 offset:20480
	ds_read_b128 v[208:211], v205 offset:40960
	ds_read_b128 v[212:215], v119 offset:23040
	ds_read_b128 v[216:219], v119 offset:25600
	ds_read_b128 v[220:223], v119 offset:28160
	s_waitcnt lgkmcnt(3)
	v_mfma_f32_16x16x32_bf16 v[6:9], v[90:93], v[208:211], v[6:9]
	s_waitcnt lgkmcnt(2)
	v_mfma_f32_16x16x32_bf16 v[30:33], v[212:215], v[208:211], v[30:33]
	s_waitcnt lgkmcnt(1)
	v_mfma_f32_16x16x32_bf16 v[38:41], v[216:219], v[208:211], v[38:41]
	s_waitcnt lgkmcnt(0)
	v_mfma_f32_16x16x32_bf16 v[42:45], v[220:223], v[208:211], v[42:45]
	ds_read_b128 v[208:211], v205 offset:43520
	s_waitcnt lgkmcnt(0)
	v_mfma_f32_16x16x32_bf16 v[46:49], v[90:93], v[208:211], v[46:49]
	v_mfma_f32_16x16x32_bf16 v[26:29], v[212:215], v[208:211], v[26:29]
	v_mfma_f32_16x16x32_bf16 v[14:17], v[216:219], v[208:211], v[14:17]
	v_mfma_f32_16x16x32_bf16 v[10:13], v[220:223], v[208:211], v[10:13]
	ds_read_b128 v[208:211], v205 offset:46080
	s_waitcnt lgkmcnt(0)
	v_mfma_f32_16x16x32_bf16 v[34:37], v[90:93], v[208:211], v[34:37]
	v_mfma_f32_16x16x32_bf16 v[22:25], v[212:215], v[208:211], v[22:25]
	v_mfma_f32_16x16x32_bf16 v[18:21], v[216:219], v[208:211], v[18:21]
	v_mfma_f32_16x16x32_bf16 v[62:65], v[220:223], v[208:211], v[62:65]
	ds_read_b128 v[208:211], v205 offset:48640
	s_waitcnt lgkmcnt(0)
	v_mfma_f32_16x16x32_bf16 v[58:61], v[90:93], v[208:211], v[58:61]
	ds_read_b128 v[90:93], v119 offset:20544
	v_mfma_f32_16x16x32_bf16 v[54:57], v[212:215], v[208:211], v[54:57]
	ds_read_b128 v[212:215], v119 offset:23104
	v_mfma_f32_16x16x32_bf16 v[50:53], v[216:219], v[208:211], v[50:53]
	ds_read_b128 v[216:219], v119 offset:25664
	v_mfma_f32_16x16x32_bf16 v[2:5], v[220:223], v[208:211], v[2:5]
	ds_read_b128 v[220:223], v119 offset:28224
	ds_read_b128 v[208:211], v205 offset:41024
	ds_read_b128 v[224:227], v205 offset:48704
	s_waitcnt lgkmcnt(1)
	v_mfma_f32_16x16x32_bf16 v[6:9], v[90:93], v[208:211], v[6:9]
	s_waitcnt vmcnt(18)
	v_mfma_f32_16x16x32_bf16 v[30:33], v[212:215], v[208:211], v[30:33]
	v_mfma_f32_16x16x32_bf16 v[38:41], v[216:219], v[208:211], v[38:41]
	v_mfma_f32_16x16x32_bf16 v[42:45], v[220:223], v[208:211], v[42:45]
	v_cvt_f32_ubyte0_e32 v200, v138
	v_cvt_f32_ubyte1_e32 v201, v138
	v_cvt_f32_ubyte2_e32 v202, v138
	v_cvt_f32_ubyte3_e32 v255, v138
	v_mul_f32_e32 v200, s34, v200
	v_mul_f32_e32 v201, s34, v201
	v_mul_f32_e32 v202, s34, v202
	v_mul_f32_e32 v255, s34, v255
	v_fma_f32 v184, v6, v200, v184
	v_fma_f32 v185, v7, v201, v185
	v_fma_f32 v186, v8, v202, v186
	v_fma_f32 v187, v9, v255, v187
	ds_read_b128 v[208:211], v205 offset:43584
	s_waitcnt lgkmcnt(0)
	v_mfma_f32_16x16x32_bf16 v[46:49], v[90:93], v[208:211], v[46:49]
	v_cvt_f32_ubyte0_e32 v200, v139
	v_cvt_f32_ubyte1_e32 v201, v139
	v_cvt_f32_ubyte2_e32 v202, v139
	v_cvt_f32_ubyte3_e32 v255, v139
	v_mul_f32_e32 v200, s34, v200
	v_mul_f32_e32 v201, s34, v201
	v_mul_f32_e32 v202, s34, v202
	v_mul_f32_e32 v255, s34, v255
	v_fma_f32 v180, v30, v200, v180
	v_fma_f32 v181, v31, v201, v181
	v_fma_f32 v182, v32, v202, v182
	v_fma_f32 v183, v33, v255, v183
	v_mfma_f32_16x16x32_bf16 v[26:29], v[212:215], v[208:211], v[26:29]
	v_cvt_f32_ubyte0_e32 v200, v140
	v_cvt_f32_ubyte1_e32 v201, v140
	v_cvt_f32_ubyte2_e32 v202, v140
	v_cvt_f32_ubyte3_e32 v255, v140
	v_mul_f32_e32 v200, s34, v200
	v_mul_f32_e32 v201, s34, v201
	v_mul_f32_e32 v202, s34, v202
	v_mul_f32_e32 v255, s34, v255
	v_fma_f32 v176, v38, v200, v176
	v_fma_f32 v177, v39, v201, v177
	v_fma_f32 v178, v40, v202, v178
	v_fma_f32 v179, v41, v255, v179
	v_mfma_f32_16x16x32_bf16 v[14:17], v[216:219], v[208:211], v[14:17]
	v_cvt_f32_ubyte0_e32 v200, v141
	v_cvt_f32_ubyte1_e32 v201, v141
	v_cvt_f32_ubyte2_e32 v202, v141
	v_cvt_f32_ubyte3_e32 v255, v141
	v_mul_f32_e32 v200, s34, v200
	v_mul_f32_e32 v201, s34, v201
	v_mul_f32_e32 v202, s34, v202
	v_mul_f32_e32 v255, s34, v255
	v_fma_f32 v172, v42, v200, v172
	v_fma_f32 v173, v43, v201, v173
	v_fma_f32 v174, v44, v202, v174
	v_fma_f32 v175, v45, v255, v175
	v_mfma_f32_16x16x32_bf16 v[10:13], v[220:223], v[208:211], v[10:13]
	v_cvt_f32_ubyte0_e32 v200, v142
	v_cvt_f32_ubyte1_e32 v201, v142
	v_cvt_f32_ubyte2_e32 v202, v142
	v_cvt_f32_ubyte3_e32 v255, v142
	v_mul_f32_e32 v200, s34, v200
	v_mul_f32_e32 v201, s34, v201
	v_mul_f32_e32 v202, s34, v202
	v_mul_f32_e32 v255, s34, v255
	v_fma_f32 v168, v46, v200, v168
	v_fma_f32 v169, v47, v201, v169
	v_fma_f32 v170, v48, v202, v170
	v_fma_f32 v171, v49, v255, v171
	ds_read_b128 v[208:211], v205 offset:46144
	s_waitcnt lgkmcnt(0)
	v_mfma_f32_16x16x32_bf16 v[34:37], v[90:93], v[208:211], v[34:37]
	v_cvt_f32_ubyte0_e32 v200, v143
	v_cvt_f32_ubyte1_e32 v201, v143
	v_cvt_f32_ubyte2_e32 v202, v143
	v_cvt_f32_ubyte3_e32 v255, v143
	v_mul_f32_e32 v200, s34, v200
	v_mul_f32_e32 v201, s34, v201
	v_mul_f32_e32 v202, s34, v202
	v_mul_f32_e32 v255, s34, v255
	v_fma_f32 v164, v26, v200, v164
	v_fma_f32 v165, v27, v201, v165
	v_fma_f32 v166, v28, v202, v166
	v_fma_f32 v167, v29, v255, v167
	v_mfma_f32_16x16x32_bf16 v[22:25], v[212:215], v[208:211], v[22:25]
	v_cvt_f32_ubyte0_e32 v200, v144
	v_cvt_f32_ubyte1_e32 v201, v144
	v_cvt_f32_ubyte2_e32 v202, v144
	v_cvt_f32_ubyte3_e32 v255, v144
	v_mul_f32_e32 v200, s34, v200
	v_mul_f32_e32 v201, s34, v201
	v_mul_f32_e32 v202, s34, v202
	v_mul_f32_e32 v255, s34, v255
	v_fma_f32 v160, v14, v200, v160
	v_fma_f32 v161, v15, v201, v161
	v_fma_f32 v162, v16, v202, v162
	v_fma_f32 v163, v17, v255, v163
	v_mfma_f32_16x16x32_bf16 v[18:21], v[216:219], v[208:211], v[18:21]
	v_cvt_f32_ubyte0_e32 v200, v145
	v_cvt_f32_ubyte1_e32 v201, v145
	v_cvt_f32_ubyte2_e32 v202, v145
	v_cvt_f32_ubyte3_e32 v255, v145
	v_mul_f32_e32 v200, s34, v200
	v_mul_f32_e32 v201, s34, v201
	v_mul_f32_e32 v202, s34, v202
	v_mul_f32_e32 v255, s34, v255
	v_fma_f32 v156, v10, v200, v156
	v_fma_f32 v157, v11, v201, v157
	v_fma_f32 v158, v12, v202, v158
	v_fma_f32 v159, v13, v255, v159
	v_mfma_f32_16x16x32_bf16 v[62:65], v[220:223], v[208:211], v[62:65]
	v_cvt_f32_ubyte0_e32 v200, v146
	v_cvt_f32_ubyte1_e32 v201, v146
	v_cvt_f32_ubyte2_e32 v202, v146
	v_cvt_f32_ubyte3_e32 v255, v146
	v_mul_f32_e32 v200, s34, v200
	v_mul_f32_e32 v201, s34, v201
	v_mul_f32_e32 v202, s34, v202
	v_mul_f32_e32 v255, s34, v255
	v_fma_f32 v136, v34, v200, v136
	v_fma_f32 v137, v35, v201, v137
	v_fma_f32 v150, v36, v202, v150
	v_fma_f32 v151, v37, v255, v151
	v_mfma_f32_16x16x32_bf16 v[58:61], v[90:93], v[224:227], v[58:61]
	v_cvt_f32_ubyte0_e32 v200, v147
	v_cvt_f32_ubyte1_e32 v201, v147
	v_cvt_f32_ubyte2_e32 v202, v147
	v_cvt_f32_ubyte3_e32 v255, v147
	v_mul_f32_e32 v200, s34, v200
	v_mul_f32_e32 v201, s34, v201
	v_mul_f32_e32 v202, s34, v202
	v_mul_f32_e32 v255, s34, v255
	v_fma_f32 v130, v22, v200, v130
	v_fma_f32 v131, v23, v201, v131
	v_fma_f32 v134, v24, v202, v134
	v_fma_f32 v135, v25, v255, v135
	v_mfma_f32_16x16x32_bf16 v[54:57], v[212:215], v[224:227], v[54:57]
	v_cvt_f32_ubyte0_e32 v200, v148
	v_cvt_f32_ubyte1_e32 v201, v148
	v_cvt_f32_ubyte2_e32 v202, v148
	v_cvt_f32_ubyte3_e32 v255, v148
	v_mul_f32_e32 v200, s34, v200
	v_mul_f32_e32 v201, s34, v201
	v_mul_f32_e32 v202, s34, v202
	v_mul_f32_e32 v255, s34, v255
	v_fma_f32 v124, v18, v200, v124
	v_fma_f32 v125, v19, v201, v125
	v_fma_f32 v126, v20, v202, v126
	v_fma_f32 v127, v21, v255, v127
	v_mfma_f32_16x16x32_bf16 v[50:53], v[216:219], v[224:227], v[50:53]
	v_cvt_f32_ubyte0_e32 v200, v149
	v_cvt_f32_ubyte1_e32 v201, v149
	v_cvt_f32_ubyte2_e32 v202, v149
	v_cvt_f32_ubyte3_e32 v255, v149
	v_mul_f32_e32 v200, s34, v200
	v_mul_f32_e32 v201, s34, v201
	v_mul_f32_e32 v202, s34, v202
	v_mul_f32_e32 v255, s34, v255
	v_fma_f32 v120, v62, v200, v120
	v_fma_f32 v121, v63, v201, v121
	v_fma_f32 v122, v64, v202, v122
	v_fma_f32 v123, v65, v255, v123
	v_mfma_f32_16x16x32_bf16 v[2:5], v[220:223], v[224:227], v[2:5]
	v_cvt_f32_ubyte0_e32 v200, v194
	v_cvt_f32_ubyte1_e32 v201, v194
	v_cvt_f32_ubyte2_e32 v202, v194
	v_cvt_f32_ubyte3_e32 v255, v194
	v_mul_f32_e32 v200, s34, v200
	v_mul_f32_e32 v201, s34, v201
	v_mul_f32_e32 v202, s34, v202
	v_mul_f32_e32 v255, s34, v255
	v_fma_f32 v114, v58, v200, v114
	v_fma_f32 v115, v59, v201, v115
	v_fma_f32 v116, v60, v202, v116
	v_fma_f32 v117, v61, v255, v117
	s_nop 7
	s_nop 3
	v_cvt_f32_ubyte0_e32 v200, v195
	v_cvt_f32_ubyte1_e32 v201, v195
	v_cvt_f32_ubyte2_e32 v202, v195
	v_cvt_f32_ubyte3_e32 v255, v195
	v_mul_f32_e32 v200, s34, v200
	v_mul_f32_e32 v201, s34, v201
	v_mul_f32_e32 v202, s34, v202
	v_mul_f32_e32 v255, s34, v255
	v_fma_f32 v106, v54, v200, v106
	v_fma_f32 v107, v55, v201, v107
	v_fma_f32 v108, v56, v202, v108
	v_fma_f32 v109, v57, v255, v109
	v_cvt_f32_ubyte0_e32 v200, v196
	v_cvt_f32_ubyte1_e32 v201, v196
	v_cvt_f32_ubyte2_e32 v202, v196
	v_cvt_f32_ubyte3_e32 v255, v196
	v_mul_f32_e32 v200, s34, v200
	v_mul_f32_e32 v201, s34, v201
	v_mul_f32_e32 v202, s34, v202
	v_mul_f32_e32 v255, s34, v255
	v_fma_f32 v100, v50, v200, v100
	v_fma_f32 v101, v51, v201, v101
	v_fma_f32 v102, v52, v202, v102
	v_fma_f32 v103, v53, v255, v103
	v_cvt_f32_ubyte0_e32 v200, v197
	v_cvt_f32_ubyte1_e32 v201, v197
	v_cvt_f32_ubyte2_e32 v202, v197
	v_cvt_f32_ubyte3_e32 v255, v197
	v_mul_f32_e32 v200, s34, v200
	v_mul_f32_e32 v201, s34, v201
	v_mul_f32_e32 v202, s34, v202
	v_mul_f32_e32 v255, s34, v255
	v_fma_f32 v96, v2, v200, v96
	v_fma_f32 v97, v3, v201, v97
	v_fma_f32 v98, v4, v202, v98
	v_fma_f32 v99, v5, v255, v99
	s_waitcnt vmcnt(11)
	ds_write_b128 v206, v[66:69] offset:0
	s_waitcnt vmcnt(10)
	ds_write_b128 v206, v[70:73] offset:10240
	s_waitcnt vmcnt(9)
	ds_write_b128 v206, v[74:77] offset:20480
	s_waitcnt vmcnt(8)
	ds_write_b128 v206, v[78:81] offset:30720
	s_waitcnt vmcnt(7)
	ds_write_b128 v0, v[82:85] offset:0
	s_waitcnt vmcnt(6)
	ds_write_b128 v0, v[86:89] offset:10240
	s_waitcnt lgkmcnt(0)
	s_barrier
	global_load_dwordx4 v[66:69], v190, s[80:81] offset:256
	global_load_dwordx4 v[70:73], v191, s[80:81] offset:256
	global_load_dwordx4 v[74:77], v190, s[86:87] offset:256
	global_load_dwordx4 v[78:81], v191, s[86:87] offset:256
	global_load_dwordx4 v[82:85], v188, s[96:97] offset:256
	global_load_dwordx4 v[86:89], v188, s[98:99] offset:256
	ds_read_b128 v[90:93], v119 offset:0
	ds_read_b128 v[208:211], v205 offset:0
	ds_read_b128 v[212:215], v119 offset:2560
	ds_read_b128 v[216:219], v119 offset:5120
	ds_read_b128 v[220:223], v119 offset:7680
	s_waitcnt lgkmcnt(3)
	v_mfma_f32_16x16x32_bf16 v[6:9], v[90:93], v[208:211], 0
	s_waitcnt lgkmcnt(2)
	v_mfma_f32_16x16x32_bf16 v[30:33], v[212:215], v[208:211], 0
	s_waitcnt vmcnt(11)
	ds_write_b128 v207, v[228:231] offset:0
	s_waitcnt lgkmcnt(2)
	v_mfma_f32_16x16x32_bf16 v[38:41], v[216:219], v[208:211], 0
	s_waitcnt lgkmcnt(1)
	v_mfma_f32_16x16x32_bf16 v[42:45], v[220:223], v[208:211], 0
	ds_read_b128 v[208:211], v205 offset:2560
	s_waitcnt lgkmcnt(0)
	v_mfma_f32_16x16x32_bf16 v[46:49], v[90:93], v[208:211], 0
	v_mfma_f32_16x16x32_bf16 v[26:29], v[212:215], v[208:211], 0
	s_waitcnt vmcnt(10)
	ds_write_b128 v207, v[232:235] offset:10240
	v_mfma_f32_16x16x32_bf16 v[14:17], v[216:219], v[208:211], 0
	v_mfma_f32_16x16x32_bf16 v[10:13], v[220:223], v[208:211], 0
	ds_read_b128 v[208:211], v205 offset:5120
	s_waitcnt lgkmcnt(0)
	v_mfma_f32_16x16x32_bf16 v[34:37], v[90:93], v[208:211], 0
	v_mfma_f32_16x16x32_bf16 v[22:25], v[212:215], v[208:211], 0
	s_waitcnt vmcnt(9)
	ds_write_b128 v207, v[236:239] offset:20480
	v_mfma_f32_16x16x32_bf16 v[18:21], v[216:219], v[208:211], 0
	v_mfma_f32_16x16x32_bf16 v[62:65], v[220:223], v[208:211], 0
	ds_read_b128 v[208:211], v205 offset:7680
	s_waitcnt lgkmcnt(0)
	v_mfma_f32_16x16x32_bf16 v[58:61], v[90:93], v[208:211], 0
	ds_read_b128 v[90:93], v119 offset:64
	v_mfma_f32_16x16x32_bf16 v[54:57], v[212:215], v[208:211], 0
	s_waitcnt vmcnt(8)
	ds_write_b128 v207, v[240:243] offset:30720
	ds_read_b128 v[212:215], v119 offset:2624
	v_mfma_f32_16x16x32_bf16 v[50:53], v[216:219], v[208:211], 0
	ds_read_b128 v[216:219], v119 offset:5184
	v_mfma_f32_16x16x32_bf16 v[2:5], v[220:223], v[208:211], 0
	ds_read_b128 v[220:223], v119 offset:7744
	ds_read_b128 v[208:211], v205 offset:64
	ds_read_b128 v[224:227], v205 offset:7744
	s_waitcnt lgkmcnt(1)
	v_mfma_f32_16x16x32_bf16 v[6:9], v[90:93], v[208:211], v[6:9]
	v_mfma_f32_16x16x32_bf16 v[30:33], v[212:215], v[208:211], v[30:33]
	s_waitcnt vmcnt(7)
	ds_write_b128 v0, v[244:247] offset:20480
	v_mfma_f32_16x16x32_bf16 v[38:41], v[216:219], v[208:211], v[38:41]
	v_mfma_f32_16x16x32_bf16 v[42:45], v[220:223], v[208:211], v[42:45]
	ds_read_b128 v[208:211], v205 offset:2624
	s_waitcnt lgkmcnt(0)
	v_mfma_f32_16x16x32_bf16 v[46:49], v[90:93], v[208:211], v[46:49]
	v_mfma_f32_16x16x32_bf16 v[26:29], v[212:215], v[208:211], v[26:29]
	s_waitcnt vmcnt(6)
	ds_write_b128 v0, v[248:251] offset:30720
	v_mfma_f32_16x16x32_bf16 v[14:17], v[216:219], v[208:211], v[14:17]
	v_mfma_f32_16x16x32_bf16 v[10:13], v[220:223], v[208:211], v[10:13]
	ds_read_b128 v[208:211], v205 offset:5184
	s_waitcnt lgkmcnt(0)
	v_mfma_f32_16x16x32_bf16 v[34:37], v[90:93], v[208:211], v[34:37]
	v_mfma_f32_16x16x32_bf16 v[22:25], v[212:215], v[208:211], v[22:25]
	v_mfma_f32_16x16x32_bf16 v[18:21], v[216:219], v[208:211], v[18:21]
	v_mfma_f32_16x16x32_bf16 v[62:65], v[220:223], v[208:211], v[62:65]
	v_mfma_f32_16x16x32_bf16 v[58:61], v[90:93], v[224:227], v[58:61]
	s_waitcnt lgkmcnt(0)
	v_mfma_f32_16x16x32_bf16 v[54:57], v[212:215], v[224:227], v[54:57]
	s_barrier
	v_mfma_f32_16x16x32_bf16 v[50:53], v[216:219], v[224:227], v[50:53]
	v_mfma_f32_16x16x32_bf16 v[2:5], v[220:223], v[224:227], v[2:5]
	global_load_dwordx4 v[228:231], v190, s[80:81] offset:384
	global_load_dwordx4 v[232:235], v191, s[80:81] offset:384
	global_load_dwordx4 v[236:239], v190, s[86:87] offset:384
	global_load_dwordx4 v[240:243], v191, s[86:87] offset:384
	global_load_dwordx4 v[244:247], v188, s[96:97] offset:384
	global_load_dwordx4 v[248:251], v188, s[98:99] offset:384
	ds_read_b128 v[90:93], v119 offset:20480
	ds_read_b128 v[208:211], v205 offset:40960
	ds_read_b128 v[212:215], v119 offset:23040
	ds_read_b128 v[216:219], v119 offset:25600
	ds_read_b128 v[220:223], v119 offset:28160
	s_waitcnt lgkmcnt(3)
	v_mfma_f32_16x16x32_bf16 v[6:9], v[90:93], v[208:211], v[6:9]
	s_waitcnt lgkmcnt(2)
	v_mfma_f32_16x16x32_bf16 v[30:33], v[212:215], v[208:211], v[30:33]
	s_waitcnt vmcnt(11)
	ds_write_b128 v206, v[66:69] offset:0
	s_waitcnt lgkmcnt(2)
	v_mfma_f32_16x16x32_bf16 v[38:41], v[216:219], v[208:211], v[38:41]
	s_waitcnt lgkmcnt(1)
	v_mfma_f32_16x16x32_bf16 v[42:45], v[220:223], v[208:211], v[42:45]
	ds_read_b128 v[208:211], v205 offset:43520
	s_waitcnt lgkmcnt(0)
	v_mfma_f32_16x16x32_bf16 v[46:49], v[90:93], v[208:211], v[46:49]
	v_mfma_f32_16x16x32_bf16 v[26:29], v[212:215], v[208:211], v[26:29]
	s_waitcnt vmcnt(10)
	ds_write_b128 v206, v[70:73] offset:10240
	v_mfma_f32_16x16x32_bf16 v[14:17], v[216:219], v[208:211], v[14:17]
	v_mfma_f32_16x16x32_bf16 v[10:13], v[220:223], v[208:211], v[10:13]
	ds_read_b128 v[208:211], v205 offset:46080
	s_waitcnt lgkmcnt(0)
	v_mfma_f32_16x16x32_bf16 v[34:37], v[90:93], v[208:211], v[34:37]
	v_mfma_f32_16x16x32_bf16 v[22:25], v[212:215], v[208:211], v[22:25]
	s_waitcnt vmcnt(9)
	ds_write_b128 v206, v[74:77] offset:20480
	v_mfma_f32_16x16x32_bf16 v[18:21], v[216:219], v[208:211], v[18:21]
	v_mfma_f32_16x16x32_bf16 v[62:65], v[220:223], v[208:211], v[62:65]
	ds_read_b128 v[208:211], v205 offset:48640
	s_waitcnt lgkmcnt(0)
	v_mfma_f32_16x16x32_bf16 v[58:61], v[90:93], v[208:211], v[58:61]
	ds_read_b128 v[90:93], v119 offset:20544
	v_mfma_f32_16x16x32_bf16 v[54:57], v[212:215], v[208:211], v[54:57]
	s_waitcnt vmcnt(8)
	ds_write_b128 v206, v[78:81] offset:30720
	ds_read_b128 v[212:215], v119 offset:23104
	v_mfma_f32_16x16x32_bf16 v[50:53], v[216:219], v[208:211], v[50:53]
	ds_read_b128 v[216:219], v119 offset:25664
	v_mfma_f32_16x16x32_bf16 v[2:5], v[220:223], v[208:211], v[2:5]
	ds_read_b128 v[220:223], v119 offset:28224
	ds_read_b128 v[208:211], v205 offset:41024
	ds_read_b128 v[224:227], v205 offset:48704
	s_waitcnt lgkmcnt(1)
	v_mfma_f32_16x16x32_bf16 v[6:9], v[90:93], v[208:211], v[6:9]
	v_mfma_f32_16x16x32_bf16 v[30:33], v[212:215], v[208:211], v[30:33]
	s_waitcnt vmcnt(7)
	ds_write_b128 v0, v[82:85] offset:0
	v_mfma_f32_16x16x32_bf16 v[38:41], v[216:219], v[208:211], v[38:41]
	v_mfma_f32_16x16x32_bf16 v[42:45], v[220:223], v[208:211], v[42:45]
	ds_read_b128 v[208:211], v205 offset:43584
	s_waitcnt lgkmcnt(0)
	v_mfma_f32_16x16x32_bf16 v[46:49], v[90:93], v[208:211], v[46:49]
	v_mfma_f32_16x16x32_bf16 v[26:29], v[212:215], v[208:211], v[26:29]
	s_waitcnt vmcnt(6)
	ds_write_b128 v0, v[86:89] offset:10240
	v_mfma_f32_16x16x32_bf16 v[14:17], v[216:219], v[208:211], v[14:17]
	v_mfma_f32_16x16x32_bf16 v[10:13], v[220:223], v[208:211], v[10:13]
	ds_read_b128 v[208:211], v205 offset:46144
	s_waitcnt lgkmcnt(0)
	v_mfma_f32_16x16x32_bf16 v[34:37], v[90:93], v[208:211], v[34:37]
	v_mfma_f32_16x16x32_bf16 v[22:25], v[212:215], v[208:211], v[22:25]
	v_mfma_f32_16x16x32_bf16 v[18:21], v[216:219], v[208:211], v[18:21]
	v_mfma_f32_16x16x32_bf16 v[62:65], v[220:223], v[208:211], v[62:65]
	v_mfma_f32_16x16x32_bf16 v[58:61], v[90:93], v[224:227], v[58:61]
	s_waitcnt lgkmcnt(0)
	v_mfma_f32_16x16x32_bf16 v[54:57], v[212:215], v[224:227], v[54:57]
	s_barrier
	v_mfma_f32_16x16x32_bf16 v[50:53], v[216:219], v[224:227], v[50:53]
	v_mfma_f32_16x16x32_bf16 v[2:5], v[220:223], v[224:227], v[2:5]
	global_load_dwordx4 v[66:69], v190, s[80:81] offset:512
	global_load_dwordx4 v[70:73], v191, s[80:81] offset:512
	global_load_dwordx4 v[74:77], v190, s[86:87] offset:512
	global_load_dwordx4 v[78:81], v191, s[86:87] offset:512
	global_load_dwordx4 v[82:85], v188, s[96:97] offset:512
	global_load_dwordx4 v[86:89], v188, s[98:99] offset:512
	ds_read_b128 v[90:93], v119 offset:0
	ds_read_b128 v[208:211], v205 offset:0
	ds_read_b128 v[212:215], v119 offset:2560
	ds_read_b128 v[216:219], v119 offset:5120
	ds_read_b128 v[220:223], v119 offset:7680
	s_waitcnt lgkmcnt(3)
	v_mfma_f32_16x16x32_bf16 v[6:9], v[90:93], v[208:211], v[6:9]
	s_waitcnt lgkmcnt(2)
	v_mfma_f32_16x16x32_bf16 v[30:33], v[212:215], v[208:211], v[30:33]
	s_waitcnt vmcnt(11)
	ds_write_b128 v207, v[228:231] offset:0
	s_waitcnt lgkmcnt(2)
	v_mfma_f32_16x16x32_bf16 v[38:41], v[216:219], v[208:211], v[38:41]
	s_waitcnt lgkmcnt(1)
	v_mfma_f32_16x16x32_bf16 v[42:45], v[220:223], v[208:211], v[42:45]
	ds_read_b128 v[208:211], v205 offset:2560
	s_waitcnt lgkmcnt(0)
	v_mfma_f32_16x16x32_bf16 v[46:49], v[90:93], v[208:211], v[46:49]
	v_mfma_f32_16x16x32_bf16 v[26:29], v[212:215], v[208:211], v[26:29]
	s_waitcnt vmcnt(10)
	ds_write_b128 v207, v[232:235] offset:10240
	v_mfma_f32_16x16x32_bf16 v[14:17], v[216:219], v[208:211], v[14:17]
	v_mfma_f32_16x16x32_bf16 v[10:13], v[220:223], v[208:211], v[10:13]
	ds_read_b128 v[208:211], v205 offset:5120
	s_waitcnt lgkmcnt(0)
	v_mfma_f32_16x16x32_bf16 v[34:37], v[90:93], v[208:211], v[34:37]
	v_mfma_f32_16x16x32_bf16 v[22:25], v[212:215], v[208:211], v[22:25]
	s_waitcnt vmcnt(9)
	ds_write_b128 v207, v[236:239] offset:20480
	v_mfma_f32_16x16x32_bf16 v[18:21], v[216:219], v[208:211], v[18:21]
	v_mfma_f32_16x16x32_bf16 v[62:65], v[220:223], v[208:211], v[62:65]
	ds_read_b128 v[208:211], v205 offset:7680
	s_waitcnt lgkmcnt(0)
	v_mfma_f32_16x16x32_bf16 v[58:61], v[90:93], v[208:211], v[58:61]
	ds_read_b128 v[90:93], v119 offset:64
	v_mfma_f32_16x16x32_bf16 v[54:57], v[212:215], v[208:211], v[54:57]
	s_waitcnt vmcnt(8)
	ds_write_b128 v207, v[240:243] offset:30720
	ds_read_b128 v[212:215], v119 offset:2624
	v_mfma_f32_16x16x32_bf16 v[50:53], v[216:219], v[208:211], v[50:53]
	ds_read_b128 v[216:219], v119 offset:5184
	v_mfma_f32_16x16x32_bf16 v[2:5], v[220:223], v[208:211], v[2:5]
	ds_read_b128 v[220:223], v119 offset:7744
	ds_read_b128 v[208:211], v205 offset:64
	ds_read_b128 v[224:227], v205 offset:7744
	s_waitcnt lgkmcnt(1)
	v_mfma_f32_16x16x32_bf16 v[6:9], v[90:93], v[208:211], v[6:9]
	v_mfma_f32_16x16x32_bf16 v[30:33], v[212:215], v[208:211], v[30:33]
	s_waitcnt vmcnt(7)
	ds_write_b128 v0, v[244:247] offset:20480
	v_mfma_f32_16x16x32_bf16 v[38:41], v[216:219], v[208:211], v[38:41]
	v_mfma_f32_16x16x32_bf16 v[42:45], v[220:223], v[208:211], v[42:45]
	ds_read_b128 v[208:211], v205 offset:2624
	s_waitcnt lgkmcnt(0)
	v_mfma_f32_16x16x32_bf16 v[46:49], v[90:93], v[208:211], v[46:49]
	v_mfma_f32_16x16x32_bf16 v[26:29], v[212:215], v[208:211], v[26:29]
	s_waitcnt vmcnt(6)
	ds_write_b128 v0, v[248:251] offset:30720
	v_mfma_f32_16x16x32_bf16 v[14:17], v[216:219], v[208:211], v[14:17]
	v_mfma_f32_16x16x32_bf16 v[10:13], v[220:223], v[208:211], v[10:13]
	ds_read_b128 v[208:211], v205 offset:5184
	s_waitcnt lgkmcnt(0)
	v_mfma_f32_16x16x32_bf16 v[34:37], v[90:93], v[208:211], v[34:37]
	v_mfma_f32_16x16x32_bf16 v[22:25], v[212:215], v[208:211], v[22:25]
	v_mfma_f32_16x16x32_bf16 v[18:21], v[216:219], v[208:211], v[18:21]
	v_mfma_f32_16x16x32_bf16 v[62:65], v[220:223], v[208:211], v[62:65]
	v_mfma_f32_16x16x32_bf16 v[58:61], v[90:93], v[224:227], v[58:61]
	s_waitcnt lgkmcnt(0)
	v_mfma_f32_16x16x32_bf16 v[54:57], v[212:215], v[224:227], v[54:57]
	s_barrier
	v_mfma_f32_16x16x32_bf16 v[50:53], v[216:219], v[224:227], v[50:53]
	v_mfma_f32_16x16x32_bf16 v[2:5], v[220:223], v[224:227], v[2:5]
	global_load_dwordx4 v[228:231], v190, s[80:81] offset:640
	global_load_dwordx4 v[232:235], v191, s[80:81] offset:640
	global_load_dwordx4 v[236:239], v190, s[86:87] offset:640
	global_load_dwordx4 v[240:243], v191, s[86:87] offset:640
	global_load_dwordx4 v[244:247], v188, s[96:97] offset:640
	global_load_dwordx4 v[248:251], v188, s[98:99] offset:640
	ds_read_b128 v[90:93], v119 offset:20480
	ds_read_b128 v[208:211], v205 offset:40960
	ds_read_b128 v[212:215], v119 offset:23040
	ds_read_b128 v[216:219], v119 offset:25600
	ds_read_b128 v[220:223], v119 offset:28160
	s_waitcnt lgkmcnt(3)
	v_mfma_f32_16x16x32_bf16 v[6:9], v[90:93], v[208:211], v[6:9]
	s_waitcnt lgkmcnt(2)
	v_mfma_f32_16x16x32_bf16 v[30:33], v[212:215], v[208:211], v[30:33]
	s_waitcnt vmcnt(11)
	ds_write_b128 v206, v[66:69] offset:0
	s_waitcnt lgkmcnt(2)
	v_mfma_f32_16x16x32_bf16 v[38:41], v[216:219], v[208:211], v[38:41]
	s_waitcnt lgkmcnt(1)
	v_mfma_f32_16x16x32_bf16 v[42:45], v[220:223], v[208:211], v[42:45]
	ds_read_b128 v[208:211], v205 offset:43520
	s_waitcnt lgkmcnt(0)
	v_mfma_f32_16x16x32_bf16 v[46:49], v[90:93], v[208:211], v[46:49]
	v_mfma_f32_16x16x32_bf16 v[26:29], v[212:215], v[208:211], v[26:29]
	s_waitcnt vmcnt(10)
	ds_write_b128 v206, v[70:73] offset:10240
	v_mfma_f32_16x16x32_bf16 v[14:17], v[216:219], v[208:211], v[14:17]
	v_mfma_f32_16x16x32_bf16 v[10:13], v[220:223], v[208:211], v[10:13]
	ds_read_b128 v[208:211], v205 offset:46080
	s_waitcnt lgkmcnt(0)
	v_mfma_f32_16x16x32_bf16 v[34:37], v[90:93], v[208:211], v[34:37]
	v_mfma_f32_16x16x32_bf16 v[22:25], v[212:215], v[208:211], v[22:25]
	s_waitcnt vmcnt(9)
	ds_write_b128 v206, v[74:77] offset:20480
	v_mfma_f32_16x16x32_bf16 v[18:21], v[216:219], v[208:211], v[18:21]
	v_mfma_f32_16x16x32_bf16 v[62:65], v[220:223], v[208:211], v[62:65]
	ds_read_b128 v[208:211], v205 offset:48640
	s_waitcnt lgkmcnt(0)
	v_mfma_f32_16x16x32_bf16 v[58:61], v[90:93], v[208:211], v[58:61]
	ds_read_b128 v[90:93], v119 offset:20544
	v_mfma_f32_16x16x32_bf16 v[54:57], v[212:215], v[208:211], v[54:57]
	s_waitcnt vmcnt(8)
	ds_write_b128 v206, v[78:81] offset:30720
	ds_read_b128 v[212:215], v119 offset:23104
	v_mfma_f32_16x16x32_bf16 v[50:53], v[216:219], v[208:211], v[50:53]
	ds_read_b128 v[216:219], v119 offset:25664
	v_mfma_f32_16x16x32_bf16 v[2:5], v[220:223], v[208:211], v[2:5]
	ds_read_b128 v[220:223], v119 offset:28224
	ds_read_b128 v[208:211], v205 offset:41024
	ds_read_b128 v[224:227], v205 offset:48704
	s_waitcnt lgkmcnt(1)
	v_mfma_f32_16x16x32_bf16 v[6:9], v[90:93], v[208:211], v[6:9]
	v_mfma_f32_16x16x32_bf16 v[30:33], v[212:215], v[208:211], v[30:33]
	s_waitcnt vmcnt(7)
	ds_write_b128 v0, v[82:85] offset:0
	v_mfma_f32_16x16x32_bf16 v[38:41], v[216:219], v[208:211], v[38:41]
	v_mfma_f32_16x16x32_bf16 v[42:45], v[220:223], v[208:211], v[42:45]
	ds_read_b128 v[208:211], v205 offset:43584
	s_waitcnt lgkmcnt(0)
	v_mfma_f32_16x16x32_bf16 v[46:49], v[90:93], v[208:211], v[46:49]
	v_mfma_f32_16x16x32_bf16 v[26:29], v[212:215], v[208:211], v[26:29]
	s_waitcnt vmcnt(6)
	ds_write_b128 v0, v[86:89] offset:10240
	v_mfma_f32_16x16x32_bf16 v[14:17], v[216:219], v[208:211], v[14:17]
	v_mfma_f32_16x16x32_bf16 v[10:13], v[220:223], v[208:211], v[10:13]
	ds_read_b128 v[208:211], v205 offset:46144
	s_waitcnt lgkmcnt(0)
	v_mfma_f32_16x16x32_bf16 v[34:37], v[90:93], v[208:211], v[34:37]
	v_mfma_f32_16x16x32_bf16 v[22:25], v[212:215], v[208:211], v[22:25]
	v_mfma_f32_16x16x32_bf16 v[18:21], v[216:219], v[208:211], v[18:21]
	v_mfma_f32_16x16x32_bf16 v[62:65], v[220:223], v[208:211], v[62:65]
	v_mfma_f32_16x16x32_bf16 v[58:61], v[90:93], v[224:227], v[58:61]
	s_waitcnt lgkmcnt(0)
	v_mfma_f32_16x16x32_bf16 v[54:57], v[212:215], v[224:227], v[54:57]
	s_barrier
	v_mfma_f32_16x16x32_bf16 v[50:53], v[216:219], v[224:227], v[50:53]
	v_mfma_f32_16x16x32_bf16 v[2:5], v[220:223], v[224:227], v[2:5]
	global_load_dwordx4 v[66:69], v190, s[80:81] offset:768
	global_load_dwordx4 v[70:73], v191, s[80:81] offset:768
	global_load_dwordx4 v[74:77], v190, s[86:87] offset:768
	global_load_dwordx4 v[78:81], v191, s[86:87] offset:768
	global_load_dwordx4 v[82:85], v188, s[96:97] offset:768
	global_load_dwordx4 v[86:89], v188, s[98:99] offset:768
	ds_read_b128 v[90:93], v119 offset:0
	ds_read_b128 v[208:211], v205 offset:0
	ds_read_b128 v[212:215], v119 offset:2560
	ds_read_b128 v[216:219], v119 offset:5120
	ds_read_b128 v[220:223], v119 offset:7680
	s_waitcnt lgkmcnt(3)
	v_mfma_f32_16x16x32_bf16 v[6:9], v[90:93], v[208:211], v[6:9]
	s_waitcnt lgkmcnt(2)
	v_mfma_f32_16x16x32_bf16 v[30:33], v[212:215], v[208:211], v[30:33]
	s_waitcnt vmcnt(11)
	ds_write_b128 v207, v[228:231] offset:0
	s_waitcnt lgkmcnt(2)
	v_mfma_f32_16x16x32_bf16 v[38:41], v[216:219], v[208:211], v[38:41]
	s_waitcnt lgkmcnt(1)
	v_mfma_f32_16x16x32_bf16 v[42:45], v[220:223], v[208:211], v[42:45]
	ds_read_b128 v[208:211], v205 offset:2560
	s_waitcnt lgkmcnt(0)
	v_mfma_f32_16x16x32_bf16 v[46:49], v[90:93], v[208:211], v[46:49]
	v_mfma_f32_16x16x32_bf16 v[26:29], v[212:215], v[208:211], v[26:29]
	s_waitcnt vmcnt(10)
	ds_write_b128 v207, v[232:235] offset:10240
	v_mfma_f32_16x16x32_bf16 v[14:17], v[216:219], v[208:211], v[14:17]
	v_mfma_f32_16x16x32_bf16 v[10:13], v[220:223], v[208:211], v[10:13]
	ds_read_b128 v[208:211], v205 offset:5120
	s_waitcnt lgkmcnt(0)
	v_mfma_f32_16x16x32_bf16 v[34:37], v[90:93], v[208:211], v[34:37]
	v_mfma_f32_16x16x32_bf16 v[22:25], v[212:215], v[208:211], v[22:25]
	s_waitcnt vmcnt(9)
	ds_write_b128 v207, v[236:239] offset:20480
	v_mfma_f32_16x16x32_bf16 v[18:21], v[216:219], v[208:211], v[18:21]
	v_mfma_f32_16x16x32_bf16 v[62:65], v[220:223], v[208:211], v[62:65]
	ds_read_b128 v[208:211], v205 offset:7680
	s_waitcnt lgkmcnt(0)
	v_mfma_f32_16x16x32_bf16 v[58:61], v[90:93], v[208:211], v[58:61]
	ds_read_b128 v[90:93], v119 offset:64
	v_mfma_f32_16x16x32_bf16 v[54:57], v[212:215], v[208:211], v[54:57]
	s_waitcnt vmcnt(8)
	ds_write_b128 v207, v[240:243] offset:30720
	ds_read_b128 v[212:215], v119 offset:2624
	v_mfma_f32_16x16x32_bf16 v[50:53], v[216:219], v[208:211], v[50:53]
	ds_read_b128 v[216:219], v119 offset:5184
	v_mfma_f32_16x16x32_bf16 v[2:5], v[220:223], v[208:211], v[2:5]
	ds_read_b128 v[220:223], v119 offset:7744
	ds_read_b128 v[208:211], v205 offset:64
	ds_read_b128 v[224:227], v205 offset:7744
	s_waitcnt lgkmcnt(1)
	v_mfma_f32_16x16x32_bf16 v[6:9], v[90:93], v[208:211], v[6:9]
	v_mfma_f32_16x16x32_bf16 v[30:33], v[212:215], v[208:211], v[30:33]
	s_waitcnt vmcnt(7)
	ds_write_b128 v0, v[244:247] offset:20480
	v_mfma_f32_16x16x32_bf16 v[38:41], v[216:219], v[208:211], v[38:41]
	v_mfma_f32_16x16x32_bf16 v[42:45], v[220:223], v[208:211], v[42:45]
	ds_read_b128 v[208:211], v205 offset:2624
	s_waitcnt lgkmcnt(0)
	v_mfma_f32_16x16x32_bf16 v[46:49], v[90:93], v[208:211], v[46:49]
	v_mfma_f32_16x16x32_bf16 v[26:29], v[212:215], v[208:211], v[26:29]
	s_waitcnt vmcnt(6)
	ds_write_b128 v0, v[248:251] offset:30720
	s_movk_i32 s10, 0x800
	s_mov_b32 s11, 0
	v_lshl_add_u64 v[200:201], v[128:129], 0, s[10:11]
	global_load_dwordx2 v[138:139], v[200:201], off
	global_load_dwordx2 v[140:141], v[200:201], off offset:32
	v_lshl_add_u64 v[200:201], v[132:133], 0, s[10:11]
	global_load_dwordx2 v[142:143], v[200:201], off
	global_load_dwordx2 v[144:145], v[200:201], off offset:32
	v_lshl_add_u64 v[200:201], v[152:153], 0, s[10:11]
	global_load_dwordx2 v[146:147], v[200:201], off
	global_load_dwordx2 v[148:149], v[200:201], off offset:32
	v_lshl_add_u64 v[200:201], v[154:155], 0, s[10:11]
	global_load_dwordx2 v[194:195], v[200:201], off
	global_load_dwordx2 v[196:197], v[200:201], off offset:32
	v_mfma_f32_16x16x32_bf16 v[14:17], v[216:219], v[208:211], v[14:17]
	v_mfma_f32_16x16x32_bf16 v[10:13], v[220:223], v[208:211], v[10:13]
	ds_read_b128 v[208:211], v205 offset:5184
	s_waitcnt lgkmcnt(0)
	v_mfma_f32_16x16x32_bf16 v[34:37], v[90:93], v[208:211], v[34:37]
	v_mfma_f32_16x16x32_bf16 v[22:25], v[212:215], v[208:211], v[22:25]
	v_mfma_f32_16x16x32_bf16 v[18:21], v[216:219], v[208:211], v[18:21]
	v_mfma_f32_16x16x32_bf16 v[62:65], v[220:223], v[208:211], v[62:65]
	v_mfma_f32_16x16x32_bf16 v[58:61], v[90:93], v[224:227], v[58:61]
	s_waitcnt lgkmcnt(0)
	v_mfma_f32_16x16x32_bf16 v[54:57], v[212:215], v[224:227], v[54:57]
	s_barrier
	v_mfma_f32_16x16x32_bf16 v[50:53], v[216:219], v[224:227], v[50:53]
	v_mfma_f32_16x16x32_bf16 v[2:5], v[220:223], v[224:227], v[2:5]
	global_load_dwordx4 v[228:231], v190, s[80:81] offset:896
	global_load_dwordx4 v[232:235], v191, s[80:81] offset:896
	global_load_dwordx4 v[236:239], v190, s[86:87] offset:896
	global_load_dwordx4 v[240:243], v191, s[86:87] offset:896
	global_load_dwordx4 v[244:247], v188, s[96:97] offset:896
	global_load_dwordx4 v[248:251], v188, s[98:99] offset:896
	ds_read_b128 v[90:93], v119 offset:20480
	ds_read_b128 v[208:211], v205 offset:40960
	ds_read_b128 v[212:215], v119 offset:23040
	ds_read_b128 v[216:219], v119 offset:25600
	ds_read_b128 v[220:223], v119 offset:28160
	s_waitcnt lgkmcnt(3)
	v_mfma_f32_16x16x32_bf16 v[6:9], v[90:93], v[208:211], v[6:9]
	s_waitcnt lgkmcnt(2)
	v_mfma_f32_16x16x32_bf16 v[30:33], v[212:215], v[208:211], v[30:33]
	s_waitcnt vmcnt(19)
	ds_write_b128 v206, v[66:69] offset:0
	s_waitcnt lgkmcnt(2)
	v_mfma_f32_16x16x32_bf16 v[38:41], v[216:219], v[208:211], v[38:41]
	s_waitcnt lgkmcnt(1)
	v_mfma_f32_16x16x32_bf16 v[42:45], v[220:223], v[208:211], v[42:45]
	ds_read_b128 v[208:211], v205 offset:43520
	s_waitcnt lgkmcnt(0)
	v_mfma_f32_16x16x32_bf16 v[46:49], v[90:93], v[208:211], v[46:49]
	v_mfma_f32_16x16x32_bf16 v[26:29], v[212:215], v[208:211], v[26:29]
	s_waitcnt vmcnt(18)
	ds_write_b128 v206, v[70:73] offset:10240
	v_mfma_f32_16x16x32_bf16 v[14:17], v[216:219], v[208:211], v[14:17]
	v_mfma_f32_16x16x32_bf16 v[10:13], v[220:223], v[208:211], v[10:13]
	ds_read_b128 v[208:211], v205 offset:46080
	s_waitcnt lgkmcnt(0)
	v_mfma_f32_16x16x32_bf16 v[34:37], v[90:93], v[208:211], v[34:37]
	v_mfma_f32_16x16x32_bf16 v[22:25], v[212:215], v[208:211], v[22:25]
	s_waitcnt vmcnt(17)
	ds_write_b128 v206, v[74:77] offset:20480
	v_mfma_f32_16x16x32_bf16 v[18:21], v[216:219], v[208:211], v[18:21]
	v_mfma_f32_16x16x32_bf16 v[62:65], v[220:223], v[208:211], v[62:65]
	ds_read_b128 v[208:211], v205 offset:48640
	s_waitcnt lgkmcnt(0)
	v_mfma_f32_16x16x32_bf16 v[58:61], v[90:93], v[208:211], v[58:61]
	ds_read_b128 v[90:93], v119 offset:20544
	v_mfma_f32_16x16x32_bf16 v[54:57], v[212:215], v[208:211], v[54:57]
	s_waitcnt vmcnt(16)
	ds_write_b128 v206, v[78:81] offset:30720
	ds_read_b128 v[212:215], v119 offset:23104
	v_mfma_f32_16x16x32_bf16 v[50:53], v[216:219], v[208:211], v[50:53]
	ds_read_b128 v[216:219], v119 offset:25664
	v_mfma_f32_16x16x32_bf16 v[2:5], v[220:223], v[208:211], v[2:5]
	ds_read_b128 v[220:223], v119 offset:28224
	ds_read_b128 v[208:211], v205 offset:41024
	ds_read_b128 v[224:227], v205 offset:48704
	s_waitcnt lgkmcnt(1)
	v_mfma_f32_16x16x32_bf16 v[6:9], v[90:93], v[208:211], v[6:9]
	v_mfma_f32_16x16x32_bf16 v[30:33], v[212:215], v[208:211], v[30:33]
	s_waitcnt vmcnt(15)
	ds_write_b128 v0, v[82:85] offset:0
	v_mfma_f32_16x16x32_bf16 v[38:41], v[216:219], v[208:211], v[38:41]
	v_mfma_f32_16x16x32_bf16 v[42:45], v[220:223], v[208:211], v[42:45]
	ds_read_b128 v[208:211], v205 offset:43584
	s_waitcnt lgkmcnt(0)
	v_mfma_f32_16x16x32_bf16 v[46:49], v[90:93], v[208:211], v[46:49]
	v_mfma_f32_16x16x32_bf16 v[26:29], v[212:215], v[208:211], v[26:29]
	s_waitcnt vmcnt(14)
	ds_write_b128 v0, v[86:89] offset:10240
	s_add_u32 s80, s80, 0xc00
	s_addc_u32 s81, s81, 0
	s_add_u32 s86, s80, 0x1f0000
	s_addc_u32 s87, s81, 0
	s_add_u32 s96, s96, 0x100000
	s_addc_u32 s97, s97, 0
	s_add_u32 s98, s96, 0x10000
	s_addc_u32 s99, s97, 0
	global_load_dwordx4 v[66:69], v190, s[80:81] offset:0
	global_load_dwordx4 v[70:73], v191, s[80:81] offset:0
	global_load_dwordx4 v[74:77], v190, s[86:87] offset:0
	global_load_dwordx4 v[78:81], v191, s[86:87] offset:0
	global_load_dwordx4 v[82:85], v188, s[96:97] offset:0
	global_load_dwordx4 v[86:89], v188, s[98:99] offset:0
	v_mfma_f32_16x16x32_bf16 v[14:17], v[216:219], v[208:211], v[14:17]
	v_mfma_f32_16x16x32_bf16 v[10:13], v[220:223], v[208:211], v[10:13]
	ds_read_b128 v[208:211], v205 offset:46144
	s_waitcnt lgkmcnt(0)
	v_mfma_f32_16x16x32_bf16 v[34:37], v[90:93], v[208:211], v[34:37]
	v_mfma_f32_16x16x32_bf16 v[22:25], v[212:215], v[208:211], v[22:25]
	v_mfma_f32_16x16x32_bf16 v[18:21], v[216:219], v[208:211], v[18:21]
	v_mfma_f32_16x16x32_bf16 v[62:65], v[220:223], v[208:211], v[62:65]
	v_mfma_f32_16x16x32_bf16 v[58:61], v[90:93], v[224:227], v[58:61]
	s_waitcnt lgkmcnt(0)
	v_mfma_f32_16x16x32_bf16 v[54:57], v[212:215], v[224:227], v[54:57]
	s_barrier
	v_mfma_f32_16x16x32_bf16 v[50:53], v[216:219], v[224:227], v[50:53]
	v_mfma_f32_16x16x32_bf16 v[2:5], v[220:223], v[224:227], v[2:5]
	ds_read_b128 v[90:93], v119 offset:0
	ds_read_b128 v[208:211], v205 offset:0
	ds_read_b128 v[212:215], v119 offset:2560
	ds_read_b128 v[216:219], v119 offset:5120
	ds_read_b128 v[220:223], v119 offset:7680
	s_waitcnt lgkmcnt(3)
	v_mfma_f32_16x16x32_bf16 v[6:9], v[90:93], v[208:211], v[6:9]
	s_waitcnt lgkmcnt(2)
	v_mfma_f32_16x16x32_bf16 v[30:33], v[212:215], v[208:211], v[30:33]
	s_waitcnt vmcnt(11)
	ds_write_b128 v207, v[228:231] offset:0
	s_waitcnt lgkmcnt(2)
	v_mfma_f32_16x16x32_bf16 v[38:41], v[216:219], v[208:211], v[38:41]
	s_waitcnt lgkmcnt(1)
	v_mfma_f32_16x16x32_bf16 v[42:45], v[220:223], v[208:211], v[42:45]
	ds_read_b128 v[208:211], v205 offset:2560
	s_waitcnt lgkmcnt(0)
	v_mfma_f32_16x16x32_bf16 v[46:49], v[90:93], v[208:211], v[46:49]
	v_mfma_f32_16x16x32_bf16 v[26:29], v[212:215], v[208:211], v[26:29]
	s_waitcnt vmcnt(10)
	ds_write_b128 v207, v[232:235] offset:10240
	v_mfma_f32_16x16x32_bf16 v[14:17], v[216:219], v[208:211], v[14:17]
	v_mfma_f32_16x16x32_bf16 v[10:13], v[220:223], v[208:211], v[10:13]
	ds_read_b128 v[208:211], v205 offset:5120
	s_waitcnt lgkmcnt(0)
	v_mfma_f32_16x16x32_bf16 v[34:37], v[90:93], v[208:211], v[34:37]
	v_mfma_f32_16x16x32_bf16 v[22:25], v[212:215], v[208:211], v[22:25]
	s_waitcnt vmcnt(9)
	ds_write_b128 v207, v[236:239] offset:20480
	v_mfma_f32_16x16x32_bf16 v[18:21], v[216:219], v[208:211], v[18:21]
	v_mfma_f32_16x16x32_bf16 v[62:65], v[220:223], v[208:211], v[62:65]
	ds_read_b128 v[208:211], v205 offset:7680
	s_waitcnt lgkmcnt(0)
	v_mfma_f32_16x16x32_bf16 v[58:61], v[90:93], v[208:211], v[58:61]
	ds_read_b128 v[90:93], v119 offset:64
	v_mfma_f32_16x16x32_bf16 v[54:57], v[212:215], v[208:211], v[54:57]
	s_waitcnt vmcnt(8)
	ds_write_b128 v207, v[240:243] offset:30720
	ds_read_b128 v[212:215], v119 offset:2624
	v_mfma_f32_16x16x32_bf16 v[50:53], v[216:219], v[208:211], v[50:53]
	ds_read_b128 v[216:219], v119 offset:5184
	v_mfma_f32_16x16x32_bf16 v[2:5], v[220:223], v[208:211], v[2:5]
	ds_read_b128 v[220:223], v119 offset:7744
	ds_read_b128 v[208:211], v205 offset:64
	ds_read_b128 v[224:227], v205 offset:7744
	s_waitcnt lgkmcnt(1)
	v_mfma_f32_16x16x32_bf16 v[6:9], v[90:93], v[208:211], v[6:9]
	v_mfma_f32_16x16x32_bf16 v[30:33], v[212:215], v[208:211], v[30:33]
	s_waitcnt vmcnt(7)
	ds_write_b128 v0, v[244:247] offset:20480
	v_mfma_f32_16x16x32_bf16 v[38:41], v[216:219], v[208:211], v[38:41]
	v_mfma_f32_16x16x32_bf16 v[42:45], v[220:223], v[208:211], v[42:45]
	ds_read_b128 v[208:211], v205 offset:2624
	s_waitcnt lgkmcnt(0)
	v_mfma_f32_16x16x32_bf16 v[46:49], v[90:93], v[208:211], v[46:49]
	v_mfma_f32_16x16x32_bf16 v[26:29], v[212:215], v[208:211], v[26:29]
	s_waitcnt vmcnt(6)
	ds_write_b128 v0, v[248:251] offset:30720
	global_load_dwordx4 v[228:231], v190, s[80:81] offset:128
	global_load_dwordx4 v[232:235], v191, s[80:81] offset:128
	global_load_dwordx4 v[236:239], v190, s[86:87] offset:128
	global_load_dwordx4 v[240:243], v191, s[86:87] offset:128
	global_load_dwordx4 v[244:247], v188, s[96:97] offset:128
	global_load_dwordx4 v[248:251], v188, s[98:99] offset:128
	v_mfma_f32_16x16x32_bf16 v[14:17], v[216:219], v[208:211], v[14:17]
	v_mfma_f32_16x16x32_bf16 v[10:13], v[220:223], v[208:211], v[10:13]
	ds_read_b128 v[208:211], v205 offset:5184
	s_waitcnt lgkmcnt(0)
	v_mfma_f32_16x16x32_bf16 v[34:37], v[90:93], v[208:211], v[34:37]
	v_mfma_f32_16x16x32_bf16 v[22:25], v[212:215], v[208:211], v[22:25]
	v_mfma_f32_16x16x32_bf16 v[18:21], v[216:219], v[208:211], v[18:21]
	v_mfma_f32_16x16x32_bf16 v[62:65], v[220:223], v[208:211], v[62:65]
	v_mfma_f32_16x16x32_bf16 v[58:61], v[90:93], v[224:227], v[58:61]
	s_waitcnt lgkmcnt(0)
	v_mfma_f32_16x16x32_bf16 v[54:57], v[212:215], v[224:227], v[54:57]
	s_barrier
	v_mfma_f32_16x16x32_bf16 v[50:53], v[216:219], v[224:227], v[50:53]
	v_mfma_f32_16x16x32_bf16 v[2:5], v[220:223], v[224:227], v[2:5]
	ds_read_b128 v[90:93], v119 offset:20480
	ds_read_b128 v[208:211], v205 offset:40960
	ds_read_b128 v[212:215], v119 offset:23040
	ds_read_b128 v[216:219], v119 offset:25600
	ds_read_b128 v[220:223], v119 offset:28160
	s_waitcnt lgkmcnt(3)
	v_mfma_f32_16x16x32_bf16 v[6:9], v[90:93], v[208:211], v[6:9]
	s_waitcnt lgkmcnt(2)
	v_mfma_f32_16x16x32_bf16 v[30:33], v[212:215], v[208:211], v[30:33]
	s_waitcnt lgkmcnt(1)
	v_mfma_f32_16x16x32_bf16 v[38:41], v[216:219], v[208:211], v[38:41]
	s_waitcnt lgkmcnt(0)
	v_mfma_f32_16x16x32_bf16 v[42:45], v[220:223], v[208:211], v[42:45]
	ds_read_b128 v[208:211], v205 offset:43520
	s_waitcnt lgkmcnt(0)
	v_mfma_f32_16x16x32_bf16 v[46:49], v[90:93], v[208:211], v[46:49]
	v_mfma_f32_16x16x32_bf16 v[26:29], v[212:215], v[208:211], v[26:29]
	v_mfma_f32_16x16x32_bf16 v[14:17], v[216:219], v[208:211], v[14:17]
	v_mfma_f32_16x16x32_bf16 v[10:13], v[220:223], v[208:211], v[10:13]
	ds_read_b128 v[208:211], v205 offset:46080
	s_waitcnt lgkmcnt(0)
	v_mfma_f32_16x16x32_bf16 v[34:37], v[90:93], v[208:211], v[34:37]
	v_mfma_f32_16x16x32_bf16 v[22:25], v[212:215], v[208:211], v[22:25]
	v_mfma_f32_16x16x32_bf16 v[18:21], v[216:219], v[208:211], v[18:21]
	v_mfma_f32_16x16x32_bf16 v[62:65], v[220:223], v[208:211], v[62:65]
	ds_read_b128 v[208:211], v205 offset:48640
	s_waitcnt lgkmcnt(0)
	v_mfma_f32_16x16x32_bf16 v[58:61], v[90:93], v[208:211], v[58:61]
	ds_read_b128 v[90:93], v119 offset:20544
	v_mfma_f32_16x16x32_bf16 v[54:57], v[212:215], v[208:211], v[54:57]
	ds_read_b128 v[212:215], v119 offset:23104
	v_mfma_f32_16x16x32_bf16 v[50:53], v[216:219], v[208:211], v[50:53]
	ds_read_b128 v[216:219], v119 offset:25664
	v_mfma_f32_16x16x32_bf16 v[2:5], v[220:223], v[208:211], v[2:5]
	ds_read_b128 v[220:223], v119 offset:28224
	ds_read_b128 v[208:211], v205 offset:41024
	ds_read_b128 v[224:227], v205 offset:48704
	s_waitcnt lgkmcnt(1)
	v_mfma_f32_16x16x32_bf16 v[6:9], v[90:93], v[208:211], v[6:9]
	s_waitcnt vmcnt(18)
	v_mfma_f32_16x16x32_bf16 v[30:33], v[212:215], v[208:211], v[30:33]
	v_mfma_f32_16x16x32_bf16 v[38:41], v[216:219], v[208:211], v[38:41]
	v_mfma_f32_16x16x32_bf16 v[42:45], v[220:223], v[208:211], v[42:45]
	v_cvt_f32_ubyte0_e32 v200, v138
	v_cvt_f32_ubyte1_e32 v201, v138
	v_cvt_f32_ubyte2_e32 v202, v138
	v_cvt_f32_ubyte3_e32 v255, v138
	v_mul_f32_e32 v200, s34, v200
	v_mul_f32_e32 v201, s34, v201
	v_mul_f32_e32 v202, s34, v202
	v_mul_f32_e32 v255, s34, v255
	v_fma_f32 v184, v6, v200, v184
	v_fma_f32 v185, v7, v201, v185
	v_fma_f32 v186, v8, v202, v186
	v_fma_f32 v187, v9, v255, v187
	ds_read_b128 v[208:211], v205 offset:43584
	s_waitcnt lgkmcnt(0)
	v_mfma_f32_16x16x32_bf16 v[46:49], v[90:93], v[208:211], v[46:49]
	v_cvt_f32_ubyte0_e32 v200, v139
	v_cvt_f32_ubyte1_e32 v201, v139
	v_cvt_f32_ubyte2_e32 v202, v139
	v_cvt_f32_ubyte3_e32 v255, v139
	v_mul_f32_e32 v200, s34, v200
	v_mul_f32_e32 v201, s34, v201
	v_mul_f32_e32 v202, s34, v202
	v_mul_f32_e32 v255, s34, v255
	v_fma_f32 v180, v30, v200, v180
	v_fma_f32 v181, v31, v201, v181
	v_fma_f32 v182, v32, v202, v182
	v_fma_f32 v183, v33, v255, v183
	v_mfma_f32_16x16x32_bf16 v[26:29], v[212:215], v[208:211], v[26:29]
	v_cvt_f32_ubyte0_e32 v200, v140
	v_cvt_f32_ubyte1_e32 v201, v140
	v_cvt_f32_ubyte2_e32 v202, v140
	v_cvt_f32_ubyte3_e32 v255, v140
	v_mul_f32_e32 v200, s34, v200
	v_mul_f32_e32 v201, s34, v201
	v_mul_f32_e32 v202, s34, v202
	v_mul_f32_e32 v255, s34, v255
	v_fma_f32 v176, v38, v200, v176
	v_fma_f32 v177, v39, v201, v177
	v_fma_f32 v178, v40, v202, v178
	v_fma_f32 v179, v41, v255, v179
	v_mfma_f32_16x16x32_bf16 v[14:17], v[216:219], v[208:211], v[14:17]
	v_cvt_f32_ubyte0_e32 v200, v141
	v_cvt_f32_ubyte1_e32 v201, v141
	v_cvt_f32_ubyte2_e32 v202, v141
	v_cvt_f32_ubyte3_e32 v255, v141
	v_mul_f32_e32 v200, s34, v200
	v_mul_f32_e32 v201, s34, v201
	v_mul_f32_e32 v202, s34, v202
	v_mul_f32_e32 v255, s34, v255
	v_fma_f32 v172, v42, v200, v172
	v_fma_f32 v173, v43, v201, v173
	v_fma_f32 v174, v44, v202, v174
	v_fma_f32 v175, v45, v255, v175
	v_mfma_f32_16x16x32_bf16 v[10:13], v[220:223], v[208:211], v[10:13]
	v_cvt_f32_ubyte0_e32 v200, v142
	v_cvt_f32_ubyte1_e32 v201, v142
	v_cvt_f32_ubyte2_e32 v202, v142
	v_cvt_f32_ubyte3_e32 v255, v142
	v_mul_f32_e32 v200, s34, v200
	v_mul_f32_e32 v201, s34, v201
	v_mul_f32_e32 v202, s34, v202
	v_mul_f32_e32 v255, s34, v255
	v_fma_f32 v168, v46, v200, v168
	v_fma_f32 v169, v47, v201, v169
	v_fma_f32 v170, v48, v202, v170
	v_fma_f32 v171, v49, v255, v171
	ds_read_b128 v[208:211], v205 offset:46144
	s_waitcnt lgkmcnt(0)
	v_mfma_f32_16x16x32_bf16 v[34:37], v[90:93], v[208:211], v[34:37]
	v_cvt_f32_ubyte0_e32 v200, v143
	v_cvt_f32_ubyte1_e32 v201, v143
	v_cvt_f32_ubyte2_e32 v202, v143
	v_cvt_f32_ubyte3_e32 v255, v143
	v_mul_f32_e32 v200, s34, v200
	v_mul_f32_e32 v201, s34, v201
	v_mul_f32_e32 v202, s34, v202
	v_mul_f32_e32 v255, s34, v255
	v_fma_f32 v164, v26, v200, v164
	v_fma_f32 v165, v27, v201, v165
	v_fma_f32 v166, v28, v202, v166
	v_fma_f32 v167, v29, v255, v167
	v_mfma_f32_16x16x32_bf16 v[22:25], v[212:215], v[208:211], v[22:25]
	v_cvt_f32_ubyte0_e32 v200, v144
	v_cvt_f32_ubyte1_e32 v201, v144
	v_cvt_f32_ubyte2_e32 v202, v144
	v_cvt_f32_ubyte3_e32 v255, v144
	v_mul_f32_e32 v200, s34, v200
	v_mul_f32_e32 v201, s34, v201
	v_mul_f32_e32 v202, s34, v202
	v_mul_f32_e32 v255, s34, v255
	v_fma_f32 v160, v14, v200, v160
	v_fma_f32 v161, v15, v201, v161
	v_fma_f32 v162, v16, v202, v162
	v_fma_f32 v163, v17, v255, v163
	v_mfma_f32_16x16x32_bf16 v[18:21], v[216:219], v[208:211], v[18:21]
	v_cvt_f32_ubyte0_e32 v200, v145
	v_cvt_f32_ubyte1_e32 v201, v145
	v_cvt_f32_ubyte2_e32 v202, v145
	v_cvt_f32_ubyte3_e32 v255, v145
	v_mul_f32_e32 v200, s34, v200
	v_mul_f32_e32 v201, s34, v201
	v_mul_f32_e32 v202, s34, v202
	v_mul_f32_e32 v255, s34, v255
	v_fma_f32 v156, v10, v200, v156
	v_fma_f32 v157, v11, v201, v157
	v_fma_f32 v158, v12, v202, v158
	v_fma_f32 v159, v13, v255, v159
	v_mfma_f32_16x16x32_bf16 v[62:65], v[220:223], v[208:211], v[62:65]
	v_cvt_f32_ubyte0_e32 v200, v146
	v_cvt_f32_ubyte1_e32 v201, v146
	v_cvt_f32_ubyte2_e32 v202, v146
	v_cvt_f32_ubyte3_e32 v255, v146
	v_mul_f32_e32 v200, s34, v200
	v_mul_f32_e32 v201, s34, v201
	v_mul_f32_e32 v202, s34, v202
	v_mul_f32_e32 v255, s34, v255
	v_fma_f32 v136, v34, v200, v136
	v_fma_f32 v137, v35, v201, v137
	v_fma_f32 v150, v36, v202, v150
	v_fma_f32 v151, v37, v255, v151
	v_mfma_f32_16x16x32_bf16 v[58:61], v[90:93], v[224:227], v[58:61]
	v_cvt_f32_ubyte0_e32 v200, v147
	v_cvt_f32_ubyte1_e32 v201, v147
	v_cvt_f32_ubyte2_e32 v202, v147
	v_cvt_f32_ubyte3_e32 v255, v147
	v_mul_f32_e32 v200, s34, v200
	v_mul_f32_e32 v201, s34, v201
	v_mul_f32_e32 v202, s34, v202
	v_mul_f32_e32 v255, s34, v255
	v_fma_f32 v130, v22, v200, v130
	v_fma_f32 v131, v23, v201, v131
	v_fma_f32 v134, v24, v202, v134
	v_fma_f32 v135, v25, v255, v135
	v_mfma_f32_16x16x32_bf16 v[54:57], v[212:215], v[224:227], v[54:57]
	v_cvt_f32_ubyte0_e32 v200, v148
	v_cvt_f32_ubyte1_e32 v201, v148
	v_cvt_f32_ubyte2_e32 v202, v148
	v_cvt_f32_ubyte3_e32 v255, v148
	v_mul_f32_e32 v200, s34, v200
	v_mul_f32_e32 v201, s34, v201
	v_mul_f32_e32 v202, s34, v202
	v_mul_f32_e32 v255, s34, v255
	v_fma_f32 v124, v18, v200, v124
	v_fma_f32 v125, v19, v201, v125
	v_fma_f32 v126, v20, v202, v126
	v_fma_f32 v127, v21, v255, v127
	v_mfma_f32_16x16x32_bf16 v[50:53], v[216:219], v[224:227], v[50:53]
	v_cvt_f32_ubyte0_e32 v200, v149
	v_cvt_f32_ubyte1_e32 v201, v149
	v_cvt_f32_ubyte2_e32 v202, v149
	v_cvt_f32_ubyte3_e32 v255, v149
	v_mul_f32_e32 v200, s34, v200
	v_mul_f32_e32 v201, s34, v201
	v_mul_f32_e32 v202, s34, v202
	v_mul_f32_e32 v255, s34, v255
	v_fma_f32 v120, v62, v200, v120
	v_fma_f32 v121, v63, v201, v121
	v_fma_f32 v122, v64, v202, v122
	v_fma_f32 v123, v65, v255, v123
	v_mfma_f32_16x16x32_bf16 v[2:5], v[220:223], v[224:227], v[2:5]
	v_cvt_f32_ubyte0_e32 v200, v194
	v_cvt_f32_ubyte1_e32 v201, v194
	v_cvt_f32_ubyte2_e32 v202, v194
	v_cvt_f32_ubyte3_e32 v255, v194
	v_mul_f32_e32 v200, s34, v200
	v_mul_f32_e32 v201, s34, v201
	v_mul_f32_e32 v202, s34, v202
	v_mul_f32_e32 v255, s34, v255
	v_fma_f32 v114, v58, v200, v114
	v_fma_f32 v115, v59, v201, v115
	v_fma_f32 v116, v60, v202, v116
	v_fma_f32 v117, v61, v255, v117
	s_nop 7
	s_nop 3
	v_cvt_f32_ubyte0_e32 v200, v195
	v_cvt_f32_ubyte1_e32 v201, v195
	v_cvt_f32_ubyte2_e32 v202, v195
	v_cvt_f32_ubyte3_e32 v255, v195
	v_mul_f32_e32 v200, s34, v200
	v_mul_f32_e32 v201, s34, v201
	v_mul_f32_e32 v202, s34, v202
	v_mul_f32_e32 v255, s34, v255
	v_fma_f32 v106, v54, v200, v106
	v_fma_f32 v107, v55, v201, v107
	v_fma_f32 v108, v56, v202, v108
	v_fma_f32 v109, v57, v255, v109
	v_cvt_f32_ubyte0_e32 v200, v196
	v_cvt_f32_ubyte1_e32 v201, v196
	v_cvt_f32_ubyte2_e32 v202, v196
	v_cvt_f32_ubyte3_e32 v255, v196
	v_mul_f32_e32 v200, s34, v200
	v_mul_f32_e32 v201, s34, v201
	v_mul_f32_e32 v202, s34, v202
	v_mul_f32_e32 v255, s34, v255
	v_fma_f32 v100, v50, v200, v100
	v_fma_f32 v101, v51, v201, v101
	v_fma_f32 v102, v52, v202, v102
	v_fma_f32 v103, v53, v255, v103
	v_cvt_f32_ubyte0_e32 v200, v197
	v_cvt_f32_ubyte1_e32 v201, v197
	v_cvt_f32_ubyte2_e32 v202, v197
	v_cvt_f32_ubyte3_e32 v255, v197
	v_mul_f32_e32 v200, s34, v200
	v_mul_f32_e32 v201, s34, v201
	v_mul_f32_e32 v202, s34, v202
	v_mul_f32_e32 v255, s34, v255
	v_fma_f32 v96, v2, v200, v96
	v_fma_f32 v97, v3, v201, v97
	v_fma_f32 v98, v4, v202, v98
	v_fma_f32 v99, v5, v255, v99
	s_waitcnt vmcnt(11)
	ds_write_b128 v206, v[66:69] offset:0
	s_waitcnt vmcnt(10)
	ds_write_b128 v206, v[70:73] offset:10240
	s_waitcnt vmcnt(9)
	ds_write_b128 v206, v[74:77] offset:20480
	s_waitcnt vmcnt(8)
	ds_write_b128 v206, v[78:81] offset:30720
	s_waitcnt vmcnt(7)
	ds_write_b128 v0, v[82:85] offset:0
	s_waitcnt vmcnt(6)
	ds_write_b128 v0, v[86:89] offset:10240
	s_waitcnt lgkmcnt(0)
	s_barrier
	global_load_dwordx4 v[66:69], v190, s[80:81] offset:256
	global_load_dwordx4 v[70:73], v191, s[80:81] offset:256
	global_load_dwordx4 v[74:77], v190, s[86:87] offset:256
	global_load_dwordx4 v[78:81], v191, s[86:87] offset:256
	global_load_dwordx4 v[82:85], v188, s[96:97] offset:256
	global_load_dwordx4 v[86:89], v188, s[98:99] offset:256
	ds_read_b128 v[90:93], v119 offset:0
	ds_read_b128 v[208:211], v205 offset:0
	ds_read_b128 v[212:215], v119 offset:2560
	ds_read_b128 v[216:219], v119 offset:5120
	ds_read_b128 v[220:223], v119 offset:7680
	s_waitcnt lgkmcnt(3)
	v_mfma_f32_16x16x32_bf16 v[6:9], v[90:93], v[208:211], 0
	s_waitcnt lgkmcnt(2)
	v_mfma_f32_16x16x32_bf16 v[30:33], v[212:215], v[208:211], 0
	s_waitcnt vmcnt(11)
	ds_write_b128 v207, v[228:231] offset:0
	s_waitcnt lgkmcnt(2)
	v_mfma_f32_16x16x32_bf16 v[38:41], v[216:219], v[208:211], 0
	s_waitcnt lgkmcnt(1)
	v_mfma_f32_16x16x32_bf16 v[42:45], v[220:223], v[208:211], 0
	ds_read_b128 v[208:211], v205 offset:2560
	s_waitcnt lgkmcnt(0)
	v_mfma_f32_16x16x32_bf16 v[46:49], v[90:93], v[208:211], 0
	v_mfma_f32_16x16x32_bf16 v[26:29], v[212:215], v[208:211], 0
	s_waitcnt vmcnt(10)
	ds_write_b128 v207, v[232:235] offset:10240
	v_mfma_f32_16x16x32_bf16 v[14:17], v[216:219], v[208:211], 0
	v_mfma_f32_16x16x32_bf16 v[10:13], v[220:223], v[208:211], 0
	ds_read_b128 v[208:211], v205 offset:5120
	s_waitcnt lgkmcnt(0)
	v_mfma_f32_16x16x32_bf16 v[34:37], v[90:93], v[208:211], 0
	v_mfma_f32_16x16x32_bf16 v[22:25], v[212:215], v[208:211], 0
	s_waitcnt vmcnt(9)
	ds_write_b128 v207, v[236:239] offset:20480
	v_mfma_f32_16x16x32_bf16 v[18:21], v[216:219], v[208:211], 0
	v_mfma_f32_16x16x32_bf16 v[62:65], v[220:223], v[208:211], 0
	ds_read_b128 v[208:211], v205 offset:7680
	s_waitcnt lgkmcnt(0)
	v_mfma_f32_16x16x32_bf16 v[58:61], v[90:93], v[208:211], 0
	ds_read_b128 v[90:93], v119 offset:64
	v_mfma_f32_16x16x32_bf16 v[54:57], v[212:215], v[208:211], 0
	s_waitcnt vmcnt(8)
	ds_write_b128 v207, v[240:243] offset:30720
	ds_read_b128 v[212:215], v119 offset:2624
	v_mfma_f32_16x16x32_bf16 v[50:53], v[216:219], v[208:211], 0
	ds_read_b128 v[216:219], v119 offset:5184
	v_mfma_f32_16x16x32_bf16 v[2:5], v[220:223], v[208:211], 0
	ds_read_b128 v[220:223], v119 offset:7744
	ds_read_b128 v[208:211], v205 offset:64
	ds_read_b128 v[224:227], v205 offset:7744
	s_waitcnt lgkmcnt(1)
	v_mfma_f32_16x16x32_bf16 v[6:9], v[90:93], v[208:211], v[6:9]
	v_mfma_f32_16x16x32_bf16 v[30:33], v[212:215], v[208:211], v[30:33]
	s_waitcnt vmcnt(7)
	ds_write_b128 v0, v[244:247] offset:20480
	v_mfma_f32_16x16x32_bf16 v[38:41], v[216:219], v[208:211], v[38:41]
	v_mfma_f32_16x16x32_bf16 v[42:45], v[220:223], v[208:211], v[42:45]
	ds_read_b128 v[208:211], v205 offset:2624
	s_waitcnt lgkmcnt(0)
	v_mfma_f32_16x16x32_bf16 v[46:49], v[90:93], v[208:211], v[46:49]
	v_mfma_f32_16x16x32_bf16 v[26:29], v[212:215], v[208:211], v[26:29]
	s_waitcnt vmcnt(6)
	ds_write_b128 v0, v[248:251] offset:30720
	v_mfma_f32_16x16x32_bf16 v[14:17], v[216:219], v[208:211], v[14:17]
	v_mfma_f32_16x16x32_bf16 v[10:13], v[220:223], v[208:211], v[10:13]
	ds_read_b128 v[208:211], v205 offset:5184
	s_waitcnt lgkmcnt(0)
	v_mfma_f32_16x16x32_bf16 v[34:37], v[90:93], v[208:211], v[34:37]
	v_mfma_f32_16x16x32_bf16 v[22:25], v[212:215], v[208:211], v[22:25]
	v_mfma_f32_16x16x32_bf16 v[18:21], v[216:219], v[208:211], v[18:21]
	v_mfma_f32_16x16x32_bf16 v[62:65], v[220:223], v[208:211], v[62:65]
	v_mfma_f32_16x16x32_bf16 v[58:61], v[90:93], v[224:227], v[58:61]
	s_waitcnt lgkmcnt(0)
	v_mfma_f32_16x16x32_bf16 v[54:57], v[212:215], v[224:227], v[54:57]
	s_barrier
	v_mfma_f32_16x16x32_bf16 v[50:53], v[216:219], v[224:227], v[50:53]
	v_mfma_f32_16x16x32_bf16 v[2:5], v[220:223], v[224:227], v[2:5]
	global_load_dwordx4 v[228:231], v190, s[80:81] offset:384
	global_load_dwordx4 v[232:235], v191, s[80:81] offset:384
	global_load_dwordx4 v[236:239], v190, s[86:87] offset:384
	global_load_dwordx4 v[240:243], v191, s[86:87] offset:384
	global_load_dwordx4 v[244:247], v188, s[96:97] offset:384
	global_load_dwordx4 v[248:251], v188, s[98:99] offset:384
	ds_read_b128 v[90:93], v119 offset:20480
	ds_read_b128 v[208:211], v205 offset:40960
	ds_read_b128 v[212:215], v119 offset:23040
	ds_read_b128 v[216:219], v119 offset:25600
	ds_read_b128 v[220:223], v119 offset:28160
	s_waitcnt lgkmcnt(3)
	v_mfma_f32_16x16x32_bf16 v[6:9], v[90:93], v[208:211], v[6:9]
	s_waitcnt lgkmcnt(2)
	v_mfma_f32_16x16x32_bf16 v[30:33], v[212:215], v[208:211], v[30:33]
	s_waitcnt vmcnt(11)
	ds_write_b128 v206, v[66:69] offset:0
	s_waitcnt lgkmcnt(2)
	v_mfma_f32_16x16x32_bf16 v[38:41], v[216:219], v[208:211], v[38:41]
	s_waitcnt lgkmcnt(1)
	v_mfma_f32_16x16x32_bf16 v[42:45], v[220:223], v[208:211], v[42:45]
	ds_read_b128 v[208:211], v205 offset:43520
	s_waitcnt lgkmcnt(0)
	v_mfma_f32_16x16x32_bf16 v[46:49], v[90:93], v[208:211], v[46:49]
	v_mfma_f32_16x16x32_bf16 v[26:29], v[212:215], v[208:211], v[26:29]
	s_waitcnt vmcnt(10)
	ds_write_b128 v206, v[70:73] offset:10240
	v_mfma_f32_16x16x32_bf16 v[14:17], v[216:219], v[208:211], v[14:17]
	v_mfma_f32_16x16x32_bf16 v[10:13], v[220:223], v[208:211], v[10:13]
	ds_read_b128 v[208:211], v205 offset:46080
	s_waitcnt lgkmcnt(0)
	v_mfma_f32_16x16x32_bf16 v[34:37], v[90:93], v[208:211], v[34:37]
	v_mfma_f32_16x16x32_bf16 v[22:25], v[212:215], v[208:211], v[22:25]
	s_waitcnt vmcnt(9)
	ds_write_b128 v206, v[74:77] offset:20480
	v_mfma_f32_16x16x32_bf16 v[18:21], v[216:219], v[208:211], v[18:21]
	v_mfma_f32_16x16x32_bf16 v[62:65], v[220:223], v[208:211], v[62:65]
	ds_read_b128 v[208:211], v205 offset:48640
	s_waitcnt lgkmcnt(0)
	v_mfma_f32_16x16x32_bf16 v[58:61], v[90:93], v[208:211], v[58:61]
	ds_read_b128 v[90:93], v119 offset:20544
	v_mfma_f32_16x16x32_bf16 v[54:57], v[212:215], v[208:211], v[54:57]
	s_waitcnt vmcnt(8)
	ds_write_b128 v206, v[78:81] offset:30720
	ds_read_b128 v[212:215], v119 offset:23104
	v_mfma_f32_16x16x32_bf16 v[50:53], v[216:219], v[208:211], v[50:53]
	ds_read_b128 v[216:219], v119 offset:25664
	v_mfma_f32_16x16x32_bf16 v[2:5], v[220:223], v[208:211], v[2:5]
	ds_read_b128 v[220:223], v119 offset:28224
	ds_read_b128 v[208:211], v205 offset:41024
	ds_read_b128 v[224:227], v205 offset:48704
	s_waitcnt lgkmcnt(1)
	v_mfma_f32_16x16x32_bf16 v[6:9], v[90:93], v[208:211], v[6:9]
	v_mfma_f32_16x16x32_bf16 v[30:33], v[212:215], v[208:211], v[30:33]
	s_waitcnt vmcnt(7)
	ds_write_b128 v0, v[82:85] offset:0
	v_mfma_f32_16x16x32_bf16 v[38:41], v[216:219], v[208:211], v[38:41]
	v_mfma_f32_16x16x32_bf16 v[42:45], v[220:223], v[208:211], v[42:45]
	ds_read_b128 v[208:211], v205 offset:43584
	s_waitcnt lgkmcnt(0)
	v_mfma_f32_16x16x32_bf16 v[46:49], v[90:93], v[208:211], v[46:49]
	v_mfma_f32_16x16x32_bf16 v[26:29], v[212:215], v[208:211], v[26:29]
	s_waitcnt vmcnt(6)
	ds_write_b128 v0, v[86:89] offset:10240
	v_mfma_f32_16x16x32_bf16 v[14:17], v[216:219], v[208:211], v[14:17]
	v_mfma_f32_16x16x32_bf16 v[10:13], v[220:223], v[208:211], v[10:13]
	ds_read_b128 v[208:211], v205 offset:46144
	s_waitcnt lgkmcnt(0)
	v_mfma_f32_16x16x32_bf16 v[34:37], v[90:93], v[208:211], v[34:37]
	v_mfma_f32_16x16x32_bf16 v[22:25], v[212:215], v[208:211], v[22:25]
	v_mfma_f32_16x16x32_bf16 v[18:21], v[216:219], v[208:211], v[18:21]
	v_mfma_f32_16x16x32_bf16 v[62:65], v[220:223], v[208:211], v[62:65]
	v_mfma_f32_16x16x32_bf16 v[58:61], v[90:93], v[224:227], v[58:61]
	s_waitcnt lgkmcnt(0)
	v_mfma_f32_16x16x32_bf16 v[54:57], v[212:215], v[224:227], v[54:57]
	s_barrier
	v_mfma_f32_16x16x32_bf16 v[50:53], v[216:219], v[224:227], v[50:53]
	v_mfma_f32_16x16x32_bf16 v[2:5], v[220:223], v[224:227], v[2:5]
	global_load_dwordx4 v[66:69], v190, s[80:81] offset:512
	global_load_dwordx4 v[70:73], v191, s[80:81] offset:512
	global_load_dwordx4 v[74:77], v190, s[86:87] offset:512
	global_load_dwordx4 v[78:81], v191, s[86:87] offset:512
	global_load_dwordx4 v[82:85], v188, s[96:97] offset:512
	global_load_dwordx4 v[86:89], v188, s[98:99] offset:512
	ds_read_b128 v[90:93], v119 offset:0
	ds_read_b128 v[208:211], v205 offset:0
	ds_read_b128 v[212:215], v119 offset:2560
	ds_read_b128 v[216:219], v119 offset:5120
	ds_read_b128 v[220:223], v119 offset:7680
	s_waitcnt lgkmcnt(3)
	v_mfma_f32_16x16x32_bf16 v[6:9], v[90:93], v[208:211], v[6:9]
	s_waitcnt lgkmcnt(2)
	v_mfma_f32_16x16x32_bf16 v[30:33], v[212:215], v[208:211], v[30:33]
	s_waitcnt vmcnt(11)
	ds_write_b128 v207, v[228:231] offset:0
	s_waitcnt lgkmcnt(2)
	v_mfma_f32_16x16x32_bf16 v[38:41], v[216:219], v[208:211], v[38:41]
	s_waitcnt lgkmcnt(1)
	v_mfma_f32_16x16x32_bf16 v[42:45], v[220:223], v[208:211], v[42:45]
	ds_read_b128 v[208:211], v205 offset:2560
	s_waitcnt lgkmcnt(0)
	v_mfma_f32_16x16x32_bf16 v[46:49], v[90:93], v[208:211], v[46:49]
	v_mfma_f32_16x16x32_bf16 v[26:29], v[212:215], v[208:211], v[26:29]
	s_waitcnt vmcnt(10)
	ds_write_b128 v207, v[232:235] offset:10240
	v_mfma_f32_16x16x32_bf16 v[14:17], v[216:219], v[208:211], v[14:17]
	v_mfma_f32_16x16x32_bf16 v[10:13], v[220:223], v[208:211], v[10:13]
	ds_read_b128 v[208:211], v205 offset:5120
	s_waitcnt lgkmcnt(0)
	v_mfma_f32_16x16x32_bf16 v[34:37], v[90:93], v[208:211], v[34:37]
	v_mfma_f32_16x16x32_bf16 v[22:25], v[212:215], v[208:211], v[22:25]
	s_waitcnt vmcnt(9)
	ds_write_b128 v207, v[236:239] offset:20480
	v_mfma_f32_16x16x32_bf16 v[18:21], v[216:219], v[208:211], v[18:21]
	v_mfma_f32_16x16x32_bf16 v[62:65], v[220:223], v[208:211], v[62:65]
	ds_read_b128 v[208:211], v205 offset:7680
	s_waitcnt lgkmcnt(0)
	v_mfma_f32_16x16x32_bf16 v[58:61], v[90:93], v[208:211], v[58:61]
	ds_read_b128 v[90:93], v119 offset:64
	v_mfma_f32_16x16x32_bf16 v[54:57], v[212:215], v[208:211], v[54:57]
	s_waitcnt vmcnt(8)
	ds_write_b128 v207, v[240:243] offset:30720
	ds_read_b128 v[212:215], v119 offset:2624
	v_mfma_f32_16x16x32_bf16 v[50:53], v[216:219], v[208:211], v[50:53]
	ds_read_b128 v[216:219], v119 offset:5184
	v_mfma_f32_16x16x32_bf16 v[2:5], v[220:223], v[208:211], v[2:5]
	ds_read_b128 v[220:223], v119 offset:7744
	ds_read_b128 v[208:211], v205 offset:64
	ds_read_b128 v[224:227], v205 offset:7744
	s_waitcnt lgkmcnt(1)
	v_mfma_f32_16x16x32_bf16 v[6:9], v[90:93], v[208:211], v[6:9]
	v_mfma_f32_16x16x32_bf16 v[30:33], v[212:215], v[208:211], v[30:33]
	s_waitcnt vmcnt(7)
	ds_write_b128 v0, v[244:247] offset:20480
	v_mfma_f32_16x16x32_bf16 v[38:41], v[216:219], v[208:211], v[38:41]
	v_mfma_f32_16x16x32_bf16 v[42:45], v[220:223], v[208:211], v[42:45]
	ds_read_b128 v[208:211], v205 offset:2624
	s_waitcnt lgkmcnt(0)
	v_mfma_f32_16x16x32_bf16 v[46:49], v[90:93], v[208:211], v[46:49]
	v_mfma_f32_16x16x32_bf16 v[26:29], v[212:215], v[208:211], v[26:29]
	s_waitcnt vmcnt(6)
	ds_write_b128 v0, v[248:251] offset:30720
	v_mfma_f32_16x16x32_bf16 v[14:17], v[216:219], v[208:211], v[14:17]
	v_mfma_f32_16x16x32_bf16 v[10:13], v[220:223], v[208:211], v[10:13]
	ds_read_b128 v[208:211], v205 offset:5184
	s_waitcnt lgkmcnt(0)
	v_mfma_f32_16x16x32_bf16 v[34:37], v[90:93], v[208:211], v[34:37]
	v_mfma_f32_16x16x32_bf16 v[22:25], v[212:215], v[208:211], v[22:25]
	v_mfma_f32_16x16x32_bf16 v[18:21], v[216:219], v[208:211], v[18:21]
	v_mfma_f32_16x16x32_bf16 v[62:65], v[220:223], v[208:211], v[62:65]
	v_mfma_f32_16x16x32_bf16 v[58:61], v[90:93], v[224:227], v[58:61]
	s_waitcnt lgkmcnt(0)
	v_mfma_f32_16x16x32_bf16 v[54:57], v[212:215], v[224:227], v[54:57]
	s_barrier
	v_mfma_f32_16x16x32_bf16 v[50:53], v[216:219], v[224:227], v[50:53]
	v_mfma_f32_16x16x32_bf16 v[2:5], v[220:223], v[224:227], v[2:5]
	global_load_dwordx4 v[228:231], v190, s[80:81] offset:640
	global_load_dwordx4 v[232:235], v191, s[80:81] offset:640
	global_load_dwordx4 v[236:239], v190, s[86:87] offset:640
	global_load_dwordx4 v[240:243], v191, s[86:87] offset:640
	global_load_dwordx4 v[244:247], v188, s[96:97] offset:640
	global_load_dwordx4 v[248:251], v188, s[98:99] offset:640
	ds_read_b128 v[90:93], v119 offset:20480
	ds_read_b128 v[208:211], v205 offset:40960
	ds_read_b128 v[212:215], v119 offset:23040
	ds_read_b128 v[216:219], v119 offset:25600
	ds_read_b128 v[220:223], v119 offset:28160
	s_waitcnt lgkmcnt(3)
	v_mfma_f32_16x16x32_bf16 v[6:9], v[90:93], v[208:211], v[6:9]
	s_waitcnt lgkmcnt(2)
	v_mfma_f32_16x16x32_bf16 v[30:33], v[212:215], v[208:211], v[30:33]
	s_waitcnt vmcnt(11)
	ds_write_b128 v206, v[66:69] offset:0
	s_waitcnt lgkmcnt(2)
	v_mfma_f32_16x16x32_bf16 v[38:41], v[216:219], v[208:211], v[38:41]
	s_waitcnt lgkmcnt(1)
	v_mfma_f32_16x16x32_bf16 v[42:45], v[220:223], v[208:211], v[42:45]
	ds_read_b128 v[208:211], v205 offset:43520
	s_waitcnt lgkmcnt(0)
	v_mfma_f32_16x16x32_bf16 v[46:49], v[90:93], v[208:211], v[46:49]
	v_mfma_f32_16x16x32_bf16 v[26:29], v[212:215], v[208:211], v[26:29]
	s_waitcnt vmcnt(10)
	ds_write_b128 v206, v[70:73] offset:10240
	v_mfma_f32_16x16x32_bf16 v[14:17], v[216:219], v[208:211], v[14:17]
	v_mfma_f32_16x16x32_bf16 v[10:13], v[220:223], v[208:211], v[10:13]
	ds_read_b128 v[208:211], v205 offset:46080
	s_waitcnt lgkmcnt(0)
	v_mfma_f32_16x16x32_bf16 v[34:37], v[90:93], v[208:211], v[34:37]
	v_mfma_f32_16x16x32_bf16 v[22:25], v[212:215], v[208:211], v[22:25]
	s_waitcnt vmcnt(9)
	ds_write_b128 v206, v[74:77] offset:20480
	v_mfma_f32_16x16x32_bf16 v[18:21], v[216:219], v[208:211], v[18:21]
	v_mfma_f32_16x16x32_bf16 v[62:65], v[220:223], v[208:211], v[62:65]
	ds_read_b128 v[208:211], v205 offset:48640
	s_waitcnt lgkmcnt(0)
	v_mfma_f32_16x16x32_bf16 v[58:61], v[90:93], v[208:211], v[58:61]
	ds_read_b128 v[90:93], v119 offset:20544
	v_mfma_f32_16x16x32_bf16 v[54:57], v[212:215], v[208:211], v[54:57]
	s_waitcnt vmcnt(8)
	ds_write_b128 v206, v[78:81] offset:30720
	ds_read_b128 v[212:215], v119 offset:23104
	v_mfma_f32_16x16x32_bf16 v[50:53], v[216:219], v[208:211], v[50:53]
	ds_read_b128 v[216:219], v119 offset:25664
	v_mfma_f32_16x16x32_bf16 v[2:5], v[220:223], v[208:211], v[2:5]
	ds_read_b128 v[220:223], v119 offset:28224
	ds_read_b128 v[208:211], v205 offset:41024
	ds_read_b128 v[224:227], v205 offset:48704
	s_waitcnt lgkmcnt(1)
	v_mfma_f32_16x16x32_bf16 v[6:9], v[90:93], v[208:211], v[6:9]
	v_mfma_f32_16x16x32_bf16 v[30:33], v[212:215], v[208:211], v[30:33]
	s_waitcnt vmcnt(7)
	ds_write_b128 v0, v[82:85] offset:0
	v_mfma_f32_16x16x32_bf16 v[38:41], v[216:219], v[208:211], v[38:41]
	v_mfma_f32_16x16x32_bf16 v[42:45], v[220:223], v[208:211], v[42:45]
	ds_read_b128 v[208:211], v205 offset:43584
	s_waitcnt lgkmcnt(0)
	v_mfma_f32_16x16x32_bf16 v[46:49], v[90:93], v[208:211], v[46:49]
	v_mfma_f32_16x16x32_bf16 v[26:29], v[212:215], v[208:211], v[26:29]
	s_waitcnt vmcnt(6)
	ds_write_b128 v0, v[86:89] offset:10240
	v_mfma_f32_16x16x32_bf16 v[14:17], v[216:219], v[208:211], v[14:17]
	v_mfma_f32_16x16x32_bf16 v[10:13], v[220:223], v[208:211], v[10:13]
	ds_read_b128 v[208:211], v205 offset:46144
	s_waitcnt lgkmcnt(0)
	v_mfma_f32_16x16x32_bf16 v[34:37], v[90:93], v[208:211], v[34:37]
	v_mfma_f32_16x16x32_bf16 v[22:25], v[212:215], v[208:211], v[22:25]
	v_mfma_f32_16x16x32_bf16 v[18:21], v[216:219], v[208:211], v[18:21]
	v_mfma_f32_16x16x32_bf16 v[62:65], v[220:223], v[208:211], v[62:65]
	v_mfma_f32_16x16x32_bf16 v[58:61], v[90:93], v[224:227], v[58:61]
	s_waitcnt lgkmcnt(0)
	v_mfma_f32_16x16x32_bf16 v[54:57], v[212:215], v[224:227], v[54:57]
	s_barrier
	v_mfma_f32_16x16x32_bf16 v[50:53], v[216:219], v[224:227], v[50:53]
	v_mfma_f32_16x16x32_bf16 v[2:5], v[220:223], v[224:227], v[2:5]
	global_load_dwordx4 v[66:69], v190, s[80:81] offset:768
	global_load_dwordx4 v[70:73], v191, s[80:81] offset:768
	global_load_dwordx4 v[74:77], v190, s[86:87] offset:768
	global_load_dwordx4 v[78:81], v191, s[86:87] offset:768
	global_load_dwordx4 v[82:85], v188, s[96:97] offset:768
	global_load_dwordx4 v[86:89], v188, s[98:99] offset:768
	ds_read_b128 v[90:93], v119 offset:0
	ds_read_b128 v[208:211], v205 offset:0
	ds_read_b128 v[212:215], v119 offset:2560
	ds_read_b128 v[216:219], v119 offset:5120
	ds_read_b128 v[220:223], v119 offset:7680
	s_waitcnt lgkmcnt(3)
	v_mfma_f32_16x16x32_bf16 v[6:9], v[90:93], v[208:211], v[6:9]
	s_waitcnt lgkmcnt(2)
	v_mfma_f32_16x16x32_bf16 v[30:33], v[212:215], v[208:211], v[30:33]
	s_waitcnt vmcnt(11)
	ds_write_b128 v207, v[228:231] offset:0
	s_waitcnt lgkmcnt(2)
	v_mfma_f32_16x16x32_bf16 v[38:41], v[216:219], v[208:211], v[38:41]
	s_waitcnt lgkmcnt(1)
	v_mfma_f32_16x16x32_bf16 v[42:45], v[220:223], v[208:211], v[42:45]
	ds_read_b128 v[208:211], v205 offset:2560
	s_waitcnt lgkmcnt(0)
	v_mfma_f32_16x16x32_bf16 v[46:49], v[90:93], v[208:211], v[46:49]
	v_mfma_f32_16x16x32_bf16 v[26:29], v[212:215], v[208:211], v[26:29]
	s_waitcnt vmcnt(10)
	ds_write_b128 v207, v[232:235] offset:10240
	v_mfma_f32_16x16x32_bf16 v[14:17], v[216:219], v[208:211], v[14:17]
	v_mfma_f32_16x16x32_bf16 v[10:13], v[220:223], v[208:211], v[10:13]
	ds_read_b128 v[208:211], v205 offset:5120
	s_waitcnt lgkmcnt(0)
	v_mfma_f32_16x16x32_bf16 v[34:37], v[90:93], v[208:211], v[34:37]
	v_mfma_f32_16x16x32_bf16 v[22:25], v[212:215], v[208:211], v[22:25]
	s_waitcnt vmcnt(9)
	ds_write_b128 v207, v[236:239] offset:20480
	v_mfma_f32_16x16x32_bf16 v[18:21], v[216:219], v[208:211], v[18:21]
	v_mfma_f32_16x16x32_bf16 v[62:65], v[220:223], v[208:211], v[62:65]
	ds_read_b128 v[208:211], v205 offset:7680
	s_waitcnt lgkmcnt(0)
	v_mfma_f32_16x16x32_bf16 v[58:61], v[90:93], v[208:211], v[58:61]
	ds_read_b128 v[90:93], v119 offset:64
	v_mfma_f32_16x16x32_bf16 v[54:57], v[212:215], v[208:211], v[54:57]
	s_waitcnt vmcnt(8)
	ds_write_b128 v207, v[240:243] offset:30720
	ds_read_b128 v[212:215], v119 offset:2624
	v_mfma_f32_16x16x32_bf16 v[50:53], v[216:219], v[208:211], v[50:53]
	ds_read_b128 v[216:219], v119 offset:5184
	v_mfma_f32_16x16x32_bf16 v[2:5], v[220:223], v[208:211], v[2:5]
	ds_read_b128 v[220:223], v119 offset:7744
	ds_read_b128 v[208:211], v205 offset:64
	ds_read_b128 v[224:227], v205 offset:7744
	s_waitcnt lgkmcnt(1)
	v_mfma_f32_16x16x32_bf16 v[6:9], v[90:93], v[208:211], v[6:9]
	v_mfma_f32_16x16x32_bf16 v[30:33], v[212:215], v[208:211], v[30:33]
	s_waitcnt vmcnt(7)
	ds_write_b128 v0, v[244:247] offset:20480
	v_mfma_f32_16x16x32_bf16 v[38:41], v[216:219], v[208:211], v[38:41]
	v_mfma_f32_16x16x32_bf16 v[42:45], v[220:223], v[208:211], v[42:45]
	ds_read_b128 v[208:211], v205 offset:2624
	s_waitcnt lgkmcnt(0)
	v_mfma_f32_16x16x32_bf16 v[46:49], v[90:93], v[208:211], v[46:49]
	v_mfma_f32_16x16x32_bf16 v[26:29], v[212:215], v[208:211], v[26:29]
	s_waitcnt vmcnt(6)
	ds_write_b128 v0, v[248:251] offset:30720
	s_movk_i32 s10, 0xc00
	s_mov_b32 s11, 0
	v_lshl_add_u64 v[200:201], v[128:129], 0, s[10:11]
	global_load_dwordx2 v[138:139], v[200:201], off
	global_load_dwordx2 v[140:141], v[200:201], off offset:32
	v_lshl_add_u64 v[200:201], v[132:133], 0, s[10:11]
	global_load_dwordx2 v[142:143], v[200:201], off
	global_load_dwordx2 v[144:145], v[200:201], off offset:32
	v_lshl_add_u64 v[200:201], v[152:153], 0, s[10:11]
	global_load_dwordx2 v[146:147], v[200:201], off
	global_load_dwordx2 v[148:149], v[200:201], off offset:32
	v_lshl_add_u64 v[200:201], v[154:155], 0, s[10:11]
	global_load_dwordx2 v[194:195], v[200:201], off
	global_load_dwordx2 v[196:197], v[200:201], off offset:32
	v_mfma_f32_16x16x32_bf16 v[14:17], v[216:219], v[208:211], v[14:17]
	v_mfma_f32_16x16x32_bf16 v[10:13], v[220:223], v[208:211], v[10:13]
	ds_read_b128 v[208:211], v205 offset:5184
	s_waitcnt lgkmcnt(0)
	v_mfma_f32_16x16x32_bf16 v[34:37], v[90:93], v[208:211], v[34:37]
	v_mfma_f32_16x16x32_bf16 v[22:25], v[212:215], v[208:211], v[22:25]
	v_mfma_f32_16x16x32_bf16 v[18:21], v[216:219], v[208:211], v[18:21]
	v_mfma_f32_16x16x32_bf16 v[62:65], v[220:223], v[208:211], v[62:65]
	v_mfma_f32_16x16x32_bf16 v[58:61], v[90:93], v[224:227], v[58:61]
	s_waitcnt lgkmcnt(0)
	v_mfma_f32_16x16x32_bf16 v[54:57], v[212:215], v[224:227], v[54:57]
	s_barrier
	v_mfma_f32_16x16x32_bf16 v[50:53], v[216:219], v[224:227], v[50:53]
	v_mfma_f32_16x16x32_bf16 v[2:5], v[220:223], v[224:227], v[2:5]
	global_load_dwordx4 v[228:231], v190, s[80:81] offset:896
	global_load_dwordx4 v[232:235], v191, s[80:81] offset:896
	global_load_dwordx4 v[236:239], v190, s[86:87] offset:896
	global_load_dwordx4 v[240:243], v191, s[86:87] offset:896
	global_load_dwordx4 v[244:247], v188, s[96:97] offset:896
	global_load_dwordx4 v[248:251], v188, s[98:99] offset:896
	ds_read_b128 v[90:93], v119 offset:20480
	ds_read_b128 v[208:211], v205 offset:40960
	ds_read_b128 v[212:215], v119 offset:23040
	ds_read_b128 v[216:219], v119 offset:25600
	ds_read_b128 v[220:223], v119 offset:28160
	s_waitcnt lgkmcnt(3)
	v_mfma_f32_16x16x32_bf16 v[6:9], v[90:93], v[208:211], v[6:9]
	s_waitcnt lgkmcnt(2)
	v_mfma_f32_16x16x32_bf16 v[30:33], v[212:215], v[208:211], v[30:33]
	s_waitcnt vmcnt(19)
	ds_write_b128 v206, v[66:69] offset:0
	s_waitcnt lgkmcnt(2)
	v_mfma_f32_16x16x32_bf16 v[38:41], v[216:219], v[208:211], v[38:41]
	s_waitcnt lgkmcnt(1)
	v_mfma_f32_16x16x32_bf16 v[42:45], v[220:223], v[208:211], v[42:45]
	ds_read_b128 v[208:211], v205 offset:43520
	s_waitcnt lgkmcnt(0)
	v_mfma_f32_16x16x32_bf16 v[46:49], v[90:93], v[208:211], v[46:49]
	v_mfma_f32_16x16x32_bf16 v[26:29], v[212:215], v[208:211], v[26:29]
	s_waitcnt vmcnt(18)
	ds_write_b128 v206, v[70:73] offset:10240
	v_mfma_f32_16x16x32_bf16 v[14:17], v[216:219], v[208:211], v[14:17]
	v_mfma_f32_16x16x32_bf16 v[10:13], v[220:223], v[208:211], v[10:13]
	ds_read_b128 v[208:211], v205 offset:46080
	s_waitcnt lgkmcnt(0)
	v_mfma_f32_16x16x32_bf16 v[34:37], v[90:93], v[208:211], v[34:37]
	v_mfma_f32_16x16x32_bf16 v[22:25], v[212:215], v[208:211], v[22:25]
	s_waitcnt vmcnt(17)
	ds_write_b128 v206, v[74:77] offset:20480
	v_mfma_f32_16x16x32_bf16 v[18:21], v[216:219], v[208:211], v[18:21]
	v_mfma_f32_16x16x32_bf16 v[62:65], v[220:223], v[208:211], v[62:65]
	ds_read_b128 v[208:211], v205 offset:48640
	s_waitcnt lgkmcnt(0)
	v_mfma_f32_16x16x32_bf16 v[58:61], v[90:93], v[208:211], v[58:61]
	ds_read_b128 v[90:93], v119 offset:20544
	v_mfma_f32_16x16x32_bf16 v[54:57], v[212:215], v[208:211], v[54:57]
	s_waitcnt vmcnt(16)
	ds_write_b128 v206, v[78:81] offset:30720
	ds_read_b128 v[212:215], v119 offset:23104
	v_mfma_f32_16x16x32_bf16 v[50:53], v[216:219], v[208:211], v[50:53]
	ds_read_b128 v[216:219], v119 offset:25664
	v_mfma_f32_16x16x32_bf16 v[2:5], v[220:223], v[208:211], v[2:5]
	ds_read_b128 v[220:223], v119 offset:28224
	ds_read_b128 v[208:211], v205 offset:41024
	ds_read_b128 v[224:227], v205 offset:48704
	s_waitcnt lgkmcnt(1)
	v_mfma_f32_16x16x32_bf16 v[6:9], v[90:93], v[208:211], v[6:9]
	v_mfma_f32_16x16x32_bf16 v[30:33], v[212:215], v[208:211], v[30:33]
	s_waitcnt vmcnt(15)
	ds_write_b128 v0, v[82:85] offset:0
	v_mfma_f32_16x16x32_bf16 v[38:41], v[216:219], v[208:211], v[38:41]
	v_mfma_f32_16x16x32_bf16 v[42:45], v[220:223], v[208:211], v[42:45]
	ds_read_b128 v[208:211], v205 offset:43584
	s_waitcnt lgkmcnt(0)
	v_mfma_f32_16x16x32_bf16 v[46:49], v[90:93], v[208:211], v[46:49]
	v_mfma_f32_16x16x32_bf16 v[26:29], v[212:215], v[208:211], v[26:29]
	s_waitcnt vmcnt(14)
	ds_write_b128 v0, v[86:89] offset:10240
	v_mfma_f32_16x16x32_bf16 v[14:17], v[216:219], v[208:211], v[14:17]
	v_mfma_f32_16x16x32_bf16 v[10:13], v[220:223], v[208:211], v[10:13]
	ds_read_b128 v[208:211], v205 offset:46144
	s_waitcnt lgkmcnt(0)
	v_mfma_f32_16x16x32_bf16 v[34:37], v[90:93], v[208:211], v[34:37]
	v_mfma_f32_16x16x32_bf16 v[22:25], v[212:215], v[208:211], v[22:25]
	v_mfma_f32_16x16x32_bf16 v[18:21], v[216:219], v[208:211], v[18:21]
	v_mfma_f32_16x16x32_bf16 v[62:65], v[220:223], v[208:211], v[62:65]
	v_mfma_f32_16x16x32_bf16 v[58:61], v[90:93], v[224:227], v[58:61]
	s_waitcnt lgkmcnt(0)
	v_mfma_f32_16x16x32_bf16 v[54:57], v[212:215], v[224:227], v[54:57]
	s_barrier
	v_mfma_f32_16x16x32_bf16 v[50:53], v[216:219], v[224:227], v[50:53]
	v_mfma_f32_16x16x32_bf16 v[2:5], v[220:223], v[224:227], v[2:5]
	ds_read_b128 v[90:93], v119 offset:0
	ds_read_b128 v[208:211], v205 offset:0
	ds_read_b128 v[212:215], v119 offset:2560
	ds_read_b128 v[216:219], v119 offset:5120
	ds_read_b128 v[220:223], v119 offset:7680
	s_waitcnt lgkmcnt(3)
	v_mfma_f32_16x16x32_bf16 v[6:9], v[90:93], v[208:211], v[6:9]
	s_waitcnt lgkmcnt(2)
	v_mfma_f32_16x16x32_bf16 v[30:33], v[212:215], v[208:211], v[30:33]
	s_waitcnt vmcnt(5)
	ds_write_b128 v207, v[228:231] offset:0
	s_waitcnt lgkmcnt(2)
	v_mfma_f32_16x16x32_bf16 v[38:41], v[216:219], v[208:211], v[38:41]
	s_waitcnt lgkmcnt(1)
	v_mfma_f32_16x16x32_bf16 v[42:45], v[220:223], v[208:211], v[42:45]
	ds_read_b128 v[208:211], v205 offset:2560
	s_waitcnt lgkmcnt(0)
	v_mfma_f32_16x16x32_bf16 v[46:49], v[90:93], v[208:211], v[46:49]
	v_mfma_f32_16x16x32_bf16 v[26:29], v[212:215], v[208:211], v[26:29]
	s_waitcnt vmcnt(4)
	ds_write_b128 v207, v[232:235] offset:10240
	v_mfma_f32_16x16x32_bf16 v[14:17], v[216:219], v[208:211], v[14:17]
	v_mfma_f32_16x16x32_bf16 v[10:13], v[220:223], v[208:211], v[10:13]
	ds_read_b128 v[208:211], v205 offset:5120
	s_waitcnt lgkmcnt(0)
	v_mfma_f32_16x16x32_bf16 v[34:37], v[90:93], v[208:211], v[34:37]
	v_mfma_f32_16x16x32_bf16 v[22:25], v[212:215], v[208:211], v[22:25]
	s_waitcnt vmcnt(3)
	ds_write_b128 v207, v[236:239] offset:20480
	v_mfma_f32_16x16x32_bf16 v[18:21], v[216:219], v[208:211], v[18:21]
	v_mfma_f32_16x16x32_bf16 v[62:65], v[220:223], v[208:211], v[62:65]
	ds_read_b128 v[208:211], v205 offset:7680
	s_waitcnt lgkmcnt(0)
	v_mfma_f32_16x16x32_bf16 v[58:61], v[90:93], v[208:211], v[58:61]
	ds_read_b128 v[90:93], v119 offset:64
	v_mfma_f32_16x16x32_bf16 v[54:57], v[212:215], v[208:211], v[54:57]
	s_waitcnt vmcnt(2)
	ds_write_b128 v207, v[240:243] offset:30720
	ds_read_b128 v[212:215], v119 offset:2624
	v_mfma_f32_16x16x32_bf16 v[50:53], v[216:219], v[208:211], v[50:53]
	ds_read_b128 v[216:219], v119 offset:5184
	v_mfma_f32_16x16x32_bf16 v[2:5], v[220:223], v[208:211], v[2:5]
	ds_read_b128 v[220:223], v119 offset:7744
	ds_read_b128 v[208:211], v205 offset:64
	ds_read_b128 v[224:227], v205 offset:7744
	s_waitcnt lgkmcnt(1)
	v_mfma_f32_16x16x32_bf16 v[6:9], v[90:93], v[208:211], v[6:9]
	v_mfma_f32_16x16x32_bf16 v[30:33], v[212:215], v[208:211], v[30:33]
	s_waitcnt vmcnt(1)
	ds_write_b128 v0, v[244:247] offset:20480
	v_mfma_f32_16x16x32_bf16 v[38:41], v[216:219], v[208:211], v[38:41]
	v_mfma_f32_16x16x32_bf16 v[42:45], v[220:223], v[208:211], v[42:45]
	ds_read_b128 v[208:211], v205 offset:2624
	s_waitcnt lgkmcnt(0)
	v_mfma_f32_16x16x32_bf16 v[46:49], v[90:93], v[208:211], v[46:49]
	v_mfma_f32_16x16x32_bf16 v[26:29], v[212:215], v[208:211], v[26:29]
	s_waitcnt vmcnt(0)
	ds_write_b128 v0, v[248:251] offset:30720
	v_mfma_f32_16x16x32_bf16 v[14:17], v[216:219], v[208:211], v[14:17]
	v_mfma_f32_16x16x32_bf16 v[10:13], v[220:223], v[208:211], v[10:13]
	ds_read_b128 v[208:211], v205 offset:5184
	s_waitcnt lgkmcnt(0)
	v_mfma_f32_16x16x32_bf16 v[34:37], v[90:93], v[208:211], v[34:37]
	v_mfma_f32_16x16x32_bf16 v[22:25], v[212:215], v[208:211], v[22:25]
	v_mfma_f32_16x16x32_bf16 v[18:21], v[216:219], v[208:211], v[18:21]
	v_mfma_f32_16x16x32_bf16 v[62:65], v[220:223], v[208:211], v[62:65]
	v_mfma_f32_16x16x32_bf16 v[58:61], v[90:93], v[224:227], v[58:61]
	s_waitcnt lgkmcnt(0)
	v_mfma_f32_16x16x32_bf16 v[54:57], v[212:215], v[224:227], v[54:57]
	s_barrier
	v_mfma_f32_16x16x32_bf16 v[50:53], v[216:219], v[224:227], v[50:53]
	v_mfma_f32_16x16x32_bf16 v[2:5], v[220:223], v[224:227], v[2:5]
	ds_read_b128 v[90:93], v119 offset:20480
	ds_read_b128 v[208:211], v205 offset:40960
	ds_read_b128 v[212:215], v119 offset:23040
	ds_read_b128 v[216:219], v119 offset:25600
	ds_read_b128 v[220:223], v119 offset:28160
	s_waitcnt lgkmcnt(3)
	v_mfma_f32_16x16x32_bf16 v[6:9], v[90:93], v[208:211], v[6:9]
	s_waitcnt lgkmcnt(2)
	v_mfma_f32_16x16x32_bf16 v[30:33], v[212:215], v[208:211], v[30:33]
	s_waitcnt lgkmcnt(1)
	v_mfma_f32_16x16x32_bf16 v[38:41], v[216:219], v[208:211], v[38:41]
	s_waitcnt lgkmcnt(0)
	v_mfma_f32_16x16x32_bf16 v[42:45], v[220:223], v[208:211], v[42:45]
	ds_read_b128 v[208:211], v205 offset:43520
	s_waitcnt lgkmcnt(0)
	v_mfma_f32_16x16x32_bf16 v[46:49], v[90:93], v[208:211], v[46:49]
	v_mfma_f32_16x16x32_bf16 v[26:29], v[212:215], v[208:211], v[26:29]
	v_mfma_f32_16x16x32_bf16 v[14:17], v[216:219], v[208:211], v[14:17]
	v_mfma_f32_16x16x32_bf16 v[10:13], v[220:223], v[208:211], v[10:13]
	ds_read_b128 v[208:211], v205 offset:46080
	s_waitcnt lgkmcnt(0)
	v_mfma_f32_16x16x32_bf16 v[34:37], v[90:93], v[208:211], v[34:37]
	v_mfma_f32_16x16x32_bf16 v[22:25], v[212:215], v[208:211], v[22:25]
	v_mfma_f32_16x16x32_bf16 v[18:21], v[216:219], v[208:211], v[18:21]
	v_mfma_f32_16x16x32_bf16 v[62:65], v[220:223], v[208:211], v[62:65]
	ds_read_b128 v[208:211], v205 offset:48640
	s_waitcnt lgkmcnt(0)
	v_mfma_f32_16x16x32_bf16 v[58:61], v[90:93], v[208:211], v[58:61]
	ds_read_b128 v[90:93], v119 offset:20544
	v_mfma_f32_16x16x32_bf16 v[54:57], v[212:215], v[208:211], v[54:57]
	ds_read_b128 v[212:215], v119 offset:23104
	v_mfma_f32_16x16x32_bf16 v[50:53], v[216:219], v[208:211], v[50:53]
	ds_read_b128 v[216:219], v119 offset:25664
	v_mfma_f32_16x16x32_bf16 v[2:5], v[220:223], v[208:211], v[2:5]
	ds_read_b128 v[220:223], v119 offset:28224
	ds_read_b128 v[208:211], v205 offset:41024
	ds_read_b128 v[224:227], v205 offset:48704
	s_waitcnt lgkmcnt(1)
	v_mfma_f32_16x16x32_bf16 v[6:9], v[90:93], v[208:211], v[6:9]
	s_waitcnt vmcnt(6)
	v_mfma_f32_16x16x32_bf16 v[30:33], v[212:215], v[208:211], v[30:33]
	v_mfma_f32_16x16x32_bf16 v[38:41], v[216:219], v[208:211], v[38:41]
	v_mfma_f32_16x16x32_bf16 v[42:45], v[220:223], v[208:211], v[42:45]
	v_cvt_f32_ubyte0_e32 v200, v138
	v_cvt_f32_ubyte1_e32 v201, v138
	v_cvt_f32_ubyte2_e32 v202, v138
	v_cvt_f32_ubyte3_e32 v255, v138
	v_mul_f32_e32 v200, s34, v200
	v_mul_f32_e32 v201, s34, v201
	v_mul_f32_e32 v202, s34, v202
	v_mul_f32_e32 v255, s34, v255
	v_fma_f32 v184, v6, v200, v184
	v_fma_f32 v185, v7, v201, v185
	v_fma_f32 v186, v8, v202, v186
	v_fma_f32 v187, v9, v255, v187
	ds_read_b128 v[208:211], v205 offset:43584
	s_waitcnt lgkmcnt(0)
	v_mfma_f32_16x16x32_bf16 v[46:49], v[90:93], v[208:211], v[46:49]
	v_cvt_f32_ubyte0_e32 v200, v139
	v_cvt_f32_ubyte1_e32 v201, v139
	v_cvt_f32_ubyte2_e32 v202, v139
	v_cvt_f32_ubyte3_e32 v255, v139
	v_mul_f32_e32 v200, s34, v200
	v_mul_f32_e32 v201, s34, v201
	v_mul_f32_e32 v202, s34, v202
	v_mul_f32_e32 v255, s34, v255
	v_fma_f32 v180, v30, v200, v180
	v_fma_f32 v181, v31, v201, v181
	v_fma_f32 v182, v32, v202, v182
	v_fma_f32 v183, v33, v255, v183
	v_mfma_f32_16x16x32_bf16 v[26:29], v[212:215], v[208:211], v[26:29]
	v_cvt_f32_ubyte0_e32 v200, v140
	v_cvt_f32_ubyte1_e32 v201, v140
	v_cvt_f32_ubyte2_e32 v202, v140
	v_cvt_f32_ubyte3_e32 v255, v140
	v_mul_f32_e32 v200, s34, v200
	v_mul_f32_e32 v201, s34, v201
	v_mul_f32_e32 v202, s34, v202
	v_mul_f32_e32 v255, s34, v255
	v_fma_f32 v176, v38, v200, v176
	v_fma_f32 v177, v39, v201, v177
	v_fma_f32 v178, v40, v202, v178
	v_fma_f32 v179, v41, v255, v179
	v_mfma_f32_16x16x32_bf16 v[14:17], v[216:219], v[208:211], v[14:17]
	v_cvt_f32_ubyte0_e32 v200, v141
	v_cvt_f32_ubyte1_e32 v201, v141
	v_cvt_f32_ubyte2_e32 v202, v141
	v_cvt_f32_ubyte3_e32 v255, v141
	v_mul_f32_e32 v200, s34, v200
	v_mul_f32_e32 v201, s34, v201
	v_mul_f32_e32 v202, s34, v202
	v_mul_f32_e32 v255, s34, v255
	v_fma_f32 v172, v42, v200, v172
	v_fma_f32 v173, v43, v201, v173
	v_fma_f32 v174, v44, v202, v174
	v_fma_f32 v175, v45, v255, v175
	v_mfma_f32_16x16x32_bf16 v[10:13], v[220:223], v[208:211], v[10:13]
	v_cvt_f32_ubyte0_e32 v200, v142
	v_cvt_f32_ubyte1_e32 v201, v142
	v_cvt_f32_ubyte2_e32 v202, v142
	v_cvt_f32_ubyte3_e32 v255, v142
	v_mul_f32_e32 v200, s34, v200
	v_mul_f32_e32 v201, s34, v201
	v_mul_f32_e32 v202, s34, v202
	v_mul_f32_e32 v255, s34, v255
	v_fma_f32 v168, v46, v200, v168
	v_fma_f32 v169, v47, v201, v169
	v_fma_f32 v170, v48, v202, v170
	v_fma_f32 v171, v49, v255, v171
	ds_read_b128 v[208:211], v205 offset:46144
	s_waitcnt lgkmcnt(0)
	v_mfma_f32_16x16x32_bf16 v[34:37], v[90:93], v[208:211], v[34:37]
	v_cvt_f32_ubyte0_e32 v200, v143
	v_cvt_f32_ubyte1_e32 v201, v143
	v_cvt_f32_ubyte2_e32 v202, v143
	v_cvt_f32_ubyte3_e32 v255, v143
	v_mul_f32_e32 v200, s34, v200
	v_mul_f32_e32 v201, s34, v201
	v_mul_f32_e32 v202, s34, v202
	v_mul_f32_e32 v255, s34, v255
	v_fma_f32 v164, v26, v200, v164
	v_fma_f32 v165, v27, v201, v165
	v_fma_f32 v166, v28, v202, v166
	v_fma_f32 v167, v29, v255, v167
	v_mfma_f32_16x16x32_bf16 v[22:25], v[212:215], v[208:211], v[22:25]
	v_cvt_f32_ubyte0_e32 v200, v144
	v_cvt_f32_ubyte1_e32 v201, v144
	v_cvt_f32_ubyte2_e32 v202, v144
	v_cvt_f32_ubyte3_e32 v255, v144
	v_mul_f32_e32 v200, s34, v200
	v_mul_f32_e32 v201, s34, v201
	v_mul_f32_e32 v202, s34, v202
	v_mul_f32_e32 v255, s34, v255
	v_fma_f32 v160, v14, v200, v160
	v_fma_f32 v161, v15, v201, v161
	v_fma_f32 v162, v16, v202, v162
	v_fma_f32 v163, v17, v255, v163
	v_mfma_f32_16x16x32_bf16 v[18:21], v[216:219], v[208:211], v[18:21]
	v_cvt_f32_ubyte0_e32 v200, v145
	v_cvt_f32_ubyte1_e32 v201, v145
	v_cvt_f32_ubyte2_e32 v202, v145
	v_cvt_f32_ubyte3_e32 v255, v145
	v_mul_f32_e32 v200, s34, v200
	v_mul_f32_e32 v201, s34, v201
	v_mul_f32_e32 v202, s34, v202
	v_mul_f32_e32 v255, s34, v255
	v_fma_f32 v156, v10, v200, v156
	v_fma_f32 v157, v11, v201, v157
	v_fma_f32 v158, v12, v202, v158
	v_fma_f32 v159, v13, v255, v159
	v_mfma_f32_16x16x32_bf16 v[62:65], v[220:223], v[208:211], v[62:65]
	v_cvt_f32_ubyte0_e32 v200, v146
	v_cvt_f32_ubyte1_e32 v201, v146
	v_cvt_f32_ubyte2_e32 v202, v146
	v_cvt_f32_ubyte3_e32 v255, v146
	v_mul_f32_e32 v200, s34, v200
	v_mul_f32_e32 v201, s34, v201
	v_mul_f32_e32 v202, s34, v202
	v_mul_f32_e32 v255, s34, v255
	v_fma_f32 v136, v34, v200, v136
	v_fma_f32 v137, v35, v201, v137
	v_fma_f32 v150, v36, v202, v150
	v_fma_f32 v151, v37, v255, v151
	v_mfma_f32_16x16x32_bf16 v[58:61], v[90:93], v[224:227], v[58:61]
	v_cvt_f32_ubyte0_e32 v200, v147
	v_cvt_f32_ubyte1_e32 v201, v147
	v_cvt_f32_ubyte2_e32 v202, v147
	v_cvt_f32_ubyte3_e32 v255, v147
	v_mul_f32_e32 v200, s34, v200
	v_mul_f32_e32 v201, s34, v201
	v_mul_f32_e32 v202, s34, v202
	v_mul_f32_e32 v255, s34, v255
	v_fma_f32 v130, v22, v200, v130
	v_fma_f32 v131, v23, v201, v131
	v_fma_f32 v134, v24, v202, v134
	v_fma_f32 v135, v25, v255, v135
	v_mfma_f32_16x16x32_bf16 v[54:57], v[212:215], v[224:227], v[54:57]
	v_cvt_f32_ubyte0_e32 v200, v148
	v_cvt_f32_ubyte1_e32 v201, v148
	v_cvt_f32_ubyte2_e32 v202, v148
	v_cvt_f32_ubyte3_e32 v255, v148
	v_mul_f32_e32 v200, s34, v200
	v_mul_f32_e32 v201, s34, v201
	v_mul_f32_e32 v202, s34, v202
	v_mul_f32_e32 v255, s34, v255
	v_fma_f32 v124, v18, v200, v124
	v_fma_f32 v125, v19, v201, v125
	v_fma_f32 v126, v20, v202, v126
	v_fma_f32 v127, v21, v255, v127
	v_mfma_f32_16x16x32_bf16 v[50:53], v[216:219], v[224:227], v[50:53]
	v_cvt_f32_ubyte0_e32 v200, v149
	v_cvt_f32_ubyte1_e32 v201, v149
	v_cvt_f32_ubyte2_e32 v202, v149
	v_cvt_f32_ubyte3_e32 v255, v149
	v_mul_f32_e32 v200, s34, v200
	v_mul_f32_e32 v201, s34, v201
	v_mul_f32_e32 v202, s34, v202
	v_mul_f32_e32 v255, s34, v255
	v_fma_f32 v120, v62, v200, v120
	v_fma_f32 v121, v63, v201, v121
	v_fma_f32 v122, v64, v202, v122
	v_fma_f32 v123, v65, v255, v123
	v_mfma_f32_16x16x32_bf16 v[2:5], v[220:223], v[224:227], v[2:5]
	v_cvt_f32_ubyte0_e32 v200, v194
	v_cvt_f32_ubyte1_e32 v201, v194
	v_cvt_f32_ubyte2_e32 v202, v194
	v_cvt_f32_ubyte3_e32 v255, v194
	v_mul_f32_e32 v200, s34, v200
	v_mul_f32_e32 v201, s34, v201
	v_mul_f32_e32 v202, s34, v202
	v_mul_f32_e32 v255, s34, v255
	v_fma_f32 v114, v58, v200, v114
	v_fma_f32 v115, v59, v201, v115
	v_fma_f32 v116, v60, v202, v116
	v_fma_f32 v117, v61, v255, v117
	s_nop 7
	s_nop 3
	v_cvt_f32_ubyte0_e32 v200, v195
	v_cvt_f32_ubyte1_e32 v201, v195
	v_cvt_f32_ubyte2_e32 v202, v195
	v_cvt_f32_ubyte3_e32 v255, v195
	v_mul_f32_e32 v200, s34, v200
	v_mul_f32_e32 v201, s34, v201
	v_mul_f32_e32 v202, s34, v202
	v_mul_f32_e32 v255, s34, v255
	v_fma_f32 v106, v54, v200, v106
	v_fma_f32 v107, v55, v201, v107
	v_fma_f32 v108, v56, v202, v108
	v_fma_f32 v109, v57, v255, v109
	v_cvt_f32_ubyte0_e32 v200, v196
	v_cvt_f32_ubyte1_e32 v201, v196
	v_cvt_f32_ubyte2_e32 v202, v196
	v_cvt_f32_ubyte3_e32 v255, v196
	v_mul_f32_e32 v200, s34, v200
	v_mul_f32_e32 v201, s34, v201
	v_mul_f32_e32 v202, s34, v202
	v_mul_f32_e32 v255, s34, v255
	v_fma_f32 v100, v50, v200, v100
	v_fma_f32 v101, v51, v201, v101
	v_fma_f32 v102, v52, v202, v102
	v_fma_f32 v103, v53, v255, v103
	v_cvt_f32_ubyte0_e32 v200, v197
	v_cvt_f32_ubyte1_e32 v201, v197
	v_cvt_f32_ubyte2_e32 v202, v197
	v_cvt_f32_ubyte3_e32 v255, v197
	v_mul_f32_e32 v200, s34, v200
	v_mul_f32_e32 v201, s34, v201
	v_mul_f32_e32 v202, s34, v202
	v_mul_f32_e32 v255, s34, v255
	v_fma_f32 v96, v2, v200, v96
	v_fma_f32 v97, v3, v201, v97
	v_fma_f32 v98, v4, v202, v98
	v_fma_f32 v99, v5, v255, v99
	v_mov_b32_e32 v138, 0xa00
	v_mov_b32_e32 v139, 0x0
	v_mov_b32_e32 v140, 0x9ff
	v_mov_b32_e32 v141, 0x0
	v_mov_b32_e32 v142, 0x200
	v_mov_b32_e32 v143, 0x0
	v_mov_b32_e32 v144, 0x1ff
	v_mov_b32_e32 v145, 0x0
	v_mov_b32_e32 v146, 0xb00
	v_mov_b32_e32 v147, 0x0
	v_mov_b32_e32 v148, 0xaff
	v_mov_b32_e32 v149, 0x0
	v_mov_b32_e32 v194, 0x358637bd
	v_mov_b32_e32 v195, 0x2000
	v_mov_b32_e32 v196, 0x3e38aa3b
	v_mov_b32_e32 v197, 0x41b17218
	v_mov_b32_e32 v200, 0x3f24fd5c
	v_mov_b32_e32 v201, 0x3f4ccccd
	v_mov_b32_e32 v202, 0xf149f2ca
	s_mov_b32 s66, 4
	s_add_u32 s6, s6, 0x400000
	s_addc_u32 s7, s7, 0
	s_cmp_eq_u32 s66, 4
	s_cbranch_scc0 .LBB0_1004
	v_lshlrev_b32_e32 v0, 1, v118
	v_lshl_add_u64 v[6:7], s[4:5], 0, v[0:1]
	v_lshlrev_b64 v[2:3], 11, v[112:113]
	v_lshl_add_u64 v[8:9], v[6:7], 0, v[2:3]
	v_cvt_pk_bf16_f32 v2, v184, v185
	v_cvt_pk_bf16_f32 v3, v186, v187
	v_cvt_pk_bf16_f32 v4, v180, v181
	v_cvt_pk_bf16_f32 v5, v182, v183
	global_store_dwordx4 v[8:9], v[2:5], off
	v_readlane_b32 s46, v254, 29
	s_mov_b32 s38, 0
	v_cvt_pk_bf16_f32 v2, v176, v177
	v_cvt_pk_bf16_f32 v3, v178, v179
	v_cvt_pk_bf16_f32 v4, v172, v173
	v_cvt_pk_bf16_f32 v5, v174, v175
	global_store_dwordx4 v[8:9], v[2:5], off offset:64
	v_readlane_b32 s47, v254, 30
	s_nop 0
	v_lshlrev_b64 v[2:3], 11, v[110:111]
	v_lshl_add_u64 v[8:9], v[6:7], 0, v[2:3]
	v_cvt_pk_bf16_f32 v2, v168, v169
	v_cvt_pk_bf16_f32 v3, v170, v171
	v_cvt_pk_bf16_f32 v4, v164, v165
	v_cvt_pk_bf16_f32 v5, v166, v167
	global_store_dwordx4 v[8:9], v[2:5], off
	s_nop 1
	v_cvt_pk_bf16_f32 v2, v160, v161
	v_cvt_pk_bf16_f32 v3, v162, v163
	v_cvt_pk_bf16_f32 v4, v156, v157
	v_cvt_pk_bf16_f32 v5, v158, v159
	global_store_dwordx4 v[8:9], v[2:5], off offset:64
	s_nop 1
	v_lshlrev_b64 v[2:3], 11, v[104:105]
	v_lshl_add_u64 v[8:9], v[6:7], 0, v[2:3]
	v_cvt_pk_bf16_f32 v2, v136, v137
	v_cvt_pk_bf16_f32 v3, v150, v151
	v_cvt_pk_bf16_f32 v4, v130, v131
	v_cvt_pk_bf16_f32 v5, v134, v135
	global_store_dwordx4 v[8:9], v[2:5], off
	s_nop 1
	v_cvt_pk_bf16_f32 v2, v124, v125
	v_cvt_pk_bf16_f32 v3, v126, v127
	v_cvt_pk_bf16_f32 v4, v120, v121
	v_cvt_pk_bf16_f32 v5, v122, v123
	global_store_dwordx4 v[8:9], v[2:5], off offset:64
	s_nop 1
	v_lshlrev_b64 v[2:3], 11, v[94:95]
	v_lshl_add_u64 v[6:7], v[6:7], 0, v[2:3]
	v_cvt_pk_bf16_f32 v2, v114, v115
	v_cvt_pk_bf16_f32 v3, v116, v117
	v_cvt_pk_bf16_f32 v4, v106, v107
	v_cvt_pk_bf16_f32 v5, v108, v109
	global_store_dwordx4 v[6:7], v[2:5], off
	s_nop 1
	v_cvt_pk_bf16_f32 v2, v100, v101
	v_cvt_pk_bf16_f32 v3, v102, v103
	v_cvt_pk_bf16_f32 v4, v96, v97
	v_cvt_pk_bf16_f32 v5, v98, v99
	global_store_dwordx4 v[6:7], v[2:5], off offset:64
